# decode loader waves run their loader section at s_setprio 2 (producer priority raise), reset before rejoining
# baseline (speedup 1.0000x reference)
.LBB0_729:
	v_mov_b32_e32 v220, v0
	s_ashr_i32 s34, s36, 1
	s_mul_hi_i32 s23, s34, 0x12000
	v_readfirstlane_b32 s22, v220
	s_ashr_i32 s37, s22, 6
	s_mul_i32 s22, s34, 0x12000
	s_add_u32 s22, s21, s22
	v_add_u32_e32 v40, 0x200, v220
	v_add_u32_e32 v42, 0x400, v220
	v_add_u32_e32 v44, 0x600, v220
	s_addc_u32 s23, s46, s23
	v_ashrrev_i32_e32 v221, 31, v220
	v_ashrrev_i32_e32 v41, 31, v40
	v_ashrrev_i32_e32 v43, 31, v42
	v_ashrrev_i32_e32 v45, 31, v44
	v_lshl_add_u64 v[4:5], v[220:221], 4, s[22:23]
	v_lshl_add_u64 v[8:9], v[40:41], 4, s[22:23]
	v_lshl_add_u64 v[12:13], v[42:43], 4, s[22:23]
	v_lshl_add_u64 v[16:17], v[44:45], 4, s[22:23]
	s_waitcnt lgkmcnt(0)
	global_load_dwordx4 v[4:7], v[4:5], off
	s_nop 0
	global_load_dwordx4 v[8:11], v[8:9], off
	s_nop 0
	global_load_dwordx4 v[12:15], v[12:13], off
	s_nop 0
	global_load_dwordx4 v[16:19], v[16:17], off
	v_add_u32_e32 v46, 0x800, v220
	v_ashrrev_i32_e32 v47, 31, v46
	v_lshl_add_u64 v[20:21], v[46:47], 4, s[22:23]
	global_load_dwordx4 v[20:23], v[20:21], off
	v_add_u32_e32 v48, 0xa00, v220
	v_ashrrev_i32_e32 v49, 31, v48
	v_lshl_add_u64 v[24:25], v[48:49], 4, s[22:23]
	global_load_dwordx4 v[24:27], v[24:25], off
	v_add_u32_e32 v50, 0xc00, v220
	v_ashrrev_i32_e32 v51, 31, v50
	v_lshl_add_u64 v[28:29], v[50:51], 4, s[22:23]
	global_load_dwordx4 v[28:31], v[28:29], off
	v_add_u32_e32 v52, 0xe00, v220
	v_ashrrev_i32_e32 v53, 31, v52
	v_lshl_add_u64 v[32:33], v[52:53], 4, s[22:23]
	global_load_dwordx4 v[32:35], v[32:33], off
	v_add_u32_e32 v54, 0x1000, v220
	v_mul_hi_i32 v2, v220, s47
	v_ashrrev_i32_e32 v55, 31, v54
	v_lshrrev_b32_e32 v36, 31, v2
	v_ashrrev_i32_e32 v2, 3, v2
	v_mul_hi_i32 v37, v40, s47
	v_add_u32_e32 v2, v2, v36
	v_lshrrev_b32_e32 v47, 31, v37
	v_ashrrev_i32_e32 v49, 3, v37
	v_lshl_add_u64 v[36:37], v[54:55], 4, s[22:23]
	global_load_dwordx4 v[36:39], v[36:37], off
	v_mul_hi_i32 v41, v42, s47
	v_mul_hi_i32 v43, v44, s47
	v_lshrrev_b32_e32 v51, 31, v41
	v_ashrrev_i32_e32 v41, 3, v41
	v_lshrrev_b32_e32 v53, 31, v43
	v_ashrrev_i32_e32 v43, 3, v43
	v_mul_lo_u32 v56, v2, 36
	v_add_u32_e32 v47, v49, v47
	v_add_u32_e32 v41, v41, v51
	v_add_u32_e32 v43, v43, v53
	v_sub_u32_e32 v49, v220, v56
	v_mul_lo_u32 v51, v47, 36
	v_mul_lo_u32 v53, v41, 36
	v_mul_lo_u32 v56, v43, 36
	v_mul_hi_i32 v45, v46, s47
	v_mul_lo_u32 v2, v2, s48
	v_lshlrev_b32_e32 v49, 4, v49
	v_sub_u32_e32 v40, v40, v51
	v_sub_u32_e32 v42, v42, v53
	v_sub_u32_e32 v44, v44, v56
	v_lshrrev_b32_e32 v55, 31, v45
	v_ashrrev_i32_e32 v45, 3, v45
	v_mul_lo_u32 v47, v47, s48
	v_mul_lo_u32 v41, v41, s48
	v_mul_lo_u32 v43, v43, s48
	v_add3_u32 v2, s49, v2, v49
	v_lshlrev_b32_e32 v40, 4, v40
	v_lshlrev_b32_e32 v42, 4, v42
	v_lshlrev_b32_e32 v44, 4, v44
	v_add3_u32 v40, s49, v47, v40
	v_add3_u32 v41, s49, v41, v42
	v_add3_u32 v42, s49, v43, v44
	s_and_b32 s35, s36, 1
	s_cmp_lt_i32 s37, 4
	v_and_b32_e32 v221, 31, v220
	s_cselect_b64 s[38:39], -1, 0
	s_cmp_gt_i32 s37, 3
	s_waitcnt vmcnt(0)
	ds_write_b128 v2, v[4:7]
	ds_write_b128 v40, v[8:11]
	ds_write_b128 v41, v[12:15]
	ds_write_b128 v42, v[16:19]
	v_add_u32_e32 v2, v45, v55
	v_mul_lo_u32 v4, v2, 36
	v_sub_u32_e32 v4, v46, v4
	v_mul_lo_u32 v2, v2, s48
	v_lshlrev_b32_e32 v4, 4, v4
	v_add3_u32 v2, s49, v2, v4
	ds_write_b128 v2, v[20:23]
	v_mul_hi_i32 v2, v48, s47
	v_lshrrev_b32_e32 v4, 31, v2
	v_ashrrev_i32_e32 v2, 3, v2
	v_add_u32_e32 v2, v2, v4
	v_mul_lo_u32 v4, v2, 36
	v_sub_u32_e32 v4, v48, v4
	v_mul_lo_u32 v2, v2, s48
	v_lshlrev_b32_e32 v4, 4, v4
	v_add3_u32 v2, s49, v2, v4
	ds_write_b128 v2, v[24:27]
	v_mul_hi_i32 v2, v50, s47
	v_lshrrev_b32_e32 v4, 31, v2
	v_ashrrev_i32_e32 v2, 3, v2
	v_add_u32_e32 v2, v2, v4
	v_mul_lo_u32 v4, v2, 36
	v_sub_u32_e32 v4, v50, v4
	v_mul_lo_u32 v2, v2, s48
	v_lshlrev_b32_e32 v4, 4, v4
	v_add3_u32 v2, s49, v2, v4
	ds_write_b128 v2, v[28:31]
	v_mul_hi_i32 v2, v52, s47
	v_lshrrev_b32_e32 v4, 31, v2
	v_ashrrev_i32_e32 v2, 3, v2
	v_add_u32_e32 v2, v2, v4
	v_mul_lo_u32 v4, v2, 36
	v_sub_u32_e32 v4, v52, v4
	v_mul_lo_u32 v2, v2, s48
	v_lshlrev_b32_e32 v4, 4, v4
	v_add3_u32 v2, s49, v2, v4
	ds_write_b128 v2, v[32:35]
	v_mul_hi_i32 v2, v54, s47
	v_lshrrev_b32_e32 v4, 31, v2
	v_ashrrev_i32_e32 v2, 3, v2
	v_add_u32_e32 v2, v2, v4
	v_mul_lo_u32 v4, v2, 36
	v_sub_u32_e32 v4, v54, v4
	v_mul_lo_u32 v2, v2, s48
	v_lshlrev_b32_e32 v4, 4, v4
	v_add3_u32 v2, s49, v2, v4
	ds_write_b128 v2, v[36:39]
	s_mov_b64 s[22:23], -1
	s_cbranch_scc0 .LBB0_733
	s_setprio 2
	s_lshl_b32 s22, s34, 6
	s_ashr_i32 s23, s22, 31
	s_lshl_b64 s[22:23], s[22:23], 2
	s_add_u32 s22, s16, s22
	v_lshlrev_b32_e32 v2, 2, v221
	s_addc_u32 s23, s17, s23
	v_lshl_or_b32 v2, s35, 7, v2
	global_load_dword v232, v2, s[22:23]
	v_mov_b32_e32 v2, 2
	v_lshlrev_b32_sdwa v2, v2, v220 dst_sel:DWORD dst_unused:UNUSED_PAD src0_sel:DWORD src1_sel:BYTE_0
	v_mov_b32_e32 v4, 4
	v_lshlrev_b32_sdwa v205, v4, v220 dst_sel:DWORD dst_unused:UNUSED_PAD src0_sel:DWORD src1_sel:BYTE_0
	v_or_b32_e32 v204, 0x400, v2
	v_or_b32_e32 v206, 0x800, v2
	v_or_b32_e32 v208, 0xc00, v2
	v_or_b32_e32 v210, 0x1000, v2
	v_or_b32_e32 v212, 0x1400, v2
	v_or_b32_e32 v216, 0x1800, v2
	v_or_b32_e32 v218, 0x1c00, v2
	v_or_b32_e32 v234, 0x2000, v2
	v_or_b32_e32 v236, 0x2400, v2
	v_or_b32_e32 v238, 0x2800, v2
	v_or_b32_e32 v250, 0x2c00, v2
	v_or_b32_e32 v252, 0x3000, v2
	v_or_b32_e32 v222, 0x3400, v2
	v_or_b32_e32 v224, 0x3800, v2
	v_or_b32_e32 v226, 0x3c00, v2
	v_lshlrev_b32_e32 v217, 2, v204
	v_lshlrev_b32_e32 v160, 2, v206
	v_lshlrev_b32_e32 v161, 2, v208
	v_lshlrev_b32_e32 v162, 2, v210
	v_lshlrev_b32_e32 v163, 2, v212
	v_lshlrev_b32_e32 v207, 2, v216
	v_lshlrev_b32_e32 v209, 2, v218
	v_lshlrev_b32_e32 v211, 2, v234
	v_lshlrev_b32_e32 v213, 2, v236
	v_lshlrev_b32_e32 v214, 2, v238
	v_lshlrev_b32_e32 v215, 2, v250
	v_lshlrev_b32_e32 v219, 2, v252
	v_lshlrev_b32_e32 v239, 2, v222
	v_lshlrev_b32_e32 v240, 2, v224
	v_lshlrev_b32_e32 v241, 2, v226
	v_or_b32_sdwa v5, v220, s50 dst_sel:DWORD dst_unused:UNUSED_PAD src0_sel:BYTE_0 src1_sel:DWORD
	v_lshlrev_b32_e32 v4, 3, v220
	v_bfe_u32 v6, v220, 3, 5
	v_lshrrev_b32_e32 v237, 6, v5
	v_lshrrev_b32_e32 v5, 3, v5
	v_and_b32_e32 v7, 0x1f8, v4
	v_and_b32_e32 v4, 56, v4
	v_mad_u32_u24 v6, v6, s48, 0
	v_mad_u32_u24 v5, v5, s48, 0
	v_add_u32_e32 v254, 0, v7
	v_add_u32_e32 v231, v6, v4
	v_add_u32_e32 v230, v5, v4
	v_bfe_u32 v235, v220, 6, 2
	v_mad_u32_u24 v233, v235, s48, v254
	v_mad_u32_u24 v168, v237, s48, v254
	v_lshlrev_b32_e32 v242, 2, v210
	v_lshlrev_b32_e32 v243, 2, v212
	v_lshlrev_b32_e32 v244, 2, v216
	v_lshlrev_b32_e32 v245, 2, v218
	v_lshlrev_b32_e32 v246, 2, v234
	v_lshlrev_b32_e32 v249, 2, v250
	v_lshlrev_b32_e32 v250, 2, v252
	v_mul_u32_u24_e32 v234, 0x250, v237
	v_lshlrev_b32_e32 v251, 2, v222
	v_mad_u32_u24 v222, v235, s48, v228
	v_lshlrev_b32_e32 v252, 2, v224
	v_mad_u32_u24 v224, v235, s48, v225
	v_lshlrev_b32_e32 v253, 2, v226
	v_mad_u32_u24 v226, v235, s48, v1
	v_mad_u32_u24 v235, v235, s48, v227
	v_lshlrev_b32_e32 v247, 2, v236
	v_lshlrev_b32_e32 v248, 2, v238
	v_add_u32_e32 v234, v254, v234
	v_add_u32_e32 v238, v254, v222
	v_add_u32_e32 v237, v254, v224
	v_add_u32_e32 v236, v254, v226
	v_add_u32_e32 v235, v254, v235
	s_waitcnt vmcnt(0)
	v_readlane_b32 s22, v232, 0
	s_ashr_i32 s23, s22, 31
	s_lshl_b64 s[42:43], s[22:23], 17
	s_add_u32 s42, s8, s42
	s_addc_u32 s43, s9, s43
	s_lshl_b64 s[44:45], s[22:23], 14
	global_load_dwordx4 v[84:87], v205, s[42:43] nt
	global_load_dwordx4 v[108:111], v207, s[42:43] nt
	s_add_u32 s44, s10, s44
	global_load_dwordx4 v[88:91], v217, s[42:43] nt
	global_load_dwordx4 v[128:131], v215, s[42:43] nt
	global_load_dwordx4 v[92:95], v160, s[42:43] nt
	global_load_dwordx4 v[96:99], v161, s[42:43] nt
	global_load_dwordx4 v[100:103], v162, s[42:43] nt
	global_load_dwordx4 v[104:107], v163, s[42:43] nt
	global_load_dwordx4 v[112:115], v209, s[42:43] nt
	global_load_dwordx4 v[116:119], v211, s[42:43] nt
	global_load_dwordx4 v[120:123], v213, s[42:43] nt
	global_load_dwordx4 v[124:127], v214, s[42:43] nt
	global_load_dwordx4 v[132:135], v219, s[42:43] nt
	global_load_dwordx4 v[136:139], v239, s[42:43] nt
	global_load_dwordx4 v[140:143], v240, s[42:43] nt
	global_load_dwordx4 v[144:147], v241, s[42:43] nt
	s_addc_u32 s45, s11, s45
	global_load_dwordx4 v[148:151], v205, s[44:45] nt
	global_load_dwordx4 v[156:159], v217, s[44:45] nt
	s_lshl_b64 s[22:23], s[22:23], 7
	s_or_b32 s22, s22, 64
	s_lshl_b64 s[44:45], s[22:23], 10
	s_add_u32 s44, s8, s44
	s_addc_u32 s45, s9, s45
	s_lshl_b64 s[22:23], s[22:23], 7
	v_readlane_b32 s42, v232, 1
	s_add_u32 s22, s10, s22
	s_addc_u32 s23, s11, s23
	s_ashr_i32 s43, s42, 31
	global_load_dwordx4 v[64:67], v160, s[44:45] nt
	global_load_dwordx4 v[60:63], v161, s[44:45] nt
	global_load_dwordx4 v[56:59], v162, s[44:45] nt
	global_load_dwordx4 v[52:55], v163, s[44:45] nt
	global_load_dwordx4 v[48:51], v207, s[44:45] nt
	global_load_dwordx4 v[44:47], v209, s[44:45] nt
	global_load_dwordx4 v[40:43], v211, s[44:45] nt
	global_load_dwordx4 v[36:39], v213, s[44:45] nt
	global_load_dwordx4 v[32:35], v214, s[44:45] nt
	global_load_dwordx4 v[28:31], v215, s[44:45] nt
	global_load_dwordx4 v[24:27], v219, s[44:45] nt
	global_load_dwordx4 v[20:23], v239, s[44:45] nt
	global_load_dwordx4 v[16:19], v240, s[44:45] nt
	global_load_dwordx4 v[12:15], v241, s[44:45] nt
	global_load_dwordx4 v[72:75], v205, s[44:45] nt
	global_load_dwordx4 v[8:11], v205, s[22:23] nt
	global_load_dwordx4 v[68:71], v217, s[44:45] nt
	global_load_dwordx4 v[4:7], v217, s[22:23] nt
	s_lshl_b64 s[22:23], s[42:43], 17
	s_add_u32 s22, s8, s22
	s_addc_u32 s23, s9, s23
	s_lshl_b64 s[44:45], s[42:43], 14
	s_add_u32 s44, s10, s44
	s_addc_u32 s45, s11, s45
	s_lshl_b64 s[42:43], s[42:43], 7
	s_or_b32 s42, s42, 64
	global_load_dwordx4 v[164:167], v205, s[22:23] nt
	global_load_dwordx4 v[80:83], v205, s[44:45] nt
	global_load_dwordx4 v[152:155], v217, s[22:23] nt
	global_load_dwordx4 v[76:79], v217, s[44:45] nt
	s_lshl_b64 s[44:45], s[42:43], 10
	s_add_u32 s44, s8, s44
	s_addc_u32 s45, s9, s45
	s_lshl_b64 s[42:43], s[42:43], 7
	s_waitcnt vmcnt(39)
	v_cvt_pk_bf16_f32 v84, v84, v85
	v_cvt_pk_bf16_f32 v85, v86, v87
	s_waitcnt vmcnt(37)
	v_cvt_pk_bf16_f32 v86, v88, v89
	v_cvt_pk_bf16_f32 v87, v90, v91
	s_waitcnt vmcnt(35)
	v_cvt_pk_bf16_f32 v88, v92, v93
	v_cvt_pk_bf16_f32 v89, v94, v95
	s_waitcnt vmcnt(34)
	v_cvt_pk_bf16_f32 v90, v96, v97
	v_cvt_pk_bf16_f32 v91, v98, v99
	s_waitcnt vmcnt(33)
	v_cvt_pk_bf16_f32 v92, v100, v101
	v_cvt_pk_bf16_f32 v93, v102, v103
	s_waitcnt vmcnt(32)
	v_cvt_pk_bf16_f32 v94, v104, v105
	v_cvt_pk_bf16_f32 v95, v106, v107
	v_cvt_pk_bf16_f32 v96, v108, v109
	v_cvt_pk_bf16_f32 v97, v110, v111
	s_waitcnt vmcnt(31)
	v_cvt_pk_bf16_f32 v98, v112, v113
	v_cvt_pk_bf16_f32 v99, v114, v115
	s_waitcnt vmcnt(30)
	v_cvt_pk_bf16_f32 v100, v116, v117
	v_cvt_pk_bf16_f32 v101, v118, v119
	s_waitcnt vmcnt(29)
	v_cvt_pk_bf16_f32 v102, v120, v121
	v_cvt_pk_bf16_f32 v103, v122, v123
	s_waitcnt vmcnt(28)
	v_cvt_pk_bf16_f32 v104, v124, v125
	v_cvt_pk_bf16_f32 v105, v126, v127
	v_cvt_pk_bf16_f32 v106, v128, v129
	v_cvt_pk_bf16_f32 v107, v130, v131
	s_waitcnt vmcnt(27)
	v_cvt_pk_bf16_f32 v108, v132, v133
	v_cvt_pk_bf16_f32 v109, v134, v135
	s_waitcnt vmcnt(26)
	v_cvt_pk_bf16_f32 v110, v136, v137
	v_cvt_pk_bf16_f32 v111, v138, v139
	s_waitcnt vmcnt(25)
	v_cvt_pk_bf16_f32 v112, v140, v141
	v_cvt_pk_bf16_f32 v113, v142, v143
	s_waitcnt vmcnt(24)
	v_cvt_pk_bf16_f32 v114, v144, v145
	v_cvt_pk_bf16_f32 v115, v146, v147
	ds_write_b64 v233, v[84:85]
	ds_write_b64 v168, v[86:87]
	ds_write_b64 v233, v[88:89] offset:4736
	ds_write_b64 v233, v[90:91] offset:7104
	ds_write_b64 v233, v[92:93] offset:9472
	ds_write_b64 v233, v[94:95] offset:11840
	ds_write_b64 v233, v[96:97] offset:14208
	ds_write_b64 v233, v[98:99] offset:16576
	ds_write_b64 v233, v[100:101] offset:18944
	ds_write_b64 v233, v[102:103] offset:21312
	ds_write_b64 v233, v[104:105] offset:23680
	ds_write_b64 v233, v[106:107] offset:26048
	ds_write_b64 v233, v[108:109] offset:28416
	ds_write_b64 v233, v[110:111] offset:30784
	ds_write_b64 v233, v[112:113] offset:33152
	ds_write_b64 v233, v[114:115] offset:35520
	s_waitcnt vmcnt(23)
	v_cvt_pk_bf16_f32 v84, v148, v149
	v_cvt_pk_bf16_f32 v85, v150, v151
	s_waitcnt vmcnt(22)
	v_cvt_pk_bf16_f32 v86, v156, v157
	v_cvt_pk_bf16_f32 v87, v158, v159
	ds_write_b64 v231, v[84:85] offset:512
	ds_write_b64 v230, v[86:87] offset:512
	global_load_dwordx4 v[200:203], v160, s[22:23] nt
	global_load_dwordx4 v[196:199], v160, s[44:45] nt
	global_load_dwordx4 v[192:195], v161, s[22:23] nt
	global_load_dwordx4 v[188:191], v161, s[44:45] nt
	global_load_dwordx4 v[184:187], v162, s[22:23] nt
	global_load_dwordx4 v[180:183], v162, s[44:45] nt
	global_load_dwordx4 v[176:179], v163, s[22:23] nt
	global_load_dwordx4 v[172:175], v163, s[44:45] nt
	global_load_dwordx4 v[168:171], v207, s[22:23] nt
	s_nop 0
	global_load_dwordx4 v[160:163], v207, s[44:45] nt
	global_load_dwordx4 v[156:159], v209, s[22:23] nt
	global_load_dwordx4 v[148:151], v209, s[44:45] nt
	global_load_dwordx4 v[144:147], v211, s[22:23] nt
	global_load_dwordx4 v[140:143], v211, s[44:45] nt
	global_load_dwordx4 v[136:139], v213, s[22:23] nt
	global_load_dwordx4 v[132:135], v213, s[44:45] nt
	global_load_dwordx4 v[128:131], v214, s[22:23] nt
	global_load_dwordx4 v[124:127], v214, s[44:45] nt
	global_load_dwordx4 v[120:123], v215, s[22:23] nt
	global_load_dwordx4 v[116:119], v215, s[44:45] nt
	global_load_dwordx4 v[112:115], v219, s[22:23] nt
	global_load_dwordx4 v[108:111], v219, s[44:45] nt
	global_load_dwordx4 v[104:107], v239, s[22:23] nt
	global_load_dwordx4 v[100:103], v239, s[44:45] nt
	global_load_dwordx4 v[96:99], v240, s[22:23] nt
	global_load_dwordx4 v[92:95], v240, s[44:45] nt
	global_load_dwordx4 v[88:91], v241, s[22:23] nt
	global_load_dwordx4 v[84:87], v241, s[44:45] nt
	s_add_u32 s22, s10, s42
	s_addc_u32 s23, s11, s43
	v_lshlrev_b32_e32 v239, 2, v204
	v_lshlrev_b32_e32 v240, 2, v206
	v_lshlrev_b32_e32 v241, 2, v208
	global_load_dwordx4 v[208:211], v205, s[44:45] nt
	global_load_dwordx4 v[212:215], v205, s[22:23] nt
	s_nop 0
	global_load_dwordx4 v[204:207], v217, s[44:45] nt
	s_nop 0
	global_load_dwordx4 v[216:219], v217, s[22:23] nt
	s_waitcnt lgkmcnt(0)
	s_barrier
	s_mov_b32 s22, 4
	s_mov_b32 s23, -6
.LBB0_731:
	s_add_i32 s42, s22, -2
	v_readlane_b32 s42, v232, s42
	s_ashr_i32 s43, s42, 31
	s_lshl_b64 s[44:45], s[42:43], 17
	s_waitcnt vmcnt(39)
	v_cvt_pk_bf16_f32 v72, v72, v73
	v_cvt_pk_bf16_f32 v73, v74, v75
	s_waitcnt vmcnt(37)
	v_cvt_pk_bf16_f32 v68, v68, v69
	v_cvt_pk_bf16_f32 v69, v70, v71
	v_cvt_pk_bf16_f32 v64, v64, v65
	v_cvt_pk_bf16_f32 v65, v66, v67
	v_cvt_pk_bf16_f32 v60, v60, v61
	v_cvt_pk_bf16_f32 v61, v62, v63
	v_cvt_pk_bf16_f32 v56, v56, v57
	v_cvt_pk_bf16_f32 v57, v58, v59
	v_cvt_pk_bf16_f32 v52, v52, v53
	v_cvt_pk_bf16_f32 v53, v54, v55
	v_cvt_pk_bf16_f32 v48, v48, v49
	v_cvt_pk_bf16_f32 v49, v50, v51
	v_cvt_pk_bf16_f32 v44, v44, v45
	v_cvt_pk_bf16_f32 v45, v46, v47
	v_cvt_pk_bf16_f32 v40, v40, v41
	v_cvt_pk_bf16_f32 v41, v42, v43
	v_cvt_pk_bf16_f32 v36, v36, v37
	v_cvt_pk_bf16_f32 v37, v38, v39
	v_cvt_pk_bf16_f32 v32, v32, v33
	v_cvt_pk_bf16_f32 v33, v34, v35
	v_cvt_pk_bf16_f32 v28, v28, v29
	v_cvt_pk_bf16_f32 v29, v30, v31
	v_cvt_pk_bf16_f32 v24, v24, v25
	v_cvt_pk_bf16_f32 v25, v26, v27
	v_cvt_pk_bf16_f32 v20, v20, v21
	v_cvt_pk_bf16_f32 v21, v22, v23
	v_cvt_pk_bf16_f32 v16, v16, v17
	v_cvt_pk_bf16_f32 v17, v18, v19
	v_cvt_pk_bf16_f32 v12, v12, v13
	v_cvt_pk_bf16_f32 v13, v14, v15
	v_cvt_pk_bf16_f32 v8, v8, v9
	v_cvt_pk_bf16_f32 v9, v10, v11
	s_waitcnt vmcnt(36)
	v_cvt_pk_bf16_f32 v4, v4, v5
	v_cvt_pk_bf16_f32 v5, v6, v7
	s_add_u32 s44, s8, s44
	ds_write_b64 v233, v[72:73] offset:37888
	ds_write_b64 v234, v[68:69] offset:37888
	ds_write_b64 v233, v[64:65] offset:42624
	ds_write_b64 v233, v[60:61] offset:44992
	ds_write_b64 v233, v[56:57] offset:47360
	ds_write_b64 v233, v[52:53] offset:49728
	ds_write_b64 v233, v[48:49] offset:52096
	ds_write_b64 v233, v[44:45] offset:54464
	ds_write_b64 v233, v[40:41] offset:56832
	ds_write_b64 v233, v[36:37] offset:59200
	ds_write_b64 v233, v[32:33] offset:61568
	ds_write_b64 v233, v[28:29] offset:63936
	ds_write_b64 v238, v[24:25] offset:37888
	ds_write_b64 v237, v[20:21] offset:37888
	ds_write_b64 v236, v[16:17] offset:37888
	ds_write_b64 v235, v[12:13] offset:37888
	ds_write_b64 v231, v[8:9] offset:38400
	ds_write_b64 v230, v[4:5] offset:38400
	s_addc_u32 s45, s9, s45
	s_lshl_b64 s[58:59], s[42:43], 14
	v_lshlrev_b32_e32 v254, 2, v2
	global_load_dwordx4 v[72:75], v254, s[44:45] nt
	global_load_dwordx4 v[68:71], v239, s[44:45] nt
	global_load_dwordx4 v[64:67], v240, s[44:45] nt
	global_load_dwordx4 v[60:63], v241, s[44:45] nt
	global_load_dwordx4 v[56:59], v242, s[44:45] nt
	global_load_dwordx4 v[52:55], v243, s[44:45] nt
	global_load_dwordx4 v[48:51], v244, s[44:45] nt
	global_load_dwordx4 v[44:47], v245, s[44:45] nt
	global_load_dwordx4 v[40:43], v246, s[44:45] nt
	global_load_dwordx4 v[36:39], v247, s[44:45] nt
	global_load_dwordx4 v[32:35], v248, s[44:45] nt
	global_load_dwordx4 v[28:31], v249, s[44:45] nt
	global_load_dwordx4 v[24:27], v250, s[44:45] nt
	global_load_dwordx4 v[20:23], v251, s[44:45] nt
	global_load_dwordx4 v[16:19], v252, s[44:45] nt
	global_load_dwordx4 v[8:11], v253, s[44:45] nt
	s_add_u32 s44, s10, s58
	s_addc_u32 s45, s11, s59
	s_waitcnt vmcnt(51)
	v_cvt_pk_bf16_f32 v164, v164, v165
	v_cvt_pk_bf16_f32 v165, v166, v167
	s_waitcnt vmcnt(49)
	v_cvt_pk_bf16_f32 v152, v152, v153
	v_cvt_pk_bf16_f32 v153, v154, v155
	global_load_dwordx4 v[12:15], v254, s[44:45] nt
	global_load_dwordx4 v[4:7], v239, s[44:45] nt
	s_waitcnt lgkmcnt(0)
	s_barrier
	ds_write_b64 v233, v[164:165]
	ds_write_b64 v234, v[152:153]
	s_waitcnt vmcnt(49)
	v_cvt_pk_bf16_f32 v152, v200, v201
	v_cvt_pk_bf16_f32 v153, v202, v203
	s_lshl_b64 s[42:43], s[42:43], 7
	ds_write_b64 v233, v[152:153] offset:4736
	s_waitcnt vmcnt(47)
	v_cvt_pk_bf16_f32 v152, v192, v193
	v_cvt_pk_bf16_f32 v153, v194, v195
	s_or_b32 s42, s42, 64
	ds_write_b64 v233, v[152:153] offset:7104
	s_waitcnt vmcnt(45)
	v_cvt_pk_bf16_f32 v152, v184, v185
	v_cvt_pk_bf16_f32 v153, v186, v187
	s_lshl_b64 s[44:45], s[42:43], 10
	ds_write_b64 v233, v[152:153] offset:9472
	s_waitcnt vmcnt(43)
	v_cvt_pk_bf16_f32 v152, v176, v177
	v_cvt_pk_bf16_f32 v153, v178, v179
	s_add_u32 s44, s8, s44
	ds_write_b64 v233, v[152:153] offset:11840
	s_waitcnt vmcnt(41)
	v_cvt_pk_bf16_f32 v152, v168, v169
	v_cvt_pk_bf16_f32 v153, v170, v171
	s_addc_u32 s45, s9, s45
	s_lshl_b64 s[42:43], s[42:43], 7
	ds_write_b64 v233, v[152:153] offset:14208
	s_waitcnt vmcnt(39)
	v_cvt_pk_bf16_f32 v152, v156, v157
	v_cvt_pk_bf16_f32 v153, v158, v159
	s_waitcnt vmcnt(37)
	v_cvt_pk_bf16_f32 v144, v144, v145
	v_cvt_pk_bf16_f32 v145, v146, v147
	s_waitcnt vmcnt(35)
	v_cvt_pk_bf16_f32 v136, v136, v137
	v_cvt_pk_bf16_f32 v137, v138, v139
	s_waitcnt vmcnt(33)
	v_cvt_pk_bf16_f32 v128, v128, v129
	v_cvt_pk_bf16_f32 v129, v130, v131
	s_waitcnt vmcnt(31)
	v_cvt_pk_bf16_f32 v120, v120, v121
	v_cvt_pk_bf16_f32 v121, v122, v123
	s_waitcnt vmcnt(29)
	v_cvt_pk_bf16_f32 v112, v112, v113
	v_cvt_pk_bf16_f32 v113, v114, v115
	s_waitcnt vmcnt(27)
	v_cvt_pk_bf16_f32 v104, v104, v105
	v_cvt_pk_bf16_f32 v105, v106, v107
	s_waitcnt vmcnt(25)
	v_cvt_pk_bf16_f32 v96, v96, v97
	v_cvt_pk_bf16_f32 v97, v98, v99
	s_waitcnt vmcnt(23)
	v_cvt_pk_bf16_f32 v88, v88, v89
	v_cvt_pk_bf16_f32 v89, v90, v91
	v_cvt_pk_bf16_f32 v80, v80, v81
	v_cvt_pk_bf16_f32 v81, v82, v83
	v_cvt_pk_bf16_f32 v76, v76, v77
	v_cvt_pk_bf16_f32 v77, v78, v79
	s_add_u32 s42, s10, s42
	ds_write_b64 v233, v[152:153] offset:16576
	ds_write_b64 v233, v[144:145] offset:18944
	ds_write_b64 v233, v[136:137] offset:21312
	ds_write_b64 v233, v[128:129] offset:23680
	ds_write_b64 v233, v[120:121] offset:26048
	ds_write_b64 v233, v[112:113] offset:28416
	ds_write_b64 v233, v[104:105] offset:30784
	ds_write_b64 v233, v[96:97] offset:33152
	ds_write_b64 v233, v[88:89] offset:35520
	ds_write_b64 v231, v[80:81] offset:512
	ds_write_b64 v230, v[76:77] offset:512
	s_addc_u32 s43, s11, s43
	global_load_dwordx4 v[200:203], v254, s[44:45] nt
	global_load_dwordx4 v[192:195], v239, s[44:45] nt
	global_load_dwordx4 v[184:187], v240, s[44:45] nt
	global_load_dwordx4 v[176:179], v241, s[44:45] nt
	global_load_dwordx4 v[168:171], v242, s[44:45] nt
	global_load_dwordx4 v[164:167], v243, s[44:45] nt
	global_load_dwordx4 v[156:159], v244, s[44:45] nt
	global_load_dwordx4 v[152:155], v245, s[44:45] nt
	global_load_dwordx4 v[144:147], v246, s[44:45] nt
	global_load_dwordx4 v[136:139], v247, s[44:45] nt
	global_load_dwordx4 v[128:131], v248, s[44:45] nt
	global_load_dwordx4 v[120:123], v249, s[44:45] nt
	global_load_dwordx4 v[112:115], v250, s[44:45] nt
	global_load_dwordx4 v[104:107], v251, s[44:45] nt
	global_load_dwordx4 v[96:99], v252, s[44:45] nt
	global_load_dwordx4 v[80:83], v253, s[44:45] nt
	global_load_dwordx4 v[88:91], v254, s[42:43] nt
	global_load_dwordx4 v[76:79], v239, s[42:43] nt
	s_add_i32 s42, s22, -1
	v_readlane_b32 s42, v232, s42
	s_ashr_i32 s43, s42, 31
	s_waitcnt vmcnt(39)
	v_cvt_pk_bf16_f32 v208, v208, v209
	v_cvt_pk_bf16_f32 v209, v210, v211
	s_waitcnt vmcnt(37)
	v_cvt_pk_bf16_f32 v204, v204, v205
	v_cvt_pk_bf16_f32 v205, v206, v207
	v_cvt_pk_bf16_f32 v84, v84, v85
	v_cvt_pk_bf16_f32 v85, v86, v87
	s_lshl_b64 s[44:45], s[42:43], 14
	s_lshl_b64 s[58:59], s[42:43], 17
	s_waitcnt lgkmcnt(0)
	s_barrier
	ds_write_b64 v233, v[208:209] offset:37888
	ds_write_b64 v234, v[204:205] offset:37888
	v_cvt_pk_bf16_f32 v196, v196, v197
	v_cvt_pk_bf16_f32 v197, v198, v199
	v_cvt_pk_bf16_f32 v188, v188, v189
	v_cvt_pk_bf16_f32 v189, v190, v191
	v_cvt_pk_bf16_f32 v180, v180, v181
	v_cvt_pk_bf16_f32 v181, v182, v183
	v_cvt_pk_bf16_f32 v172, v172, v173
	v_cvt_pk_bf16_f32 v173, v174, v175
	v_cvt_pk_bf16_f32 v160, v160, v161
	v_cvt_pk_bf16_f32 v161, v162, v163
	v_cvt_pk_bf16_f32 v148, v148, v149
	v_cvt_pk_bf16_f32 v149, v150, v151
	v_cvt_pk_bf16_f32 v140, v140, v141
	v_cvt_pk_bf16_f32 v141, v142, v143
	v_cvt_pk_bf16_f32 v132, v132, v133
	v_cvt_pk_bf16_f32 v133, v134, v135
	v_cvt_pk_bf16_f32 v124, v124, v125
	v_cvt_pk_bf16_f32 v125, v126, v127
	v_cvt_pk_bf16_f32 v116, v116, v117
	v_cvt_pk_bf16_f32 v117, v118, v119
	v_cvt_pk_bf16_f32 v108, v108, v109
	v_cvt_pk_bf16_f32 v109, v110, v111
	v_cvt_pk_bf16_f32 v100, v100, v101
	v_cvt_pk_bf16_f32 v101, v102, v103
	v_cvt_pk_bf16_f32 v92, v92, v93
	v_cvt_pk_bf16_f32 v93, v94, v95
	ds_write_b64 v235, v[84:85] offset:37888
	v_cvt_pk_bf16_f32 v84, v212, v213
	v_cvt_pk_bf16_f32 v85, v214, v215
	s_add_u32 s58, s8, s58
	ds_write_b64 v233, v[196:197] offset:42624
	ds_write_b64 v233, v[188:189] offset:44992
	ds_write_b64 v233, v[180:181] offset:47360
	ds_write_b64 v233, v[172:173] offset:49728
	ds_write_b64 v233, v[160:161] offset:52096
	ds_write_b64 v233, v[148:149] offset:54464
	ds_write_b64 v233, v[140:141] offset:56832
	ds_write_b64 v233, v[132:133] offset:59200
	ds_write_b64 v233, v[124:125] offset:61568
	ds_write_b64 v233, v[116:117] offset:63936
	ds_write_b64 v238, v[108:109] offset:37888
	ds_write_b64 v237, v[100:101] offset:37888
	ds_write_b64 v236, v[92:93] offset:37888
	ds_write_b64 v231, v[84:85] offset:38400
	s_waitcnt vmcnt(36)
	v_cvt_pk_bf16_f32 v84, v216, v217
	v_cvt_pk_bf16_f32 v85, v218, v219
	s_addc_u32 s59, s9, s59
	ds_write_b64 v230, v[84:85] offset:38400
	s_add_u32 s44, s10, s44
	global_load_dwordx4 v[216:219], v254, s[58:59] nt
	global_load_dwordx4 v[212:215], v239, s[58:59] nt
	global_load_dwordx4 v[208:211], v240, s[58:59] nt
	global_load_dwordx4 v[204:207], v241, s[58:59] nt
	global_load_dwordx4 v[196:199], v242, s[58:59] nt
	global_load_dwordx4 v[188:191], v243, s[58:59] nt
	global_load_dwordx4 v[180:183], v244, s[58:59] nt
	global_load_dwordx4 v[172:175], v245, s[58:59] nt
	global_load_dwordx4 v[160:163], v246, s[58:59] nt
	global_load_dwordx4 v[148:151], v247, s[58:59] nt
	global_load_dwordx4 v[140:143], v248, s[58:59] nt
	global_load_dwordx4 v[132:135], v249, s[58:59] nt
	global_load_dwordx4 v[124:127], v250, s[58:59] nt
	global_load_dwordx4 v[116:119], v251, s[58:59] nt
	global_load_dwordx4 v[108:111], v252, s[58:59] nt
	global_load_dwordx4 v[92:95], v253, s[58:59] nt
	s_addc_u32 s45, s11, s45
	global_load_dwordx4 v[100:103], v254, s[44:45] nt
	global_load_dwordx4 v[84:87], v239, s[44:45] nt
	s_lshl_b64 s[42:43], s[42:43], 7
	s_or_b32 s42, s42, 64
	s_lshl_b64 s[44:45], s[42:43], 10
	s_add_u32 s44, s8, s44
	s_waitcnt vmcnt(53)
	v_cvt_pk_bf16_f32 v72, v72, v73
	v_cvt_pk_bf16_f32 v73, v74, v75
	s_waitcnt vmcnt(52)
	v_cvt_pk_bf16_f32 v68, v68, v69
	v_cvt_pk_bf16_f32 v69, v70, v71
	s_waitcnt vmcnt(38)
	v_cvt_pk_bf16_f32 v8, v8, v9
	v_cvt_pk_bf16_f32 v9, v10, v11
	s_addc_u32 s45, s9, s45
	s_lshl_b64 s[42:43], s[42:43], 7
	s_waitcnt lgkmcnt(0)
	s_barrier
	ds_write_b64 v233, v[72:73]
	ds_write_b64 v234, v[68:69]
	v_cvt_pk_bf16_f32 v64, v64, v65
	v_cvt_pk_bf16_f32 v65, v66, v67
	v_cvt_pk_bf16_f32 v60, v60, v61
	v_cvt_pk_bf16_f32 v61, v62, v63
	v_cvt_pk_bf16_f32 v56, v56, v57
	v_cvt_pk_bf16_f32 v57, v58, v59
	v_cvt_pk_bf16_f32 v52, v52, v53
	v_cvt_pk_bf16_f32 v53, v54, v55
	v_cvt_pk_bf16_f32 v48, v48, v49
	v_cvt_pk_bf16_f32 v49, v50, v51
	v_cvt_pk_bf16_f32 v44, v44, v45
	v_cvt_pk_bf16_f32 v45, v46, v47
	v_cvt_pk_bf16_f32 v40, v40, v41
	v_cvt_pk_bf16_f32 v41, v42, v43
	v_cvt_pk_bf16_f32 v36, v36, v37
	v_cvt_pk_bf16_f32 v37, v38, v39
	v_cvt_pk_bf16_f32 v32, v32, v33
	v_cvt_pk_bf16_f32 v33, v34, v35
	v_cvt_pk_bf16_f32 v28, v28, v29
	v_cvt_pk_bf16_f32 v29, v30, v31
	v_cvt_pk_bf16_f32 v24, v24, v25
	v_cvt_pk_bf16_f32 v25, v26, v27
	v_cvt_pk_bf16_f32 v20, v20, v21
	v_cvt_pk_bf16_f32 v21, v22, v23
	v_cvt_pk_bf16_f32 v16, v16, v17
	v_cvt_pk_bf16_f32 v17, v18, v19
	ds_write_b64 v233, v[8:9] offset:35520
	s_waitcnt vmcnt(37)
	v_cvt_pk_bf16_f32 v8, v12, v13
	v_cvt_pk_bf16_f32 v9, v14, v15
	s_waitcnt vmcnt(36)
	v_cvt_pk_bf16_f32 v4, v4, v5
	v_cvt_pk_bf16_f32 v5, v6, v7
	s_add_u32 s42, s10, s42
	ds_write_b64 v233, v[64:65] offset:4736
	ds_write_b64 v233, v[60:61] offset:7104
	ds_write_b64 v233, v[56:57] offset:9472
	ds_write_b64 v233, v[52:53] offset:11840
	ds_write_b64 v233, v[48:49] offset:14208
	ds_write_b64 v233, v[44:45] offset:16576
	ds_write_b64 v233, v[40:41] offset:18944
	ds_write_b64 v233, v[36:37] offset:21312
	ds_write_b64 v233, v[32:33] offset:23680
	ds_write_b64 v233, v[28:29] offset:26048
	ds_write_b64 v233, v[24:25] offset:28416
	ds_write_b64 v233, v[20:21] offset:30784
	ds_write_b64 v233, v[16:17] offset:33152
	ds_write_b64 v231, v[8:9] offset:512
	ds_write_b64 v230, v[4:5] offset:512
	s_addc_u32 s43, s11, s43
	global_load_dwordx4 v[72:75], v254, s[44:45] nt
	global_load_dwordx4 v[68:71], v239, s[44:45] nt
	global_load_dwordx4 v[64:67], v240, s[44:45] nt
	global_load_dwordx4 v[60:63], v241, s[44:45] nt
	global_load_dwordx4 v[56:59], v242, s[44:45] nt
	global_load_dwordx4 v[52:55], v243, s[44:45] nt
	global_load_dwordx4 v[48:51], v244, s[44:45] nt
	global_load_dwordx4 v[44:47], v245, s[44:45] nt
	global_load_dwordx4 v[40:43], v246, s[44:45] nt
	global_load_dwordx4 v[36:39], v247, s[44:45] nt
	global_load_dwordx4 v[32:35], v248, s[44:45] nt
	global_load_dwordx4 v[28:31], v249, s[44:45] nt
	global_load_dwordx4 v[24:27], v250, s[44:45] nt
	global_load_dwordx4 v[20:23], v251, s[44:45] nt
	global_load_dwordx4 v[16:19], v252, s[44:45] nt
	global_load_dwordx4 v[12:15], v253, s[44:45] nt
	global_load_dwordx4 v[8:11], v254, s[42:43] nt
	global_load_dwordx4 v[4:7], v239, s[42:43] nt
	v_readlane_b32 s42, v232, s22
	s_ashr_i32 s43, s42, 31
	s_lshl_b64 s[44:45], s[42:43], 14
	s_lshl_b64 s[58:59], s[42:43], 17
	s_add_u32 s58, s8, s58
	s_addc_u32 s59, s9, s59
	s_waitcnt vmcnt(53)
	v_cvt_pk_bf16_f32 v200, v200, v201
	v_cvt_pk_bf16_f32 v201, v202, v203
	s_waitcnt vmcnt(52)
	v_cvt_pk_bf16_f32 v192, v192, v193
	v_cvt_pk_bf16_f32 v193, v194, v195
	s_waitcnt vmcnt(38)
	v_cvt_pk_bf16_f32 v80, v80, v81
	v_cvt_pk_bf16_f32 v81, v82, v83
	s_add_u32 s44, s10, s44
	s_waitcnt lgkmcnt(0)
	s_barrier
	ds_write_b64 v233, v[200:201] offset:37888
	ds_write_b64 v234, v[192:193] offset:37888
	v_cvt_pk_bf16_f32 v184, v184, v185
	v_cvt_pk_bf16_f32 v185, v186, v187
	v_cvt_pk_bf16_f32 v176, v176, v177
	v_cvt_pk_bf16_f32 v177, v178, v179
	v_cvt_pk_bf16_f32 v168, v168, v169
	v_cvt_pk_bf16_f32 v169, v170, v171
	v_cvt_pk_bf16_f32 v164, v164, v165
	v_cvt_pk_bf16_f32 v165, v166, v167
	v_cvt_pk_bf16_f32 v156, v156, v157
	v_cvt_pk_bf16_f32 v157, v158, v159
	v_cvt_pk_bf16_f32 v152, v152, v153
	v_cvt_pk_bf16_f32 v153, v154, v155
	v_cvt_pk_bf16_f32 v144, v144, v145
	v_cvt_pk_bf16_f32 v145, v146, v147
	v_cvt_pk_bf16_f32 v136, v136, v137
	v_cvt_pk_bf16_f32 v137, v138, v139
	v_cvt_pk_bf16_f32 v128, v128, v129
	v_cvt_pk_bf16_f32 v129, v130, v131
	v_cvt_pk_bf16_f32 v120, v120, v121
	v_cvt_pk_bf16_f32 v121, v122, v123
	v_cvt_pk_bf16_f32 v112, v112, v113
	v_cvt_pk_bf16_f32 v113, v114, v115
	v_cvt_pk_bf16_f32 v104, v104, v105
	v_cvt_pk_bf16_f32 v105, v106, v107
	v_cvt_pk_bf16_f32 v96, v96, v97
	v_cvt_pk_bf16_f32 v97, v98, v99
	ds_write_b64 v235, v[80:81] offset:37888
	s_waitcnt vmcnt(37)
	v_cvt_pk_bf16_f32 v80, v88, v89
	v_cvt_pk_bf16_f32 v81, v90, v91
	s_waitcnt vmcnt(36)
	v_cvt_pk_bf16_f32 v76, v76, v77
	v_cvt_pk_bf16_f32 v77, v78, v79
	s_addc_u32 s45, s11, s45
	s_lshl_b64 s[42:43], s[42:43], 7
	ds_write_b64 v233, v[184:185] offset:42624
	ds_write_b64 v233, v[176:177] offset:44992
	ds_write_b64 v233, v[168:169] offset:47360
	ds_write_b64 v233, v[164:165] offset:49728
	ds_write_b64 v233, v[156:157] offset:52096
	ds_write_b64 v233, v[152:153] offset:54464
	ds_write_b64 v233, v[144:145] offset:56832
	ds_write_b64 v233, v[136:137] offset:59200
	ds_write_b64 v233, v[128:129] offset:61568
	ds_write_b64 v233, v[120:121] offset:63936
	ds_write_b64 v238, v[112:113] offset:37888
	ds_write_b64 v237, v[104:105] offset:37888
	ds_write_b64 v236, v[96:97] offset:37888
	ds_write_b64 v231, v[80:81] offset:38400
	ds_write_b64 v230, v[76:77] offset:38400
	s_or_b32 s42, s42, 64
	global_load_dwordx4 v[164:167], v254, s[58:59] nt
	global_load_dwordx4 v[152:155], v239, s[58:59] nt
	global_load_dwordx4 v[200:203], v240, s[58:59] nt
	global_load_dwordx4 v[192:195], v241, s[58:59] nt
	global_load_dwordx4 v[184:187], v242, s[58:59] nt
	global_load_dwordx4 v[176:179], v243, s[58:59] nt
	global_load_dwordx4 v[168:171], v244, s[58:59] nt
	global_load_dwordx4 v[156:159], v245, s[58:59] nt
	global_load_dwordx4 v[144:147], v246, s[58:59] nt
	global_load_dwordx4 v[136:139], v247, s[58:59] nt
	global_load_dwordx4 v[128:131], v248, s[58:59] nt
	global_load_dwordx4 v[120:123], v249, s[58:59] nt
	global_load_dwordx4 v[112:115], v250, s[58:59] nt
	global_load_dwordx4 v[104:107], v251, s[58:59] nt
	global_load_dwordx4 v[96:99], v252, s[58:59] nt
	global_load_dwordx4 v[88:91], v253, s[58:59] nt
	global_load_dwordx4 v[80:83], v254, s[44:45] nt
	global_load_dwordx4 v[76:79], v239, s[44:45] nt
	s_waitcnt vmcnt(53)
	v_cvt_pk_bf16_f32 v216, v216, v217
	v_cvt_pk_bf16_f32 v217, v218, v219
	s_waitcnt vmcnt(52)
	v_cvt_pk_bf16_f32 v212, v212, v213
	v_cvt_pk_bf16_f32 v213, v214, v215
	s_waitcnt vmcnt(38)
	v_cvt_pk_bf16_f32 v92, v92, v93
	v_cvt_pk_bf16_f32 v93, v94, v95
	s_lshl_b64 s[44:45], s[42:43], 10
	s_waitcnt lgkmcnt(0)
	s_barrier
	ds_write_b64 v233, v[216:217]
	ds_write_b64 v234, v[212:213]
	v_cvt_pk_bf16_f32 v208, v208, v209
	v_cvt_pk_bf16_f32 v209, v210, v211
	v_cvt_pk_bf16_f32 v204, v204, v205
	v_cvt_pk_bf16_f32 v205, v206, v207
	v_cvt_pk_bf16_f32 v196, v196, v197
	v_cvt_pk_bf16_f32 v197, v198, v199
	v_cvt_pk_bf16_f32 v188, v188, v189
	v_cvt_pk_bf16_f32 v189, v190, v191
	v_cvt_pk_bf16_f32 v180, v180, v181
	v_cvt_pk_bf16_f32 v181, v182, v183
	v_cvt_pk_bf16_f32 v172, v172, v173
	v_cvt_pk_bf16_f32 v173, v174, v175
	v_cvt_pk_bf16_f32 v160, v160, v161
	v_cvt_pk_bf16_f32 v161, v162, v163
	v_cvt_pk_bf16_f32 v148, v148, v149
	v_cvt_pk_bf16_f32 v149, v150, v151
	v_cvt_pk_bf16_f32 v140, v140, v141
	v_cvt_pk_bf16_f32 v141, v142, v143
	v_cvt_pk_bf16_f32 v132, v132, v133
	v_cvt_pk_bf16_f32 v133, v134, v135
	v_cvt_pk_bf16_f32 v124, v124, v125
	v_cvt_pk_bf16_f32 v125, v126, v127
	v_cvt_pk_bf16_f32 v116, v116, v117
	v_cvt_pk_bf16_f32 v117, v118, v119
	v_cvt_pk_bf16_f32 v108, v108, v109
	v_cvt_pk_bf16_f32 v109, v110, v111
	ds_write_b64 v233, v[92:93] offset:35520
	s_waitcnt vmcnt(37)
	v_cvt_pk_bf16_f32 v92, v100, v101
	v_cvt_pk_bf16_f32 v93, v102, v103
	s_waitcnt vmcnt(36)
	v_cvt_pk_bf16_f32 v84, v84, v85
	v_cvt_pk_bf16_f32 v85, v86, v87
	s_add_u32 s44, s8, s44
	ds_write_b64 v233, v[208:209] offset:4736
	ds_write_b64 v233, v[204:205] offset:7104
	ds_write_b64 v233, v[196:197] offset:9472
	ds_write_b64 v233, v[188:189] offset:11840
	ds_write_b64 v233, v[180:181] offset:14208
	ds_write_b64 v233, v[172:173] offset:16576
	ds_write_b64 v233, v[160:161] offset:18944
	ds_write_b64 v233, v[148:149] offset:21312
	ds_write_b64 v233, v[140:141] offset:23680
	ds_write_b64 v233, v[132:133] offset:26048
	ds_write_b64 v233, v[124:125] offset:28416
	ds_write_b64 v233, v[116:117] offset:30784
	ds_write_b64 v233, v[108:109] offset:33152
	ds_write_b64 v231, v[92:93] offset:512
	ds_write_b64 v230, v[84:85] offset:512
	s_addc_u32 s45, s9, s45
	global_load_dwordx4 v[208:211], v254, s[44:45] nt
	global_load_dwordx4 v[204:207], v239, s[44:45] nt
	global_load_dwordx4 v[196:199], v240, s[44:45] nt
	global_load_dwordx4 v[188:191], v241, s[44:45] nt
	global_load_dwordx4 v[180:183], v242, s[44:45] nt
	global_load_dwordx4 v[172:175], v243, s[44:45] nt
	global_load_dwordx4 v[160:163], v244, s[44:45] nt
	global_load_dwordx4 v[148:151], v245, s[44:45] nt
	global_load_dwordx4 v[140:143], v246, s[44:45] nt
	global_load_dwordx4 v[132:135], v247, s[44:45] nt
	global_load_dwordx4 v[124:127], v248, s[44:45] nt
	global_load_dwordx4 v[116:119], v249, s[44:45] nt
	global_load_dwordx4 v[108:111], v250, s[44:45] nt
	global_load_dwordx4 v[100:103], v251, s[44:45] nt
	global_load_dwordx4 v[92:95], v252, s[44:45] nt
	global_load_dwordx4 v[84:87], v253, s[44:45] nt
	s_lshl_b64 s[42:43], s[42:43], 7
	s_add_u32 s42, s10, s42
	s_addc_u32 s43, s11, s43
	global_load_dwordx4 v[212:215], v254, s[42:43] nt
	global_load_dwordx4 v[216:219], v239, s[42:43] nt
	s_waitcnt lgkmcnt(0)
	s_barrier
	s_add_i32 s23, s23, 6
	s_add_i32 s22, s22, 3
	s_cmp_gt_u32 s23, 53
	s_cbranch_scc0 .LBB0_731
	v_readlane_b32 s22, v232, 31
	s_ashr_i32 s23, s22, 31
	s_lshl_b64 s[22:23], s[22:23], 7
	s_or_b32 s22, s22, 64
	s_lshl_b64 s[42:43], s[22:23], 10
	s_add_u32 s42, s8, s42
	s_waitcnt vmcnt(53)
	v_cvt_pk_bf16_f32 v72, v72, v73
	v_cvt_pk_bf16_f32 v73, v74, v75
	s_waitcnt vmcnt(52)
	v_cvt_pk_bf16_f32 v68, v68, v69
	v_cvt_pk_bf16_f32 v69, v70, v71
	s_waitcnt vmcnt(51)
	v_cvt_pk_bf16_f32 v64, v64, v65
	v_cvt_pk_bf16_f32 v65, v66, v67
	s_waitcnt vmcnt(50)
	v_cvt_pk_bf16_f32 v60, v60, v61
	v_cvt_pk_bf16_f32 v61, v62, v63
	s_waitcnt vmcnt(49)
	v_cvt_pk_bf16_f32 v56, v56, v57
	v_cvt_pk_bf16_f32 v57, v58, v59
	s_waitcnt vmcnt(48)
	v_cvt_pk_bf16_f32 v52, v52, v53
	v_cvt_pk_bf16_f32 v53, v54, v55
	s_waitcnt vmcnt(47)
	v_cvt_pk_bf16_f32 v48, v48, v49
	v_cvt_pk_bf16_f32 v49, v50, v51
	s_waitcnt vmcnt(46)
	v_cvt_pk_bf16_f32 v44, v44, v45
	v_cvt_pk_bf16_f32 v45, v46, v47
	s_waitcnt vmcnt(45)
	v_cvt_pk_bf16_f32 v40, v40, v41
	v_cvt_pk_bf16_f32 v41, v42, v43
	s_waitcnt vmcnt(44)
	v_cvt_pk_bf16_f32 v36, v36, v37
	v_cvt_pk_bf16_f32 v37, v38, v39
	s_waitcnt vmcnt(43)
	v_cvt_pk_bf16_f32 v32, v32, v33
	v_cvt_pk_bf16_f32 v33, v34, v35
	s_waitcnt vmcnt(42)
	v_cvt_pk_bf16_f32 v28, v28, v29
	v_cvt_pk_bf16_f32 v29, v30, v31
	s_waitcnt vmcnt(41)
	v_cvt_pk_bf16_f32 v24, v24, v25
	v_cvt_pk_bf16_f32 v25, v26, v27
	s_waitcnt vmcnt(40)
	v_cvt_pk_bf16_f32 v20, v20, v21
	v_cvt_pk_bf16_f32 v21, v22, v23
	s_waitcnt vmcnt(39)
	v_cvt_pk_bf16_f32 v16, v16, v17
	v_cvt_pk_bf16_f32 v17, v18, v19
	s_waitcnt vmcnt(38)
	v_cvt_pk_bf16_f32 v12, v12, v13
	v_cvt_pk_bf16_f32 v13, v14, v15
	s_waitcnt vmcnt(37)
	v_cvt_pk_bf16_f32 v8, v8, v9
	v_cvt_pk_bf16_f32 v9, v10, v11
	s_waitcnt vmcnt(36)
	v_cvt_pk_bf16_f32 v4, v4, v5
	v_cvt_pk_bf16_f32 v5, v6, v7
	s_addc_u32 s43, s9, s43
	s_lshl_b64 s[22:23], s[22:23], 7
	ds_write_b64 v233, v[72:73] offset:37888
	ds_write_b64 v234, v[68:69] offset:37888
	ds_write_b64 v233, v[64:65] offset:42624
	ds_write_b64 v233, v[60:61] offset:44992
	ds_write_b64 v233, v[56:57] offset:47360
	ds_write_b64 v233, v[52:53] offset:49728
	ds_write_b64 v233, v[48:49] offset:52096
	ds_write_b64 v233, v[44:45] offset:54464
	ds_write_b64 v233, v[40:41] offset:56832
	ds_write_b64 v233, v[36:37] offset:59200
	ds_write_b64 v233, v[32:33] offset:61568
	ds_write_b64 v233, v[28:29] offset:63936
	ds_write_b64 v238, v[24:25] offset:37888
	ds_write_b64 v237, v[20:21] offset:37888
	ds_write_b64 v236, v[16:17] offset:37888
	ds_write_b64 v235, v[12:13] offset:37888
	ds_write_b64 v231, v[8:9] offset:38400
	ds_write_b64 v230, v[4:5] offset:38400
	s_add_u32 s22, s10, s22
	global_load_dwordx4 v[36:39], v240, s[42:43] nt
	global_load_dwordx4 v[40:43], v241, s[42:43] nt
	global_load_dwordx4 v[44:47], v242, s[42:43] nt
	global_load_dwordx4 v[48:51], v243, s[42:43] nt
	global_load_dwordx4 v[52:55], v244, s[42:43] nt
	global_load_dwordx4 v[56:59], v245, s[42:43] nt
	global_load_dwordx4 v[60:63], v246, s[42:43] nt
	global_load_dwordx4 v[64:67], v247, s[42:43] nt
	global_load_dwordx4 v[32:35], v248, s[42:43] nt
	global_load_dwordx4 v[28:31], v249, s[42:43] nt
	global_load_dwordx4 v[24:27], v250, s[42:43] nt
	global_load_dwordx4 v[20:23], v251, s[42:43] nt
	global_load_dwordx4 v[16:19], v252, s[42:43] nt
	global_load_dwordx4 v[8:11], v253, s[42:43] nt
	s_addc_u32 s23, s11, s23
	global_load_dwordx4 v[68:71], v254, s[42:43] nt
	global_load_dwordx4 v[12:15], v254, s[22:23] nt
	global_load_dwordx4 v[72:75], v239, s[42:43] nt
	global_load_dwordx4 v[4:7], v239, s[22:23] nt
	s_waitcnt vmcnt(53)
	v_cvt_pk_bf16_f32 v164, v164, v165
	v_cvt_pk_bf16_f32 v165, v166, v167
	s_waitcnt vmcnt(52)
	v_cvt_pk_bf16_f32 v152, v152, v153
	v_cvt_pk_bf16_f32 v153, v154, v155
	s_waitcnt lgkmcnt(0)
	s_barrier
	ds_write_b64 v233, v[164:165]
	ds_write_b64 v234, v[152:153]
	s_waitcnt vmcnt(51)
	v_cvt_pk_bf16_f32 v152, v200, v201
	v_cvt_pk_bf16_f32 v153, v202, v203
	ds_write_b64 v233, v[152:153] offset:4736
	s_waitcnt vmcnt(50)
	v_cvt_pk_bf16_f32 v152, v192, v193
	v_cvt_pk_bf16_f32 v153, v194, v195
	ds_write_b64 v233, v[152:153] offset:7104
	s_waitcnt vmcnt(49)
	v_cvt_pk_bf16_f32 v152, v184, v185
	v_cvt_pk_bf16_f32 v153, v186, v187
	ds_write_b64 v233, v[152:153] offset:9472
	s_waitcnt vmcnt(48)
	v_cvt_pk_bf16_f32 v152, v176, v177
	v_cvt_pk_bf16_f32 v153, v178, v179
	ds_write_b64 v233, v[152:153] offset:11840
	s_waitcnt vmcnt(47)
	v_cvt_pk_bf16_f32 v152, v168, v169
	v_cvt_pk_bf16_f32 v153, v170, v171
	ds_write_b64 v233, v[152:153] offset:14208
	s_waitcnt vmcnt(46)
	v_cvt_pk_bf16_f32 v152, v156, v157
	v_cvt_pk_bf16_f32 v153, v158, v159
	s_waitcnt vmcnt(45)
	v_cvt_pk_bf16_f32 v144, v144, v145
	v_cvt_pk_bf16_f32 v145, v146, v147
	s_waitcnt vmcnt(44)
	v_cvt_pk_bf16_f32 v136, v136, v137
	v_cvt_pk_bf16_f32 v137, v138, v139
	s_waitcnt vmcnt(43)
	v_cvt_pk_bf16_f32 v128, v128, v129
	v_cvt_pk_bf16_f32 v129, v130, v131
	s_waitcnt vmcnt(42)
	v_cvt_pk_bf16_f32 v120, v120, v121
	v_cvt_pk_bf16_f32 v121, v122, v123
	s_waitcnt vmcnt(41)
	v_cvt_pk_bf16_f32 v112, v112, v113
	v_cvt_pk_bf16_f32 v113, v114, v115
	s_waitcnt vmcnt(40)
	v_cvt_pk_bf16_f32 v104, v104, v105
	v_cvt_pk_bf16_f32 v105, v106, v107
	s_waitcnt vmcnt(39)
	v_cvt_pk_bf16_f32 v96, v96, v97
	v_cvt_pk_bf16_f32 v97, v98, v99
	s_waitcnt vmcnt(38)
	v_cvt_pk_bf16_f32 v88, v88, v89
	v_cvt_pk_bf16_f32 v89, v90, v91
	s_waitcnt vmcnt(37)
	v_cvt_pk_bf16_f32 v80, v80, v81
	v_cvt_pk_bf16_f32 v81, v82, v83
	s_waitcnt vmcnt(36)
	v_cvt_pk_bf16_f32 v76, v76, v77
	v_cvt_pk_bf16_f32 v77, v78, v79
	ds_write_b64 v233, v[152:153] offset:16576
	ds_write_b64 v233, v[144:145] offset:18944
	ds_write_b64 v233, v[136:137] offset:21312
	ds_write_b64 v233, v[128:129] offset:23680
	ds_write_b64 v233, v[120:121] offset:26048
	ds_write_b64 v233, v[112:113] offset:28416
	ds_write_b64 v233, v[104:105] offset:30784
	ds_write_b64 v233, v[96:97] offset:33152
	ds_write_b64 v233, v[88:89] offset:35520
	ds_write_b64 v231, v[80:81] offset:512
	ds_write_b64 v230, v[76:77] offset:512
	s_waitcnt vmcnt(35)
	v_cvt_pk_bf16_f32 v76, v208, v209
	v_cvt_pk_bf16_f32 v77, v210, v211
	s_waitcnt lgkmcnt(0)
	s_barrier
	ds_write_b64 v233, v[76:77] offset:37888
	s_waitcnt vmcnt(34)
	v_cvt_pk_bf16_f32 v76, v204, v205
	v_cvt_pk_bf16_f32 v77, v206, v207
	ds_write_b64 v234, v[76:77] offset:37888
	s_waitcnt vmcnt(33)
	v_cvt_pk_bf16_f32 v76, v196, v197
	v_cvt_pk_bf16_f32 v77, v198, v199
	ds_write_b64 v233, v[76:77] offset:42624
	s_waitcnt vmcnt(32)
	v_cvt_pk_bf16_f32 v76, v188, v189
	v_cvt_pk_bf16_f32 v77, v190, v191
	ds_write_b64 v233, v[76:77] offset:44992
	s_waitcnt vmcnt(31)
	v_cvt_pk_bf16_f32 v76, v180, v181
	v_cvt_pk_bf16_f32 v77, v182, v183
	ds_write_b64 v233, v[76:77] offset:47360
	s_waitcnt vmcnt(30)
	v_cvt_pk_bf16_f32 v76, v172, v173
	v_cvt_pk_bf16_f32 v77, v174, v175
	ds_write_b64 v233, v[76:77] offset:49728
	s_waitcnt vmcnt(29)
	v_cvt_pk_bf16_f32 v76, v160, v161
	v_cvt_pk_bf16_f32 v77, v162, v163
	ds_write_b64 v233, v[76:77] offset:52096
	s_waitcnt vmcnt(28)
	v_cvt_pk_bf16_f32 v76, v148, v149
	v_cvt_pk_bf16_f32 v77, v150, v151
	ds_write_b64 v233, v[76:77] offset:54464
	s_waitcnt vmcnt(27)
	v_cvt_pk_bf16_f32 v76, v140, v141
	v_cvt_pk_bf16_f32 v77, v142, v143
	ds_write_b64 v233, v[76:77] offset:56832
	s_waitcnt vmcnt(26)
	v_cvt_pk_bf16_f32 v76, v132, v133
	v_cvt_pk_bf16_f32 v77, v134, v135
	ds_write_b64 v233, v[76:77] offset:59200
	s_waitcnt vmcnt(25)
	v_cvt_pk_bf16_f32 v76, v124, v125
	v_cvt_pk_bf16_f32 v77, v126, v127
	ds_write_b64 v233, v[76:77] offset:61568
	s_waitcnt vmcnt(24)
	v_cvt_pk_bf16_f32 v76, v116, v117
	v_cvt_pk_bf16_f32 v77, v118, v119
	ds_write_b64 v233, v[76:77] offset:63936
	s_waitcnt vmcnt(23)
	v_cvt_pk_bf16_f32 v76, v108, v109
	v_cvt_pk_bf16_f32 v77, v110, v111
	ds_write_b64 v238, v[76:77] offset:37888
	s_waitcnt vmcnt(22)
	v_cvt_pk_bf16_f32 v76, v100, v101
	v_cvt_pk_bf16_f32 v77, v102, v103
	ds_write_b64 v237, v[76:77] offset:37888
	s_waitcnt vmcnt(21)
	v_cvt_pk_bf16_f32 v76, v92, v93
	v_cvt_pk_bf16_f32 v77, v94, v95
	ds_write_b64 v236, v[76:77] offset:37888
	s_waitcnt vmcnt(20)
	v_cvt_pk_bf16_f32 v76, v84, v85
	v_cvt_pk_bf16_f32 v77, v86, v87
	ds_write_b64 v235, v[76:77] offset:37888
	s_waitcnt vmcnt(19)
	v_cvt_pk_bf16_f32 v76, v212, v213
	v_cvt_pk_bf16_f32 v77, v214, v215
	ds_write_b64 v231, v[76:77] offset:38400
	s_waitcnt vmcnt(18)
	v_cvt_pk_bf16_f32 v76, v216, v217
	v_cvt_pk_bf16_f32 v77, v218, v219
	ds_write_b64 v230, v[76:77] offset:38400
	s_waitcnt vmcnt(3)
	v_cvt_pk_bf16_f32 v68, v68, v69
	v_cvt_pk_bf16_f32 v69, v70, v71
	s_waitcnt lgkmcnt(0)
	s_barrier
	ds_write_b64 v233, v[68:69]
	s_waitcnt vmcnt(1)
	v_cvt_pk_bf16_f32 v68, v72, v73
	v_cvt_pk_bf16_f32 v69, v74, v75
	v_cvt_pk_bf16_f32 v36, v36, v37
	v_cvt_pk_bf16_f32 v37, v38, v39
	ds_write_b64 v234, v[68:69]
	ds_write_b64 v233, v[36:37] offset:4736
	v_cvt_pk_bf16_f32 v36, v40, v41
	v_cvt_pk_bf16_f32 v37, v42, v43
	ds_write_b64 v233, v[36:37] offset:7104
	v_cvt_pk_bf16_f32 v36, v44, v45
	v_cvt_pk_bf16_f32 v37, v46, v47
	ds_write_b64 v233, v[36:37] offset:9472
	v_cvt_pk_bf16_f32 v36, v48, v49
	v_cvt_pk_bf16_f32 v37, v50, v51
	ds_write_b64 v233, v[36:37] offset:11840
	v_cvt_pk_bf16_f32 v36, v52, v53
	v_cvt_pk_bf16_f32 v37, v54, v55
	ds_write_b64 v233, v[36:37] offset:14208
	v_cvt_pk_bf16_f32 v36, v56, v57
	v_cvt_pk_bf16_f32 v37, v58, v59
	ds_write_b64 v233, v[36:37] offset:16576
	v_cvt_pk_bf16_f32 v36, v60, v61
	v_cvt_pk_bf16_f32 v37, v62, v63
	v_cvt_pk_bf16_f32 v8, v8, v9
	v_cvt_pk_bf16_f32 v9, v10, v11
	ds_write_b64 v233, v[36:37] offset:18944
	v_cvt_pk_bf16_f32 v36, v64, v65
	v_cvt_pk_bf16_f32 v37, v66, v67
	v_cvt_pk_bf16_f32 v32, v32, v33
	v_cvt_pk_bf16_f32 v33, v34, v35
	v_cvt_pk_bf16_f32 v28, v28, v29
	v_cvt_pk_bf16_f32 v29, v30, v31
	v_cvt_pk_bf16_f32 v24, v24, v25
	v_cvt_pk_bf16_f32 v25, v26, v27
	v_cvt_pk_bf16_f32 v20, v20, v21
	v_cvt_pk_bf16_f32 v21, v22, v23
	v_cvt_pk_bf16_f32 v16, v16, v17
	v_cvt_pk_bf16_f32 v17, v18, v19
	ds_write_b64 v233, v[8:9] offset:35520
	v_cvt_pk_bf16_f32 v8, v12, v13
	v_cvt_pk_bf16_f32 v9, v14, v15
	s_waitcnt vmcnt(0)
	v_cvt_pk_bf16_f32 v4, v4, v5
	v_cvt_pk_bf16_f32 v5, v6, v7
	ds_write_b64 v233, v[36:37] offset:21312
	ds_write_b64 v233, v[32:33] offset:23680
	ds_write_b64 v233, v[28:29] offset:26048
	ds_write_b64 v233, v[24:25] offset:28416
	ds_write_b64 v233, v[20:21] offset:30784
	ds_write_b64 v233, v[16:17] offset:33152
	ds_write_b64 v231, v[8:9] offset:512
	ds_write_b64 v230, v[4:5] offset:512
	s_waitcnt lgkmcnt(0)
	s_barrier
	s_mov_b64 s[22:23], 0
	s_setprio 0

.LBB0_828:
	v_mov_b32_e32 v220, v0
	s_ashr_i32 s3, s2, 1
	s_mul_hi_i32 s5, s3, 0x12000
	v_readfirstlane_b32 s4, v220
	s_ashr_i32 s46, s4, 6
	s_mul_i32 s4, s3, 0x12000
	s_add_u32 s4, s54, s4
	v_add_u32_e32 v40, 0x200, v220
	v_add_u32_e32 v42, 0x400, v220
	v_add_u32_e32 v44, 0x600, v220
	s_addc_u32 s5, s55, s5
	v_ashrrev_i32_e32 v221, 31, v220
	v_ashrrev_i32_e32 v41, 31, v40
	v_ashrrev_i32_e32 v43, 31, v42
	v_ashrrev_i32_e32 v45, 31, v44
	v_lshl_add_u64 v[4:5], v[220:221], 4, s[4:5]
	v_lshl_add_u64 v[8:9], v[40:41], 4, s[4:5]
	v_lshl_add_u64 v[12:13], v[42:43], 4, s[4:5]
	v_lshl_add_u64 v[16:17], v[44:45], 4, s[4:5]
	s_waitcnt lgkmcnt(0)
	global_load_dwordx4 v[4:7], v[4:5], off
	s_nop 0
	global_load_dwordx4 v[8:11], v[8:9], off
	s_nop 0
	global_load_dwordx4 v[12:15], v[12:13], off
	s_nop 0
	global_load_dwordx4 v[16:19], v[16:17], off
	v_add_u32_e32 v46, 0x800, v220
	v_ashrrev_i32_e32 v47, 31, v46
	v_lshl_add_u64 v[20:21], v[46:47], 4, s[4:5]
	global_load_dwordx4 v[20:23], v[20:21], off
	v_add_u32_e32 v48, 0xa00, v220
	v_ashrrev_i32_e32 v49, 31, v48
	v_lshl_add_u64 v[24:25], v[48:49], 4, s[4:5]
	global_load_dwordx4 v[24:27], v[24:25], off
	v_add_u32_e32 v50, 0xc00, v220
	v_ashrrev_i32_e32 v51, 31, v50
	v_lshl_add_u64 v[28:29], v[50:51], 4, s[4:5]
	global_load_dwordx4 v[28:31], v[28:29], off
	v_add_u32_e32 v52, 0xe00, v220
	v_ashrrev_i32_e32 v53, 31, v52
	v_lshl_add_u64 v[32:33], v[52:53], 4, s[4:5]
	global_load_dwordx4 v[32:35], v[32:33], off
	v_add_u32_e32 v54, 0x1000, v220
	v_mul_hi_i32 v2, v220, s70
	v_ashrrev_i32_e32 v55, 31, v54
	v_lshrrev_b32_e32 v36, 31, v2
	v_ashrrev_i32_e32 v2, 3, v2
	v_mul_hi_i32 v37, v40, s70
	v_add_u32_e32 v2, v2, v36
	v_lshrrev_b32_e32 v47, 31, v37
	v_ashrrev_i32_e32 v49, 3, v37
	v_lshl_add_u64 v[36:37], v[54:55], 4, s[4:5]
	global_load_dwordx4 v[36:39], v[36:37], off
	v_mul_hi_i32 v41, v42, s70
	v_mul_hi_i32 v43, v44, s70
	v_lshrrev_b32_e32 v51, 31, v41
	v_ashrrev_i32_e32 v41, 3, v41
	v_lshrrev_b32_e32 v53, 31, v43
	v_ashrrev_i32_e32 v43, 3, v43
	v_mul_lo_u32 v56, v2, 36
	v_add_u32_e32 v47, v49, v47
	v_add_u32_e32 v41, v41, v51
	v_add_u32_e32 v43, v43, v53
	v_sub_u32_e32 v49, v220, v56
	v_mul_lo_u32 v51, v47, 36
	v_mul_lo_u32 v53, v41, 36
	v_mul_lo_u32 v56, v43, 36
	v_mul_hi_i32 v45, v46, s70
	v_mul_lo_u32 v2, v2, s71
	v_lshlrev_b32_e32 v49, 4, v49
	v_sub_u32_e32 v40, v40, v51
	v_sub_u32_e32 v42, v42, v53
	v_sub_u32_e32 v44, v44, v56
	v_lshrrev_b32_e32 v55, 31, v45
	v_ashrrev_i32_e32 v45, 3, v45
	v_mul_lo_u32 v47, v47, s71
	v_mul_lo_u32 v41, v41, s71
	v_mul_lo_u32 v43, v43, s71
	v_add3_u32 v2, s56, v2, v49
	v_lshlrev_b32_e32 v40, 4, v40
	v_lshlrev_b32_e32 v42, 4, v42
	v_lshlrev_b32_e32 v44, 4, v44
	v_add3_u32 v40, s56, v47, v40
	v_add3_u32 v41, s56, v41, v42
	v_add3_u32 v42, s56, v43, v44
	s_and_b32 s21, s2, 1
	s_cmp_lt_i32 s46, 4
	v_and_b32_e32 v221, 31, v220
	s_cselect_b64 s[4:5], -1, 0
	s_cmp_gt_i32 s46, 3
	s_waitcnt vmcnt(0)
	ds_write_b128 v2, v[4:7]
	ds_write_b128 v40, v[8:11]
	ds_write_b128 v41, v[12:15]
	ds_write_b128 v42, v[16:19]
	v_add_u32_e32 v2, v45, v55
	v_mul_lo_u32 v4, v2, 36
	v_sub_u32_e32 v4, v46, v4
	v_mul_lo_u32 v2, v2, s71
	v_lshlrev_b32_e32 v4, 4, v4
	v_add3_u32 v2, s56, v2, v4
	ds_write_b128 v2, v[20:23]
	v_mul_hi_i32 v2, v48, s70
	v_lshrrev_b32_e32 v4, 31, v2
	v_ashrrev_i32_e32 v2, 3, v2
	v_add_u32_e32 v2, v2, v4
	v_mul_lo_u32 v4, v2, 36
	v_sub_u32_e32 v4, v48, v4
	v_mul_lo_u32 v2, v2, s71
	v_lshlrev_b32_e32 v4, 4, v4
	v_add3_u32 v2, s56, v2, v4
	ds_write_b128 v2, v[24:27]
	v_mul_hi_i32 v2, v50, s70
	v_lshrrev_b32_e32 v4, 31, v2
	v_ashrrev_i32_e32 v2, 3, v2
	v_add_u32_e32 v2, v2, v4
	v_mul_lo_u32 v4, v2, 36
	v_sub_u32_e32 v4, v50, v4
	v_mul_lo_u32 v2, v2, s71
	v_lshlrev_b32_e32 v4, 4, v4
	v_add3_u32 v2, s56, v2, v4
	ds_write_b128 v2, v[28:31]
	v_mul_hi_i32 v2, v52, s70
	v_lshrrev_b32_e32 v4, 31, v2
	v_ashrrev_i32_e32 v2, 3, v2
	v_add_u32_e32 v2, v2, v4
	v_mul_lo_u32 v4, v2, 36
	v_sub_u32_e32 v4, v52, v4
	v_mul_lo_u32 v2, v2, s71
	v_lshlrev_b32_e32 v4, 4, v4
	v_add3_u32 v2, s56, v2, v4
	ds_write_b128 v2, v[32:35]
	v_mul_hi_i32 v2, v54, s70
	v_lshrrev_b32_e32 v4, 31, v2
	v_ashrrev_i32_e32 v2, 3, v2
	v_add_u32_e32 v2, v2, v4
	v_mul_lo_u32 v4, v2, 36
	v_sub_u32_e32 v4, v54, v4
	v_mul_lo_u32 v2, v2, s71
	v_lshlrev_b32_e32 v4, 4, v4
	v_add3_u32 v2, s56, v2, v4
	ds_write_b128 v2, v[36:39]
	s_mov_b64 s[22:23], -1
	s_cbranch_scc0 .LBB0_832
	s_setprio 2
	s_lshl_b32 s22, s3, 6
	s_ashr_i32 s23, s22, 31
	s_lshl_b64 s[22:23], s[22:23], 2
	s_add_u32 s22, s16, s22
	v_lshlrev_b32_e32 v2, 2, v221
	s_addc_u32 s23, s17, s23
	v_lshl_or_b32 v2, s21, 7, v2
	global_load_dword v233, v2, s[22:23]
	v_mov_b32_e32 v2, 2
	v_lshlrev_b32_sdwa v2, v2, v220 dst_sel:DWORD dst_unused:UNUSED_PAD src0_sel:DWORD src1_sel:BYTE_0
	v_lshlrev_b32_sdwa v209, v223, v220 dst_sel:DWORD dst_unused:UNUSED_PAD src0_sel:DWORD src1_sel:BYTE_0
	v_or_b32_e32 v90, 0x400, v2
	v_or_b32_e32 v88, 0x800, v2
	v_or_b32_e32 v226, 0xc00, v2
	v_or_b32_e32 v106, 0x1000, v2
	v_or_b32_e32 v104, 0x1400, v2
	v_or_b32_e32 v224, 0x1800, v2
	v_or_b32_e32 v222, 0x1c00, v2
	v_or_b32_e32 v206, 0x2000, v2
	v_or_b32_e32 v204, 0x2400, v2
	v_or_b32_e32 v218, 0x2800, v2
	v_or_b32_e32 v214, 0x2c00, v2
	v_or_b32_e32 v212, 0x3000, v2
	v_or_b32_e32 v216, 0x3400, v2
	v_or_b32_e32 v210, 0x3800, v2
	v_or_b32_e32 v208, 0x3c00, v2
	v_lshlrev_b32_e32 v219, 2, v90
	v_lshlrev_b32_e32 v89, 2, v88
	v_lshlrev_b32_e32 v91, 2, v226
	v_lshlrev_b32_e32 v105, 2, v106
	v_lshlrev_b32_e32 v107, 2, v104
	v_lshlrev_b32_e32 v172, 2, v224
	v_lshlrev_b32_e32 v205, 2, v222
	v_lshlrev_b32_e32 v207, 2, v206
	v_lshlrev_b32_e32 v213, 2, v204
	v_lshlrev_b32_e32 v215, 2, v218
	v_lshlrev_b32_e32 v237, 2, v214
	v_lshlrev_b32_e32 v238, 2, v212
	v_lshlrev_b32_e32 v239, 2, v216
	v_lshlrev_b32_e32 v240, 2, v210
	v_lshlrev_b32_e32 v244, 2, v208
	v_or_b32_sdwa v5, v220, s66 dst_sel:DWORD dst_unused:UNUSED_PAD src0_sel:BYTE_0 src1_sel:DWORD
	v_lshlrev_b32_e32 v4, 3, v220
	v_bfe_u32 v6, v220, 3, 5
	v_lshrrev_b32_e32 v217, 6, v5
	v_lshrrev_b32_e32 v5, 3, v5
	v_and_b32_e32 v7, 0x1f8, v4
	v_and_b32_e32 v4, 56, v4
	v_mad_u32_u24 v6, v6, s71, 0
	v_mad_u32_u24 v5, v5, s71, 0
	v_add_u32_e32 v254, 0, v7
	v_add_u32_e32 v235, v6, v4
	v_add_u32_e32 v234, v5, v4
	v_bfe_u32 v211, v220, 6, 2
	v_mad_u32_u24 v236, v211, s71, v254
	v_mad_u32_u24 v173, v217, s71, v254
	v_lshlrev_b32_e32 v246, 2, v206
	v_lshlrev_b32_e32 v247, 2, v204
	v_lshlrev_b32_e32 v249, 2, v214
	v_lshlrev_b32_e32 v250, 2, v212
	v_lshlrev_b32_e32 v251, 2, v216
	v_mad_u32_u24 v216, v211, s71, v225
	v_lshlrev_b32_e32 v252, 2, v210
	v_mad_u32_u24 v210, v211, s71, v227
	v_lshlrev_b32_e32 v253, 2, v208
	v_mad_u32_u24 v208, v211, s71, v228
	v_mad_u32_u24 v211, v211, s71, v229
	v_lshlrev_b32_e32 v241, 2, v226
	v_lshlrev_b32_e32 v242, 2, v106
	v_lshlrev_b32_e32 v243, 2, v104
	v_lshlrev_b32_e32 v245, 2, v222
	v_lshlrev_b32_e32 v248, 2, v218
	v_add_u32_e32 v226, v254, v208
	s_waitcnt vmcnt(0)
	v_readlane_b32 s22, v233, 0
	s_ashr_i32 s23, s22, 31
	s_lshl_b64 s[34:35], s[22:23], 17
	s_add_u32 s34, s8, s34
	s_addc_u32 s35, s9, s35
	s_lshl_b64 s[50:51], s[22:23], 14
	global_load_dwordx4 v[84:87], v209, s[34:35] nt
	global_load_dwordx4 v[124:127], v207, s[34:35] nt
	s_add_u32 s50, s10, s50
	global_load_dwordx4 v[92:95], v219, s[34:35] nt
	global_load_dwordx4 v[140:143], v237, s[34:35] nt
	global_load_dwordx4 v[96:99], v89, s[34:35] nt
	global_load_dwordx4 v[100:103], v91, s[34:35] nt
	global_load_dwordx4 v[108:111], v105, s[34:35] nt
	global_load_dwordx4 v[112:115], v107, s[34:35] nt
	global_load_dwordx4 v[116:119], v172, s[34:35] nt
	global_load_dwordx4 v[120:123], v205, s[34:35] nt
	global_load_dwordx4 v[128:131], v213, s[34:35] nt
	global_load_dwordx4 v[136:139], v215, s[34:35] nt
	global_load_dwordx4 v[148:151], v238, s[34:35] nt
	global_load_dwordx4 v[152:155], v239, s[34:35] nt
	global_load_dwordx4 v[156:159], v240, s[34:35] nt
	global_load_dwordx4 v[160:163], v244, s[34:35] nt
	s_addc_u32 s51, s11, s51
	global_load_dwordx4 v[164:167], v209, s[50:51] nt
	global_load_dwordx4 v[168:171], v219, s[50:51] nt
	s_lshl_b64 s[22:23], s[22:23], 7
	s_or_b32 s22, s22, 64
	s_lshl_b64 s[50:51], s[22:23], 10
	s_add_u32 s50, s8, s50
	s_addc_u32 s51, s9, s51
	s_lshl_b64 s[22:23], s[22:23], 7
	v_readlane_b32 s34, v233, 1
	s_add_u32 s22, s10, s22
	s_addc_u32 s23, s11, s23
	s_ashr_i32 s35, s34, 31
	global_load_dwordx4 v[64:67], v89, s[50:51] nt
	global_load_dwordx4 v[60:63], v91, s[50:51] nt
	global_load_dwordx4 v[56:59], v105, s[50:51] nt
	global_load_dwordx4 v[52:55], v107, s[50:51] nt
	global_load_dwordx4 v[48:51], v172, s[50:51] nt
	global_load_dwordx4 v[44:47], v205, s[50:51] nt
	global_load_dwordx4 v[40:43], v207, s[50:51] nt
	global_load_dwordx4 v[36:39], v213, s[50:51] nt
	global_load_dwordx4 v[32:35], v215, s[50:51] nt
	global_load_dwordx4 v[28:31], v237, s[50:51] nt
	global_load_dwordx4 v[24:27], v238, s[50:51] nt
	global_load_dwordx4 v[20:23], v239, s[50:51] nt
	global_load_dwordx4 v[16:19], v240, s[50:51] nt
	global_load_dwordx4 v[8:11], v244, s[50:51] nt
	global_load_dwordx4 v[72:75], v209, s[50:51] nt
	global_load_dwordx4 v[68:71], v219, s[50:51] nt
	global_load_dwordx4 v[12:15], v209, s[22:23] nt
	global_load_dwordx4 v[4:7], v219, s[22:23] nt
	s_lshl_b64 s[22:23], s[34:35], 17
	s_add_u32 s22, s8, s22
	s_addc_u32 s23, s9, s23
	s_lshl_b64 s[50:51], s[34:35], 14
	s_add_u32 s50, s10, s50
	s_addc_u32 s51, s11, s51
	s_lshl_b64 s[52:53], s[34:35], 7
	s_or_b32 s52, s52, 64
	global_load_dwordx4 v[144:147], v209, s[22:23] nt
	global_load_dwordx4 v[132:135], v219, s[22:23] nt
	global_load_dwordx4 v[80:83], v209, s[50:51] nt
	global_load_dwordx4 v[76:79], v219, s[50:51] nt
	s_lshl_b64 s[34:35], s[52:53], 10
	s_add_u32 s34, s8, s34
	s_addc_u32 s35, s9, s35
	s_lshl_b64 s[50:51], s[52:53], 7
	s_add_u32 s50, s10, s50
	s_addc_u32 s51, s11, s51
	s_waitcnt vmcnt(39)
	v_cvt_pk_bf16_f32 v84, v84, v85
	v_cvt_pk_bf16_f32 v85, v86, v87
	s_waitcnt vmcnt(37)
	v_cvt_pk_bf16_f32 v86, v92, v93
	v_cvt_pk_bf16_f32 v87, v94, v95
	s_waitcnt vmcnt(35)
	v_cvt_pk_bf16_f32 v92, v96, v97
	v_cvt_pk_bf16_f32 v93, v98, v99
	s_waitcnt vmcnt(34)
	v_cvt_pk_bf16_f32 v94, v100, v101
	v_cvt_pk_bf16_f32 v95, v102, v103
	s_waitcnt vmcnt(33)
	v_cvt_pk_bf16_f32 v96, v108, v109
	v_cvt_pk_bf16_f32 v97, v110, v111
	s_waitcnt vmcnt(32)
	v_cvt_pk_bf16_f32 v98, v112, v113
	v_cvt_pk_bf16_f32 v99, v114, v115
	s_waitcnt vmcnt(31)
	v_cvt_pk_bf16_f32 v100, v116, v117
	v_cvt_pk_bf16_f32 v101, v118, v119
	s_waitcnt vmcnt(30)
	v_cvt_pk_bf16_f32 v102, v120, v121
	v_cvt_pk_bf16_f32 v103, v122, v123
	v_cvt_pk_bf16_f32 v108, v124, v125
	v_cvt_pk_bf16_f32 v109, v126, v127
	s_waitcnt vmcnt(29)
	v_cvt_pk_bf16_f32 v110, v128, v129
	v_cvt_pk_bf16_f32 v111, v130, v131
	s_waitcnt vmcnt(28)
	v_cvt_pk_bf16_f32 v112, v136, v137
	v_cvt_pk_bf16_f32 v113, v138, v139
	v_cvt_pk_bf16_f32 v114, v140, v141
	v_cvt_pk_bf16_f32 v115, v142, v143
	s_waitcnt vmcnt(27)
	v_cvt_pk_bf16_f32 v116, v148, v149
	v_cvt_pk_bf16_f32 v117, v150, v151
	s_waitcnt vmcnt(26)
	v_cvt_pk_bf16_f32 v118, v152, v153
	v_cvt_pk_bf16_f32 v119, v154, v155
	s_waitcnt vmcnt(25)
	v_cvt_pk_bf16_f32 v120, v156, v157
	v_cvt_pk_bf16_f32 v121, v158, v159
	s_waitcnt vmcnt(24)
	v_cvt_pk_bf16_f32 v122, v160, v161
	v_cvt_pk_bf16_f32 v123, v162, v163
	ds_write_b64 v236, v[84:85]
	ds_write_b64 v173, v[86:87]
	ds_write_b64 v236, v[92:93] offset:4736
	ds_write_b64 v236, v[94:95] offset:7104
	ds_write_b64 v236, v[96:97] offset:9472
	ds_write_b64 v236, v[98:99] offset:11840
	ds_write_b64 v236, v[100:101] offset:14208
	ds_write_b64 v236, v[102:103] offset:16576
	ds_write_b64 v236, v[108:109] offset:18944
	ds_write_b64 v236, v[110:111] offset:21312
	ds_write_b64 v236, v[112:113] offset:23680
	ds_write_b64 v236, v[114:115] offset:26048
	ds_write_b64 v236, v[116:117] offset:28416
	ds_write_b64 v236, v[118:119] offset:30784
	ds_write_b64 v236, v[120:121] offset:33152
	ds_write_b64 v236, v[122:123] offset:35520
	s_waitcnt vmcnt(23)
	v_cvt_pk_bf16_f32 v84, v164, v165
	v_cvt_pk_bf16_f32 v85, v166, v167
	s_waitcnt vmcnt(22)
	v_cvt_pk_bf16_f32 v86, v168, v169
	v_cvt_pk_bf16_f32 v87, v170, v171
	ds_write_b64 v235, v[84:85] offset:512
	ds_write_b64 v234, v[86:87] offset:512
	global_load_dwordx4 v[188:191], v89, s[22:23] nt
	global_load_dwordx4 v[200:203], v89, s[34:35] nt
	global_load_dwordx4 v[184:187], v91, s[22:23] nt
	global_load_dwordx4 v[196:199], v91, s[34:35] nt
	global_load_dwordx4 v[176:179], v105, s[22:23] nt
	global_load_dwordx4 v[192:195], v105, s[34:35] nt
	global_load_dwordx4 v[168:171], v107, s[22:23] nt
	global_load_dwordx4 v[180:183], v107, s[34:35] nt
	global_load_dwordx4 v[160:163], v172, s[22:23] nt
	s_nop 0
	global_load_dwordx4 v[172:175], v172, s[34:35] nt
	s_nop 0
	global_load_dwordx4 v[152:155], v205, s[22:23] nt
	global_load_dwordx4 v[164:167], v205, s[34:35] nt
	global_load_dwordx4 v[140:143], v207, s[22:23] nt
	global_load_dwordx4 v[156:159], v207, s[34:35] nt
	global_load_dwordx4 v[128:131], v213, s[22:23] nt
	global_load_dwordx4 v[148:151], v213, s[34:35] nt
	global_load_dwordx4 v[120:123], v215, s[22:23] nt
	global_load_dwordx4 v[136:139], v215, s[34:35] nt
	global_load_dwordx4 v[112:115], v237, s[22:23] nt
	global_load_dwordx4 v[124:127], v237, s[34:35] nt
	global_load_dwordx4 v[100:103], v238, s[22:23] nt
	global_load_dwordx4 v[116:119], v238, s[34:35] nt
	global_load_dwordx4 v[92:95], v239, s[22:23] nt
	global_load_dwordx4 v[108:111], v239, s[34:35] nt
	global_load_dwordx4 v[84:87], v240, s[22:23] nt
	global_load_dwordx4 v[96:99], v240, s[34:35] nt
	global_load_dwordx4 v[204:207], v209, s[34:35] nt
	global_load_dwordx4 v[212:215], v209, s[50:51] nt
	v_mul_u32_u24_e32 v209, 0x250, v217
	v_lshlrev_b32_e32 v239, 2, v90
	v_lshlrev_b32_e32 v240, 2, v88
	global_load_dwordx4 v[88:91], v244, s[22:23] nt
	global_load_dwordx4 v[104:107], v244, s[34:35] nt
	v_lshlrev_b32_e32 v244, 2, v224
	v_add_u32_e32 v222, v254, v209
	v_add_u32_e32 v238, v254, v216
	v_add_u32_e32 v237, v254, v210
	v_add_u32_e32 v224, v254, v211
	global_load_dwordx4 v[208:211], v219, s[34:35] nt
	s_nop 0
	global_load_dwordx4 v[216:219], v219, s[50:51] nt
	s_waitcnt lgkmcnt(0)
	s_barrier
	s_mov_b32 s22, 4
	s_mov_b32 s23, -6
.LBB0_830:
	s_add_i32 s34, s22, -2
	v_readlane_b32 s50, v233, s34
	s_ashr_i32 s51, s50, 31
	s_waitcnt vmcnt(39)
	v_cvt_pk_bf16_f32 v72, v72, v73
	v_cvt_pk_bf16_f32 v73, v74, v75
	s_waitcnt vmcnt(38)
	v_cvt_pk_bf16_f32 v68, v68, v69
	v_cvt_pk_bf16_f32 v69, v70, v71
	v_cvt_pk_bf16_f32 v8, v8, v9
	v_cvt_pk_bf16_f32 v9, v10, v11
	s_lshl_b64 s[34:35], s[50:51], 17
	ds_write_b64 v236, v[72:73] offset:37888
	ds_write_b64 v222, v[68:69] offset:37888
	v_cvt_pk_bf16_f32 v64, v64, v65
	v_cvt_pk_bf16_f32 v65, v66, v67
	v_cvt_pk_bf16_f32 v60, v60, v61
	v_cvt_pk_bf16_f32 v61, v62, v63
	v_cvt_pk_bf16_f32 v56, v56, v57
	v_cvt_pk_bf16_f32 v57, v58, v59
	v_cvt_pk_bf16_f32 v52, v52, v53
	v_cvt_pk_bf16_f32 v53, v54, v55
	v_cvt_pk_bf16_f32 v48, v48, v49
	v_cvt_pk_bf16_f32 v49, v50, v51
	v_cvt_pk_bf16_f32 v44, v44, v45
	v_cvt_pk_bf16_f32 v45, v46, v47
	v_cvt_pk_bf16_f32 v40, v40, v41
	v_cvt_pk_bf16_f32 v41, v42, v43
	v_cvt_pk_bf16_f32 v36, v36, v37
	v_cvt_pk_bf16_f32 v37, v38, v39
	v_cvt_pk_bf16_f32 v32, v32, v33
	v_cvt_pk_bf16_f32 v33, v34, v35
	v_cvt_pk_bf16_f32 v28, v28, v29
	v_cvt_pk_bf16_f32 v29, v30, v31
	v_cvt_pk_bf16_f32 v24, v24, v25
	v_cvt_pk_bf16_f32 v25, v26, v27
	v_cvt_pk_bf16_f32 v20, v20, v21
	v_cvt_pk_bf16_f32 v21, v22, v23
	v_cvt_pk_bf16_f32 v16, v16, v17
	v_cvt_pk_bf16_f32 v17, v18, v19
	ds_write_b64 v224, v[8:9] offset:37888
	s_waitcnt vmcnt(37)
	v_cvt_pk_bf16_f32 v8, v12, v13
	v_cvt_pk_bf16_f32 v9, v14, v15
	s_waitcnt vmcnt(36)
	v_cvt_pk_bf16_f32 v4, v4, v5
	v_cvt_pk_bf16_f32 v5, v6, v7
	s_add_u32 s34, s8, s34
	ds_write_b64 v236, v[64:65] offset:42624
	ds_write_b64 v236, v[60:61] offset:44992
	ds_write_b64 v236, v[56:57] offset:47360
	ds_write_b64 v236, v[52:53] offset:49728
	ds_write_b64 v236, v[48:49] offset:52096
	ds_write_b64 v236, v[44:45] offset:54464
	ds_write_b64 v236, v[40:41] offset:56832
	ds_write_b64 v236, v[36:37] offset:59200
	ds_write_b64 v236, v[32:33] offset:61568
	ds_write_b64 v236, v[28:29] offset:63936
	ds_write_b64 v238, v[24:25] offset:37888
	ds_write_b64 v237, v[20:21] offset:37888
	ds_write_b64 v226, v[16:17] offset:37888
	ds_write_b64 v235, v[8:9] offset:38400
	ds_write_b64 v234, v[4:5] offset:38400
	s_addc_u32 s35, s9, s35
	s_lshl_b64 s[52:53], s[50:51], 14
	v_lshlrev_b32_e32 v254, 2, v2
	global_load_dwordx4 v[72:75], v254, s[34:35] nt
	global_load_dwordx4 v[68:71], v239, s[34:35] nt
	global_load_dwordx4 v[64:67], v240, s[34:35] nt
	global_load_dwordx4 v[60:63], v241, s[34:35] nt
	global_load_dwordx4 v[56:59], v242, s[34:35] nt
	global_load_dwordx4 v[52:55], v243, s[34:35] nt
	global_load_dwordx4 v[48:51], v244, s[34:35] nt
	global_load_dwordx4 v[44:47], v245, s[34:35] nt
	global_load_dwordx4 v[40:43], v246, s[34:35] nt
	global_load_dwordx4 v[36:39], v247, s[34:35] nt
	global_load_dwordx4 v[32:35], v248, s[34:35] nt
	global_load_dwordx4 v[28:31], v249, s[34:35] nt
	global_load_dwordx4 v[24:27], v250, s[34:35] nt
	global_load_dwordx4 v[20:23], v251, s[34:35] nt
	global_load_dwordx4 v[16:19], v252, s[34:35] nt
	global_load_dwordx4 v[8:11], v253, s[34:35] nt
	s_add_u32 s34, s10, s52
	s_addc_u32 s35, s11, s53
	s_waitcnt vmcnt(51)
	v_cvt_pk_bf16_f32 v144, v144, v145
	v_cvt_pk_bf16_f32 v145, v146, v147
	s_waitcnt vmcnt(50)
	v_cvt_pk_bf16_f32 v132, v132, v133
	v_cvt_pk_bf16_f32 v133, v134, v135
	global_load_dwordx4 v[12:15], v254, s[34:35] nt
	global_load_dwordx4 v[4:7], v239, s[34:35] nt
	s_waitcnt lgkmcnt(0)
	s_barrier
	ds_write_b64 v236, v[144:145]
	ds_write_b64 v222, v[132:133]
	s_waitcnt vmcnt(49)
	v_cvt_pk_bf16_f32 v132, v188, v189
	v_cvt_pk_bf16_f32 v133, v190, v191
	ds_write_b64 v236, v[132:133] offset:4736
	s_waitcnt vmcnt(47)
	v_cvt_pk_bf16_f32 v132, v184, v185
	v_cvt_pk_bf16_f32 v133, v186, v187
	s_lshl_b64 s[34:35], s[50:51], 7
	ds_write_b64 v236, v[132:133] offset:7104
	s_waitcnt vmcnt(45)
	v_cvt_pk_bf16_f32 v132, v176, v177
	v_cvt_pk_bf16_f32 v133, v178, v179
	s_or_b32 s34, s34, 64
	ds_write_b64 v236, v[132:133] offset:9472
	s_waitcnt vmcnt(43)
	v_cvt_pk_bf16_f32 v132, v168, v169
	v_cvt_pk_bf16_f32 v133, v170, v171
	s_lshl_b64 s[50:51], s[34:35], 10
	ds_write_b64 v236, v[132:133] offset:11840
	s_waitcnt vmcnt(41)
	v_cvt_pk_bf16_f32 v132, v160, v161
	v_cvt_pk_bf16_f32 v133, v162, v163
	s_add_u32 s50, s8, s50
	ds_write_b64 v236, v[132:133] offset:14208
	s_waitcnt vmcnt(39)
	v_cvt_pk_bf16_f32 v132, v152, v153
	v_cvt_pk_bf16_f32 v133, v154, v155
	s_waitcnt vmcnt(25)
	v_cvt_pk_bf16_f32 v84, v84, v85
	v_cvt_pk_bf16_f32 v85, v86, v87
	s_addc_u32 s51, s9, s51
	s_lshl_b64 s[34:35], s[34:35], 7
	ds_write_b64 v236, v[132:133] offset:16576
	v_cvt_pk_bf16_f32 v132, v140, v141
	v_cvt_pk_bf16_f32 v133, v142, v143
	v_cvt_pk_bf16_f32 v128, v128, v129
	v_cvt_pk_bf16_f32 v129, v130, v131
	v_cvt_pk_bf16_f32 v120, v120, v121
	v_cvt_pk_bf16_f32 v121, v122, v123
	v_cvt_pk_bf16_f32 v112, v112, v113
	v_cvt_pk_bf16_f32 v113, v114, v115
	v_cvt_pk_bf16_f32 v100, v100, v101
	v_cvt_pk_bf16_f32 v101, v102, v103
	v_cvt_pk_bf16_f32 v92, v92, v93
	v_cvt_pk_bf16_f32 v93, v94, v95
	ds_write_b64 v236, v[84:85] offset:33152
	s_waitcnt vmcnt(21)
	v_cvt_pk_bf16_f32 v84, v88, v89
	v_cvt_pk_bf16_f32 v85, v90, v91
	v_cvt_pk_bf16_f32 v80, v80, v81
	v_cvt_pk_bf16_f32 v81, v82, v83
	v_cvt_pk_bf16_f32 v76, v76, v77
	v_cvt_pk_bf16_f32 v77, v78, v79
	s_add_u32 s34, s10, s34
	ds_write_b64 v236, v[132:133] offset:18944
	ds_write_b64 v236, v[128:129] offset:21312
	ds_write_b64 v236, v[120:121] offset:23680
	ds_write_b64 v236, v[112:113] offset:26048
	ds_write_b64 v236, v[100:101] offset:28416
	ds_write_b64 v236, v[92:93] offset:30784
	ds_write_b64 v236, v[84:85] offset:35520
	ds_write_b64 v235, v[80:81] offset:512
	ds_write_b64 v234, v[76:77] offset:512
	s_addc_u32 s35, s11, s35
	global_load_dwordx4 v[188:191], v254, s[50:51] nt
	global_load_dwordx4 v[184:187], v239, s[50:51] nt
	global_load_dwordx4 v[176:179], v240, s[50:51] nt
	global_load_dwordx4 v[168:171], v241, s[50:51] nt
	global_load_dwordx4 v[160:163], v242, s[50:51] nt
	global_load_dwordx4 v[152:155], v243, s[50:51] nt
	global_load_dwordx4 v[144:147], v244, s[50:51] nt
	global_load_dwordx4 v[140:143], v245, s[50:51] nt
	global_load_dwordx4 v[132:135], v246, s[50:51] nt
	global_load_dwordx4 v[128:131], v247, s[50:51] nt
	global_load_dwordx4 v[120:123], v248, s[50:51] nt
	global_load_dwordx4 v[112:115], v249, s[50:51] nt
	global_load_dwordx4 v[100:103], v250, s[50:51] nt
	global_load_dwordx4 v[92:95], v251, s[50:51] nt
	global_load_dwordx4 v[88:91], v252, s[50:51] nt
	global_load_dwordx4 v[80:83], v253, s[50:51] nt
	global_load_dwordx4 v[84:87], v254, s[34:35] nt
	global_load_dwordx4 v[76:79], v239, s[34:35] nt
	s_add_i32 s34, s22, -1
	v_cvt_pk_bf16_f32 v204, v204, v205
	v_cvt_pk_bf16_f32 v205, v206, v207
	v_readlane_b32 s34, v233, s34
	s_waitcnt lgkmcnt(0)
	s_barrier
	ds_write_b64 v236, v[204:205] offset:37888
	s_waitcnt vmcnt(37)
	v_cvt_pk_bf16_f32 v204, v208, v209
	v_cvt_pk_bf16_f32 v205, v210, v211
	v_cvt_pk_bf16_f32 v96, v96, v97
	v_cvt_pk_bf16_f32 v97, v98, v99
	s_ashr_i32 s35, s34, 31
	ds_write_b64 v222, v[204:205] offset:37888
	ds_write_b64 v226, v[96:97] offset:37888
	v_cvt_pk_bf16_f32 v96, v104, v105
	v_cvt_pk_bf16_f32 v97, v106, v107
	s_lshl_b64 s[50:51], s[34:35], 14
	s_lshl_b64 s[52:53], s[34:35], 17
	v_cvt_pk_bf16_f32 v200, v200, v201
	v_cvt_pk_bf16_f32 v201, v202, v203
	v_cvt_pk_bf16_f32 v196, v196, v197
	v_cvt_pk_bf16_f32 v197, v198, v199
	v_cvt_pk_bf16_f32 v192, v192, v193
	v_cvt_pk_bf16_f32 v193, v194, v195
	v_cvt_pk_bf16_f32 v180, v180, v181
	v_cvt_pk_bf16_f32 v181, v182, v183
	v_cvt_pk_bf16_f32 v172, v172, v173
	v_cvt_pk_bf16_f32 v173, v174, v175
	v_cvt_pk_bf16_f32 v164, v164, v165
	v_cvt_pk_bf16_f32 v165, v166, v167
	v_cvt_pk_bf16_f32 v156, v156, v157
	v_cvt_pk_bf16_f32 v157, v158, v159
	v_cvt_pk_bf16_f32 v148, v148, v149
	v_cvt_pk_bf16_f32 v149, v150, v151
	v_cvt_pk_bf16_f32 v136, v136, v137
	v_cvt_pk_bf16_f32 v137, v138, v139
	v_cvt_pk_bf16_f32 v124, v124, v125
	v_cvt_pk_bf16_f32 v125, v126, v127
	v_cvt_pk_bf16_f32 v116, v116, v117
	v_cvt_pk_bf16_f32 v117, v118, v119
	v_cvt_pk_bf16_f32 v108, v108, v109
	v_cvt_pk_bf16_f32 v109, v110, v111
	ds_write_b64 v224, v[96:97] offset:37888
	v_cvt_pk_bf16_f32 v96, v212, v213
	v_cvt_pk_bf16_f32 v97, v214, v215
	s_add_u32 s52, s8, s52
	ds_write_b64 v236, v[200:201] offset:42624
	ds_write_b64 v236, v[196:197] offset:44992
	ds_write_b64 v236, v[192:193] offset:47360
	ds_write_b64 v236, v[180:181] offset:49728
	ds_write_b64 v236, v[172:173] offset:52096
	ds_write_b64 v236, v[164:165] offset:54464
	ds_write_b64 v236, v[156:157] offset:56832
	ds_write_b64 v236, v[148:149] offset:59200
	ds_write_b64 v236, v[136:137] offset:61568
	ds_write_b64 v236, v[124:125] offset:63936
	ds_write_b64 v238, v[116:117] offset:37888
	ds_write_b64 v237, v[108:109] offset:37888
	ds_write_b64 v235, v[96:97] offset:38400
	s_waitcnt vmcnt(36)
	v_cvt_pk_bf16_f32 v96, v216, v217
	v_cvt_pk_bf16_f32 v97, v218, v219
	s_addc_u32 s53, s9, s53
	ds_write_b64 v234, v[96:97] offset:38400
	s_add_u32 s50, s10, s50
	global_load_dwordx4 v[216:219], v254, s[52:53] nt
	global_load_dwordx4 v[212:215], v239, s[52:53] nt
	global_load_dwordx4 v[208:211], v240, s[52:53] nt
	global_load_dwordx4 v[204:207], v241, s[52:53] nt
	global_load_dwordx4 v[200:203], v242, s[52:53] nt
	global_load_dwordx4 v[196:199], v243, s[52:53] nt
	global_load_dwordx4 v[192:195], v244, s[52:53] nt
	global_load_dwordx4 v[180:183], v245, s[52:53] nt
	global_load_dwordx4 v[172:175], v246, s[52:53] nt
	global_load_dwordx4 v[164:167], v247, s[52:53] nt
	global_load_dwordx4 v[156:159], v248, s[52:53] nt
	global_load_dwordx4 v[148:151], v249, s[52:53] nt
	global_load_dwordx4 v[136:139], v250, s[52:53] nt
	global_load_dwordx4 v[124:127], v251, s[52:53] nt
	global_load_dwordx4 v[116:119], v252, s[52:53] nt
	global_load_dwordx4 v[104:107], v253, s[52:53] nt
	s_addc_u32 s51, s11, s51
	global_load_dwordx4 v[108:111], v254, s[50:51] nt
	global_load_dwordx4 v[96:99], v239, s[50:51] nt
	s_lshl_b64 s[34:35], s[34:35], 7
	s_or_b32 s34, s34, 64
	s_waitcnt vmcnt(53)
	v_cvt_pk_bf16_f32 v72, v72, v73
	v_cvt_pk_bf16_f32 v73, v74, v75
	s_waitcnt vmcnt(52)
	v_cvt_pk_bf16_f32 v68, v68, v69
	v_cvt_pk_bf16_f32 v69, v70, v71
	s_waitcnt vmcnt(38)
	v_cvt_pk_bf16_f32 v8, v8, v9
	v_cvt_pk_bf16_f32 v9, v10, v11
	s_lshl_b64 s[50:51], s[34:35], 10
	s_waitcnt lgkmcnt(0)
	s_barrier
	ds_write_b64 v236, v[72:73]
	ds_write_b64 v222, v[68:69]
	v_cvt_pk_bf16_f32 v64, v64, v65
	v_cvt_pk_bf16_f32 v65, v66, v67
	v_cvt_pk_bf16_f32 v60, v60, v61
	v_cvt_pk_bf16_f32 v61, v62, v63
	v_cvt_pk_bf16_f32 v56, v56, v57
	v_cvt_pk_bf16_f32 v57, v58, v59
	v_cvt_pk_bf16_f32 v52, v52, v53
	v_cvt_pk_bf16_f32 v53, v54, v55
	v_cvt_pk_bf16_f32 v48, v48, v49
	v_cvt_pk_bf16_f32 v49, v50, v51
	v_cvt_pk_bf16_f32 v44, v44, v45
	v_cvt_pk_bf16_f32 v45, v46, v47
	v_cvt_pk_bf16_f32 v40, v40, v41
	v_cvt_pk_bf16_f32 v41, v42, v43
	v_cvt_pk_bf16_f32 v36, v36, v37
	v_cvt_pk_bf16_f32 v37, v38, v39
	v_cvt_pk_bf16_f32 v32, v32, v33
	v_cvt_pk_bf16_f32 v33, v34, v35
	v_cvt_pk_bf16_f32 v28, v28, v29
	v_cvt_pk_bf16_f32 v29, v30, v31
	v_cvt_pk_bf16_f32 v24, v24, v25
	v_cvt_pk_bf16_f32 v25, v26, v27
	v_cvt_pk_bf16_f32 v20, v20, v21
	v_cvt_pk_bf16_f32 v21, v22, v23
	v_cvt_pk_bf16_f32 v16, v16, v17
	v_cvt_pk_bf16_f32 v17, v18, v19
	ds_write_b64 v236, v[8:9] offset:35520
	s_waitcnt vmcnt(37)
	v_cvt_pk_bf16_f32 v8, v12, v13
	v_cvt_pk_bf16_f32 v9, v14, v15
	s_waitcnt vmcnt(36)
	v_cvt_pk_bf16_f32 v4, v4, v5
	v_cvt_pk_bf16_f32 v5, v6, v7
	s_add_u32 s50, s8, s50
	ds_write_b64 v236, v[64:65] offset:4736
	ds_write_b64 v236, v[60:61] offset:7104
	ds_write_b64 v236, v[56:57] offset:9472
	ds_write_b64 v236, v[52:53] offset:11840
	ds_write_b64 v236, v[48:49] offset:14208
	ds_write_b64 v236, v[44:45] offset:16576
	ds_write_b64 v236, v[40:41] offset:18944
	ds_write_b64 v236, v[36:37] offset:21312
	ds_write_b64 v236, v[32:33] offset:23680
	ds_write_b64 v236, v[28:29] offset:26048
	ds_write_b64 v236, v[24:25] offset:28416
	ds_write_b64 v236, v[20:21] offset:30784
	ds_write_b64 v236, v[16:17] offset:33152
	ds_write_b64 v235, v[8:9] offset:512
	ds_write_b64 v234, v[4:5] offset:512
	s_addc_u32 s51, s9, s51
	s_lshl_b64 s[34:35], s[34:35], 7
	global_load_dwordx4 v[72:75], v254, s[50:51] nt
	global_load_dwordx4 v[68:71], v239, s[50:51] nt
	global_load_dwordx4 v[64:67], v240, s[50:51] nt
	global_load_dwordx4 v[60:63], v241, s[50:51] nt
	global_load_dwordx4 v[56:59], v242, s[50:51] nt
	global_load_dwordx4 v[52:55], v243, s[50:51] nt
	global_load_dwordx4 v[48:51], v244, s[50:51] nt
	global_load_dwordx4 v[44:47], v245, s[50:51] nt
	global_load_dwordx4 v[40:43], v246, s[50:51] nt
	global_load_dwordx4 v[36:39], v247, s[50:51] nt
	global_load_dwordx4 v[32:35], v248, s[50:51] nt
	global_load_dwordx4 v[28:31], v249, s[50:51] nt
	global_load_dwordx4 v[24:27], v250, s[50:51] nt
	global_load_dwordx4 v[20:23], v251, s[50:51] nt
	global_load_dwordx4 v[16:19], v252, s[50:51] nt
	global_load_dwordx4 v[8:11], v253, s[50:51] nt
	s_add_u32 s34, s10, s34
	v_readlane_b32 s50, v233, s22
	s_addc_u32 s35, s11, s35
	s_ashr_i32 s51, s50, 31
	global_load_dwordx4 v[12:15], v254, s[34:35] nt
	global_load_dwordx4 v[4:7], v239, s[34:35] nt
	s_lshl_b64 s[34:35], s[50:51], 14
	s_lshl_b64 s[52:53], s[50:51], 17
	s_add_u32 s52, s8, s52
	s_waitcnt vmcnt(53)
	v_cvt_pk_bf16_f32 v188, v188, v189
	v_cvt_pk_bf16_f32 v189, v190, v191
	s_waitcnt vmcnt(52)
	v_cvt_pk_bf16_f32 v184, v184, v185
	v_cvt_pk_bf16_f32 v185, v186, v187
	s_waitcnt vmcnt(38)
	v_cvt_pk_bf16_f32 v80, v80, v81
	v_cvt_pk_bf16_f32 v81, v82, v83
	s_addc_u32 s53, s9, s53
	s_waitcnt lgkmcnt(0)
	s_barrier
	ds_write_b64 v236, v[188:189] offset:37888
	ds_write_b64 v222, v[184:185] offset:37888
	v_cvt_pk_bf16_f32 v176, v176, v177
	v_cvt_pk_bf16_f32 v177, v178, v179
	v_cvt_pk_bf16_f32 v168, v168, v169
	v_cvt_pk_bf16_f32 v169, v170, v171
	v_cvt_pk_bf16_f32 v160, v160, v161
	v_cvt_pk_bf16_f32 v161, v162, v163
	v_cvt_pk_bf16_f32 v152, v152, v153
	v_cvt_pk_bf16_f32 v153, v154, v155
	v_cvt_pk_bf16_f32 v144, v144, v145
	v_cvt_pk_bf16_f32 v145, v146, v147
	v_cvt_pk_bf16_f32 v140, v140, v141
	v_cvt_pk_bf16_f32 v141, v142, v143
	v_cvt_pk_bf16_f32 v132, v132, v133
	v_cvt_pk_bf16_f32 v133, v134, v135
	v_cvt_pk_bf16_f32 v128, v128, v129
	v_cvt_pk_bf16_f32 v129, v130, v131
	v_cvt_pk_bf16_f32 v120, v120, v121
	v_cvt_pk_bf16_f32 v121, v122, v123
	v_cvt_pk_bf16_f32 v112, v112, v113
	v_cvt_pk_bf16_f32 v113, v114, v115
	v_cvt_pk_bf16_f32 v100, v100, v101
	v_cvt_pk_bf16_f32 v101, v102, v103
	v_cvt_pk_bf16_f32 v92, v92, v93
	v_cvt_pk_bf16_f32 v93, v94, v95
	v_cvt_pk_bf16_f32 v88, v88, v89
	v_cvt_pk_bf16_f32 v89, v90, v91
	ds_write_b64 v224, v[80:81] offset:37888
	s_waitcnt vmcnt(37)
	v_cvt_pk_bf16_f32 v80, v84, v85
	v_cvt_pk_bf16_f32 v81, v86, v87
	s_waitcnt vmcnt(36)
	v_cvt_pk_bf16_f32 v76, v76, v77
	v_cvt_pk_bf16_f32 v77, v78, v79
	s_add_u32 s34, s10, s34
	ds_write_b64 v236, v[176:177] offset:42624
	ds_write_b64 v236, v[168:169] offset:44992
	ds_write_b64 v236, v[160:161] offset:47360
	ds_write_b64 v236, v[152:153] offset:49728
	ds_write_b64 v236, v[144:145] offset:52096
	ds_write_b64 v236, v[140:141] offset:54464
	ds_write_b64 v236, v[132:133] offset:56832
	ds_write_b64 v236, v[128:129] offset:59200
	ds_write_b64 v236, v[120:121] offset:61568
	ds_write_b64 v236, v[112:113] offset:63936
	ds_write_b64 v238, v[100:101] offset:37888
	ds_write_b64 v237, v[92:93] offset:37888
	ds_write_b64 v226, v[88:89] offset:37888
	ds_write_b64 v235, v[80:81] offset:38400
	ds_write_b64 v234, v[76:77] offset:38400
	s_addc_u32 s35, s11, s35
	global_load_dwordx4 v[144:147], v254, s[52:53] nt
	global_load_dwordx4 v[132:135], v239, s[52:53] nt
	global_load_dwordx4 v[188:191], v240, s[52:53] nt
	global_load_dwordx4 v[184:187], v241, s[52:53] nt
	global_load_dwordx4 v[176:179], v242, s[52:53] nt
	global_load_dwordx4 v[168:171], v243, s[52:53] nt
	global_load_dwordx4 v[160:163], v244, s[52:53] nt
	global_load_dwordx4 v[152:155], v245, s[52:53] nt
	global_load_dwordx4 v[140:143], v246, s[52:53] nt
	global_load_dwordx4 v[128:131], v247, s[52:53] nt
	global_load_dwordx4 v[120:123], v248, s[52:53] nt
	global_load_dwordx4 v[112:115], v249, s[52:53] nt
	global_load_dwordx4 v[100:103], v250, s[52:53] nt
	global_load_dwordx4 v[92:95], v251, s[52:53] nt
	global_load_dwordx4 v[84:87], v252, s[52:53] nt
	global_load_dwordx4 v[88:91], v253, s[52:53] nt
	global_load_dwordx4 v[80:83], v254, s[34:35] nt
	global_load_dwordx4 v[76:79], v239, s[34:35] nt
	s_lshl_b64 s[34:35], s[50:51], 7
	s_or_b32 s34, s34, 64
	s_waitcnt vmcnt(53)
	v_cvt_pk_bf16_f32 v216, v216, v217
	v_cvt_pk_bf16_f32 v217, v218, v219
	s_waitcnt vmcnt(52)
	v_cvt_pk_bf16_f32 v212, v212, v213
	v_cvt_pk_bf16_f32 v213, v214, v215
	s_waitcnt vmcnt(38)
	v_cvt_pk_bf16_f32 v104, v104, v105
	v_cvt_pk_bf16_f32 v105, v106, v107
	s_lshl_b64 s[50:51], s[34:35], 10
	s_waitcnt lgkmcnt(0)
	s_barrier
	ds_write_b64 v236, v[216:217]
	ds_write_b64 v222, v[212:213]
	v_cvt_pk_bf16_f32 v208, v208, v209
	v_cvt_pk_bf16_f32 v209, v210, v211
	v_cvt_pk_bf16_f32 v204, v204, v205
	v_cvt_pk_bf16_f32 v205, v206, v207
	v_cvt_pk_bf16_f32 v200, v200, v201
	v_cvt_pk_bf16_f32 v201, v202, v203
	v_cvt_pk_bf16_f32 v196, v196, v197
	v_cvt_pk_bf16_f32 v197, v198, v199
	v_cvt_pk_bf16_f32 v192, v192, v193
	v_cvt_pk_bf16_f32 v193, v194, v195
	v_cvt_pk_bf16_f32 v180, v180, v181
	v_cvt_pk_bf16_f32 v181, v182, v183
	v_cvt_pk_bf16_f32 v172, v172, v173
	v_cvt_pk_bf16_f32 v173, v174, v175
	v_cvt_pk_bf16_f32 v164, v164, v165
	v_cvt_pk_bf16_f32 v165, v166, v167
	v_cvt_pk_bf16_f32 v156, v156, v157
	v_cvt_pk_bf16_f32 v157, v158, v159
	v_cvt_pk_bf16_f32 v148, v148, v149
	v_cvt_pk_bf16_f32 v149, v150, v151
	v_cvt_pk_bf16_f32 v136, v136, v137
	v_cvt_pk_bf16_f32 v137, v138, v139
	v_cvt_pk_bf16_f32 v124, v124, v125
	v_cvt_pk_bf16_f32 v125, v126, v127
	v_cvt_pk_bf16_f32 v116, v116, v117
	v_cvt_pk_bf16_f32 v117, v118, v119
	ds_write_b64 v236, v[104:105] offset:35520
	s_waitcnt vmcnt(37)
	v_cvt_pk_bf16_f32 v104, v108, v109
	v_cvt_pk_bf16_f32 v105, v110, v111
	s_waitcnt vmcnt(36)
	v_cvt_pk_bf16_f32 v96, v96, v97
	v_cvt_pk_bf16_f32 v97, v98, v99
	s_add_u32 s50, s8, s50
	ds_write_b64 v236, v[208:209] offset:4736
	ds_write_b64 v236, v[204:205] offset:7104
	ds_write_b64 v236, v[200:201] offset:9472
	ds_write_b64 v236, v[196:197] offset:11840
	ds_write_b64 v236, v[192:193] offset:14208
	ds_write_b64 v236, v[180:181] offset:16576
	ds_write_b64 v236, v[172:173] offset:18944
	ds_write_b64 v236, v[164:165] offset:21312
	ds_write_b64 v236, v[156:157] offset:23680
	ds_write_b64 v236, v[148:149] offset:26048
	ds_write_b64 v236, v[136:137] offset:28416
	ds_write_b64 v236, v[124:125] offset:30784
	ds_write_b64 v236, v[116:117] offset:33152
	ds_write_b64 v235, v[104:105] offset:512
	ds_write_b64 v234, v[96:97] offset:512
	s_addc_u32 s51, s9, s51
	global_load_dwordx4 v[204:207], v254, s[50:51] nt
	global_load_dwordx4 v[208:211], v239, s[50:51] nt
	global_load_dwordx4 v[200:203], v240, s[50:51] nt
	global_load_dwordx4 v[196:199], v241, s[50:51] nt
	global_load_dwordx4 v[192:195], v242, s[50:51] nt
	global_load_dwordx4 v[180:183], v243, s[50:51] nt
	global_load_dwordx4 v[172:175], v244, s[50:51] nt
	global_load_dwordx4 v[164:167], v245, s[50:51] nt
	global_load_dwordx4 v[156:159], v246, s[50:51] nt
	global_load_dwordx4 v[148:151], v247, s[50:51] nt
	global_load_dwordx4 v[136:139], v248, s[50:51] nt
	global_load_dwordx4 v[124:127], v249, s[50:51] nt
	global_load_dwordx4 v[116:119], v250, s[50:51] nt
	global_load_dwordx4 v[108:111], v251, s[50:51] nt
	global_load_dwordx4 v[96:99], v252, s[50:51] nt
	global_load_dwordx4 v[104:107], v253, s[50:51] nt
	s_lshl_b64 s[34:35], s[34:35], 7
	s_add_u32 s50, s10, s34
	s_addc_u32 s51, s11, s35
	global_load_dwordx4 v[212:215], v254, s[50:51] nt
	global_load_dwordx4 v[216:219], v239, s[50:51] nt
	s_waitcnt lgkmcnt(0)
	s_barrier
	s_add_i32 s23, s23, 6
	s_add_i32 s22, s22, 3
	s_cmp_gt_u32 s23, 53
	s_cbranch_scc0 .LBB0_830
	v_readlane_b32 s22, v233, 31
	s_ashr_i32 s23, s22, 31
	s_lshl_b64 s[22:23], s[22:23], 7
	s_or_b32 s22, s22, 64
	s_lshl_b64 s[34:35], s[22:23], 10
	s_waitcnt vmcnt(53)
	v_cvt_pk_bf16_f32 v72, v72, v73
	v_cvt_pk_bf16_f32 v73, v74, v75
	s_waitcnt vmcnt(52)
	v_cvt_pk_bf16_f32 v68, v68, v69
	v_cvt_pk_bf16_f32 v69, v70, v71
	s_waitcnt vmcnt(38)
	v_cvt_pk_bf16_f32 v8, v8, v9
	v_cvt_pk_bf16_f32 v9, v10, v11
	s_add_u32 s34, s8, s34
	ds_write_b64 v236, v[72:73] offset:37888
	ds_write_b64 v222, v[68:69] offset:37888
	v_cvt_pk_bf16_f32 v64, v64, v65
	v_cvt_pk_bf16_f32 v65, v66, v67
	v_cvt_pk_bf16_f32 v60, v60, v61
	v_cvt_pk_bf16_f32 v61, v62, v63
	v_cvt_pk_bf16_f32 v56, v56, v57
	v_cvt_pk_bf16_f32 v57, v58, v59
	v_cvt_pk_bf16_f32 v52, v52, v53
	v_cvt_pk_bf16_f32 v53, v54, v55
	v_cvt_pk_bf16_f32 v48, v48, v49
	v_cvt_pk_bf16_f32 v49, v50, v51
	v_cvt_pk_bf16_f32 v44, v44, v45
	v_cvt_pk_bf16_f32 v45, v46, v47
	v_cvt_pk_bf16_f32 v40, v40, v41
	v_cvt_pk_bf16_f32 v41, v42, v43
	v_cvt_pk_bf16_f32 v36, v36, v37
	v_cvt_pk_bf16_f32 v37, v38, v39
	v_cvt_pk_bf16_f32 v32, v32, v33
	v_cvt_pk_bf16_f32 v33, v34, v35
	v_cvt_pk_bf16_f32 v28, v28, v29
	v_cvt_pk_bf16_f32 v29, v30, v31
	v_cvt_pk_bf16_f32 v24, v24, v25
	v_cvt_pk_bf16_f32 v25, v26, v27
	v_cvt_pk_bf16_f32 v20, v20, v21
	v_cvt_pk_bf16_f32 v21, v22, v23
	v_cvt_pk_bf16_f32 v16, v16, v17
	v_cvt_pk_bf16_f32 v17, v18, v19
	ds_write_b64 v224, v[8:9] offset:37888
	s_waitcnt vmcnt(37)
	v_cvt_pk_bf16_f32 v8, v12, v13
	v_cvt_pk_bf16_f32 v9, v14, v15
	s_waitcnt vmcnt(36)
	v_cvt_pk_bf16_f32 v4, v4, v5
	v_cvt_pk_bf16_f32 v5, v6, v7
	s_addc_u32 s35, s9, s35
	s_lshl_b64 s[22:23], s[22:23], 7
	ds_write_b64 v236, v[64:65] offset:42624
	ds_write_b64 v236, v[60:61] offset:44992
	ds_write_b64 v236, v[56:57] offset:47360
	ds_write_b64 v236, v[52:53] offset:49728
	ds_write_b64 v236, v[48:49] offset:52096
	ds_write_b64 v236, v[44:45] offset:54464
	ds_write_b64 v236, v[40:41] offset:56832
	ds_write_b64 v236, v[36:37] offset:59200
	ds_write_b64 v236, v[32:33] offset:61568
	ds_write_b64 v236, v[28:29] offset:63936
	ds_write_b64 v238, v[24:25] offset:37888
	ds_write_b64 v237, v[20:21] offset:37888
	ds_write_b64 v226, v[16:17] offset:37888
	ds_write_b64 v235, v[8:9] offset:38400
	ds_write_b64 v234, v[4:5] offset:38400
	s_add_u32 s22, s10, s22
	global_load_dwordx4 v[36:39], v240, s[34:35] nt
	global_load_dwordx4 v[40:43], v241, s[34:35] nt
	global_load_dwordx4 v[44:47], v242, s[34:35] nt
	global_load_dwordx4 v[48:51], v243, s[34:35] nt
	global_load_dwordx4 v[52:55], v244, s[34:35] nt
	global_load_dwordx4 v[56:59], v245, s[34:35] nt
	global_load_dwordx4 v[60:63], v246, s[34:35] nt
	global_load_dwordx4 v[64:67], v247, s[34:35] nt
	global_load_dwordx4 v[32:35], v248, s[34:35] nt
	global_load_dwordx4 v[28:31], v249, s[34:35] nt
	global_load_dwordx4 v[24:27], v250, s[34:35] nt
	global_load_dwordx4 v[20:23], v251, s[34:35] nt
	global_load_dwordx4 v[16:19], v252, s[34:35] nt
	global_load_dwordx4 v[8:11], v253, s[34:35] nt
	s_addc_u32 s23, s11, s23
	global_load_dwordx4 v[68:71], v254, s[34:35] nt
	global_load_dwordx4 v[12:15], v254, s[22:23] nt
	global_load_dwordx4 v[72:75], v239, s[34:35] nt
	global_load_dwordx4 v[4:7], v239, s[22:23] nt
	s_waitcnt vmcnt(53)
	v_cvt_pk_bf16_f32 v144, v144, v145
	v_cvt_pk_bf16_f32 v145, v146, v147
	s_waitcnt vmcnt(52)
	v_cvt_pk_bf16_f32 v132, v132, v133
	v_cvt_pk_bf16_f32 v133, v134, v135
	s_waitcnt lgkmcnt(0)
	s_barrier
	ds_write_b64 v236, v[144:145]
	ds_write_b64 v222, v[132:133]
	s_waitcnt vmcnt(51)
	v_cvt_pk_bf16_f32 v132, v188, v189
	v_cvt_pk_bf16_f32 v133, v190, v191
	ds_write_b64 v236, v[132:133] offset:4736
	s_waitcnt vmcnt(50)
	v_cvt_pk_bf16_f32 v132, v184, v185
	v_cvt_pk_bf16_f32 v133, v186, v187
	ds_write_b64 v236, v[132:133] offset:7104
	s_waitcnt vmcnt(49)
	v_cvt_pk_bf16_f32 v132, v176, v177
	v_cvt_pk_bf16_f32 v133, v178, v179
	ds_write_b64 v236, v[132:133] offset:9472
	s_waitcnt vmcnt(48)
	v_cvt_pk_bf16_f32 v132, v168, v169
	v_cvt_pk_bf16_f32 v133, v170, v171
	ds_write_b64 v236, v[132:133] offset:11840
	s_waitcnt vmcnt(47)
	v_cvt_pk_bf16_f32 v132, v160, v161
	v_cvt_pk_bf16_f32 v133, v162, v163
	ds_write_b64 v236, v[132:133] offset:14208
	s_waitcnt vmcnt(46)
	v_cvt_pk_bf16_f32 v132, v152, v153
	v_cvt_pk_bf16_f32 v133, v154, v155
	s_waitcnt vmcnt(39)
	v_cvt_pk_bf16_f32 v84, v84, v85
	v_cvt_pk_bf16_f32 v85, v86, v87
	ds_write_b64 v236, v[132:133] offset:16576
	v_cvt_pk_bf16_f32 v132, v140, v141
	v_cvt_pk_bf16_f32 v133, v142, v143
	v_cvt_pk_bf16_f32 v128, v128, v129
	v_cvt_pk_bf16_f32 v129, v130, v131
	v_cvt_pk_bf16_f32 v120, v120, v121
	v_cvt_pk_bf16_f32 v121, v122, v123
	v_cvt_pk_bf16_f32 v112, v112, v113
	v_cvt_pk_bf16_f32 v113, v114, v115
	v_cvt_pk_bf16_f32 v100, v100, v101
	v_cvt_pk_bf16_f32 v101, v102, v103
	v_cvt_pk_bf16_f32 v92, v92, v93
	v_cvt_pk_bf16_f32 v93, v94, v95
	ds_write_b64 v236, v[84:85] offset:33152
	s_waitcnt vmcnt(38)
	v_cvt_pk_bf16_f32 v84, v88, v89
	v_cvt_pk_bf16_f32 v85, v90, v91
	s_waitcnt vmcnt(37)
	v_cvt_pk_bf16_f32 v80, v80, v81
	v_cvt_pk_bf16_f32 v81, v82, v83
	s_waitcnt vmcnt(36)
	v_cvt_pk_bf16_f32 v76, v76, v77
	v_cvt_pk_bf16_f32 v77, v78, v79
	ds_write_b64 v236, v[132:133] offset:18944
	ds_write_b64 v236, v[128:129] offset:21312
	ds_write_b64 v236, v[120:121] offset:23680
	ds_write_b64 v236, v[112:113] offset:26048
	ds_write_b64 v236, v[100:101] offset:28416
	ds_write_b64 v236, v[92:93] offset:30784
	ds_write_b64 v236, v[84:85] offset:35520
	ds_write_b64 v235, v[80:81] offset:512
	ds_write_b64 v234, v[76:77] offset:512
	s_waitcnt vmcnt(35)
	v_cvt_pk_bf16_f32 v76, v204, v205
	v_cvt_pk_bf16_f32 v77, v206, v207
	s_waitcnt lgkmcnt(0)
	s_barrier
	ds_write_b64 v236, v[76:77] offset:37888
	s_waitcnt vmcnt(34)
	v_cvt_pk_bf16_f32 v76, v208, v209
	v_cvt_pk_bf16_f32 v77, v210, v211
	ds_write_b64 v222, v[76:77] offset:37888
	s_waitcnt vmcnt(33)
	v_cvt_pk_bf16_f32 v76, v200, v201
	v_cvt_pk_bf16_f32 v77, v202, v203
	ds_write_b64 v236, v[76:77] offset:42624
	s_waitcnt vmcnt(32)
	v_cvt_pk_bf16_f32 v76, v196, v197
	v_cvt_pk_bf16_f32 v77, v198, v199
	ds_write_b64 v236, v[76:77] offset:44992
	s_waitcnt vmcnt(31)
	v_cvt_pk_bf16_f32 v76, v192, v193
	v_cvt_pk_bf16_f32 v77, v194, v195
	ds_write_b64 v236, v[76:77] offset:47360
	s_waitcnt vmcnt(30)
	v_cvt_pk_bf16_f32 v76, v180, v181
	v_cvt_pk_bf16_f32 v77, v182, v183
	ds_write_b64 v236, v[76:77] offset:49728
	s_waitcnt vmcnt(29)
	v_cvt_pk_bf16_f32 v76, v172, v173
	v_cvt_pk_bf16_f32 v77, v174, v175
	ds_write_b64 v236, v[76:77] offset:52096
	s_waitcnt vmcnt(28)
	v_cvt_pk_bf16_f32 v76, v164, v165
	v_cvt_pk_bf16_f32 v77, v166, v167
	ds_write_b64 v236, v[76:77] offset:54464
	s_waitcnt vmcnt(27)
	v_cvt_pk_bf16_f32 v76, v156, v157
	v_cvt_pk_bf16_f32 v77, v158, v159
	ds_write_b64 v236, v[76:77] offset:56832
	s_waitcnt vmcnt(26)
	v_cvt_pk_bf16_f32 v76, v148, v149
	v_cvt_pk_bf16_f32 v77, v150, v151
	ds_write_b64 v236, v[76:77] offset:59200
	s_waitcnt vmcnt(25)
	v_cvt_pk_bf16_f32 v76, v136, v137
	v_cvt_pk_bf16_f32 v77, v138, v139
	ds_write_b64 v236, v[76:77] offset:61568
	s_waitcnt vmcnt(24)
	v_cvt_pk_bf16_f32 v76, v124, v125
	v_cvt_pk_bf16_f32 v77, v126, v127
	ds_write_b64 v236, v[76:77] offset:63936
	s_waitcnt vmcnt(23)
	v_cvt_pk_bf16_f32 v76, v116, v117
	v_cvt_pk_bf16_f32 v77, v118, v119
	ds_write_b64 v238, v[76:77] offset:37888
	s_waitcnt vmcnt(22)
	v_cvt_pk_bf16_f32 v76, v108, v109
	v_cvt_pk_bf16_f32 v77, v110, v111
	ds_write_b64 v237, v[76:77] offset:37888
	s_waitcnt vmcnt(21)
	v_cvt_pk_bf16_f32 v76, v96, v97
	v_cvt_pk_bf16_f32 v77, v98, v99
	ds_write_b64 v226, v[76:77] offset:37888
	s_waitcnt vmcnt(20)
	v_cvt_pk_bf16_f32 v76, v104, v105
	v_cvt_pk_bf16_f32 v77, v106, v107
	ds_write_b64 v224, v[76:77] offset:37888
	s_waitcnt vmcnt(19)
	v_cvt_pk_bf16_f32 v76, v212, v213
	v_cvt_pk_bf16_f32 v77, v214, v215
	ds_write_b64 v235, v[76:77] offset:38400
	s_waitcnt vmcnt(18)
	v_cvt_pk_bf16_f32 v76, v216, v217
	v_cvt_pk_bf16_f32 v77, v218, v219
	ds_write_b64 v234, v[76:77] offset:38400
	s_waitcnt vmcnt(3)
	v_cvt_pk_bf16_f32 v68, v68, v69
	v_cvt_pk_bf16_f32 v69, v70, v71
	s_waitcnt lgkmcnt(0)
	s_barrier
	ds_write_b64 v236, v[68:69]
	s_waitcnt vmcnt(1)
	v_cvt_pk_bf16_f32 v68, v72, v73
	v_cvt_pk_bf16_f32 v69, v74, v75
	v_cvt_pk_bf16_f32 v36, v36, v37
	v_cvt_pk_bf16_f32 v37, v38, v39
	ds_write_b64 v222, v[68:69]
	ds_write_b64 v236, v[36:37] offset:4736
	v_cvt_pk_bf16_f32 v36, v40, v41
	v_cvt_pk_bf16_f32 v37, v42, v43
	ds_write_b64 v236, v[36:37] offset:7104
	v_cvt_pk_bf16_f32 v36, v44, v45
	v_cvt_pk_bf16_f32 v37, v46, v47
	ds_write_b64 v236, v[36:37] offset:9472
	v_cvt_pk_bf16_f32 v36, v48, v49
	v_cvt_pk_bf16_f32 v37, v50, v51
	ds_write_b64 v236, v[36:37] offset:11840
	v_cvt_pk_bf16_f32 v36, v52, v53
	v_cvt_pk_bf16_f32 v37, v54, v55
	ds_write_b64 v236, v[36:37] offset:14208
	v_cvt_pk_bf16_f32 v36, v56, v57
	v_cvt_pk_bf16_f32 v37, v58, v59
	ds_write_b64 v236, v[36:37] offset:16576
	v_cvt_pk_bf16_f32 v36, v60, v61
	v_cvt_pk_bf16_f32 v37, v62, v63
	v_cvt_pk_bf16_f32 v8, v8, v9
	v_cvt_pk_bf16_f32 v9, v10, v11
	ds_write_b64 v236, v[36:37] offset:18944
	v_cvt_pk_bf16_f32 v36, v64, v65
	v_cvt_pk_bf16_f32 v37, v66, v67
	v_cvt_pk_bf16_f32 v32, v32, v33
	v_cvt_pk_bf16_f32 v33, v34, v35
	v_cvt_pk_bf16_f32 v28, v28, v29
	v_cvt_pk_bf16_f32 v29, v30, v31
	v_cvt_pk_bf16_f32 v24, v24, v25
	v_cvt_pk_bf16_f32 v25, v26, v27
	v_cvt_pk_bf16_f32 v20, v20, v21
	v_cvt_pk_bf16_f32 v21, v22, v23
	v_cvt_pk_bf16_f32 v16, v16, v17
	v_cvt_pk_bf16_f32 v17, v18, v19
	ds_write_b64 v236, v[8:9] offset:35520
	v_cvt_pk_bf16_f32 v8, v12, v13
	v_cvt_pk_bf16_f32 v9, v14, v15
	s_waitcnt vmcnt(0)
	v_cvt_pk_bf16_f32 v4, v4, v5
	v_cvt_pk_bf16_f32 v5, v6, v7
	ds_write_b64 v236, v[36:37] offset:21312
	ds_write_b64 v236, v[32:33] offset:23680
	ds_write_b64 v236, v[28:29] offset:26048
	ds_write_b64 v236, v[24:25] offset:28416
	ds_write_b64 v236, v[20:21] offset:30784
	ds_write_b64 v236, v[16:17] offset:33152
	ds_write_b64 v235, v[8:9] offset:512
	ds_write_b64 v234, v[4:5] offset:512
	s_waitcnt lgkmcnt(0)
	s_barrier
	s_mov_b64 s[22:23], 0
	s_setprio 0

.LBB0_903:
	v_mov_b32_e32 v220, v0
	s_ashr_i32 s5, s4, 1
	s_mul_hi_i32 s13, s5, 0x12000
	v_readfirstlane_b32 s12, v220
	s_ashr_i32 s23, s12, 6
	s_mul_i32 s12, s5, 0x12000
	s_add_u32 s12, s54, s12
	v_add_u32_e32 v40, 0x200, v220
	v_add_u32_e32 v42, 0x400, v220
	v_add_u32_e32 v44, 0x600, v220
	s_addc_u32 s13, s55, s13
	v_ashrrev_i32_e32 v221, 31, v220
	v_ashrrev_i32_e32 v41, 31, v40
	v_ashrrev_i32_e32 v43, 31, v42
	v_ashrrev_i32_e32 v45, 31, v44
	v_lshl_add_u64 v[4:5], v[220:221], 4, s[12:13]
	v_lshl_add_u64 v[8:9], v[40:41], 4, s[12:13]
	v_lshl_add_u64 v[12:13], v[42:43], 4, s[12:13]
	v_lshl_add_u64 v[16:17], v[44:45], 4, s[12:13]
	s_waitcnt lgkmcnt(0)
	global_load_dwordx4 v[4:7], v[4:5], off
	s_nop 0
	global_load_dwordx4 v[8:11], v[8:9], off
	s_nop 0
	global_load_dwordx4 v[12:15], v[12:13], off
	s_nop 0
	global_load_dwordx4 v[16:19], v[16:17], off
	v_add_u32_e32 v46, 0x800, v220
	v_ashrrev_i32_e32 v47, 31, v46
	v_lshl_add_u64 v[20:21], v[46:47], 4, s[12:13]
	global_load_dwordx4 v[20:23], v[20:21], off
	v_add_u32_e32 v48, 0xa00, v220
	v_ashrrev_i32_e32 v49, 31, v48
	v_lshl_add_u64 v[24:25], v[48:49], 4, s[12:13]
	global_load_dwordx4 v[24:27], v[24:25], off
	v_add_u32_e32 v50, 0xc00, v220
	v_ashrrev_i32_e32 v51, 31, v50
	v_lshl_add_u64 v[28:29], v[50:51], 4, s[12:13]
	global_load_dwordx4 v[28:31], v[28:29], off
	v_add_u32_e32 v52, 0xe00, v220
	v_ashrrev_i32_e32 v53, 31, v52
	v_lshl_add_u64 v[32:33], v[52:53], 4, s[12:13]
	global_load_dwordx4 v[32:35], v[32:33], off
	v_add_u32_e32 v54, 0x1000, v220
	v_mul_hi_i32 v2, v220, s21
	v_ashrrev_i32_e32 v55, 31, v54
	v_lshrrev_b32_e32 v36, 31, v2
	v_ashrrev_i32_e32 v2, 3, v2
	v_mul_hi_i32 v37, v40, s21
	v_add_u32_e32 v2, v2, v36
	v_lshrrev_b32_e32 v47, 31, v37
	v_ashrrev_i32_e32 v49, 3, v37
	v_lshl_add_u64 v[36:37], v[54:55], 4, s[12:13]
	global_load_dwordx4 v[36:39], v[36:37], off
	v_mul_hi_i32 v41, v42, s21
	v_mul_hi_i32 v43, v44, s21
	v_lshrrev_b32_e32 v51, 31, v41
	v_ashrrev_i32_e32 v41, 3, v41
	v_lshrrev_b32_e32 v53, 31, v43
	v_ashrrev_i32_e32 v43, 3, v43
	v_mul_lo_u32 v56, v2, 36
	v_add_u32_e32 v47, v49, v47
	v_add_u32_e32 v41, v41, v51
	v_add_u32_e32 v43, v43, v53
	v_sub_u32_e32 v49, v220, v56
	v_mul_lo_u32 v51, v47, 36
	v_mul_lo_u32 v53, v41, 36
	v_mul_lo_u32 v56, v43, 36
	v_mul_hi_i32 v45, v46, s21
	v_mul_lo_u32 v2, v2, s34
	v_lshlrev_b32_e32 v49, 4, v49
	v_sub_u32_e32 v40, v40, v51
	v_sub_u32_e32 v42, v42, v53
	v_sub_u32_e32 v44, v44, v56
	v_lshrrev_b32_e32 v55, 31, v45
	v_ashrrev_i32_e32 v45, 3, v45
	v_mul_lo_u32 v47, v47, s34
	v_mul_lo_u32 v41, v41, s34
	v_mul_lo_u32 v43, v43, s34
	v_add3_u32 v2, s56, v2, v49
	v_lshlrev_b32_e32 v40, 4, v40
	v_lshlrev_b32_e32 v42, 4, v42
	v_lshlrev_b32_e32 v44, 4, v44
	v_add3_u32 v40, s56, v47, v40
	v_add3_u32 v41, s56, v41, v42
	v_add3_u32 v42, s56, v43, v44
	s_and_b32 s22, s4, 1
	s_cmp_lt_i32 s23, 4
	v_and_b32_e32 v221, 31, v220
	s_cselect_b64 s[12:13], -1, 0
	s_cmp_gt_i32 s23, 3
	s_waitcnt vmcnt(8)
	ds_write_b128 v2, v[4:7]
	s_waitcnt vmcnt(7)
	ds_write_b128 v40, v[8:11]
	s_waitcnt vmcnt(6)
	ds_write_b128 v41, v[12:15]
	s_waitcnt vmcnt(5)
	ds_write_b128 v42, v[16:19]
	v_add_u32_e32 v2, v45, v55
	v_mul_lo_u32 v4, v2, 36
	v_sub_u32_e32 v4, v46, v4
	v_mul_lo_u32 v2, v2, s34
	v_lshlrev_b32_e32 v4, 4, v4
	v_add3_u32 v2, s56, v2, v4
	s_waitcnt vmcnt(4)
	ds_write_b128 v2, v[20:23]
	v_mul_hi_i32 v2, v48, s21
	v_lshrrev_b32_e32 v4, 31, v2
	v_ashrrev_i32_e32 v2, 3, v2
	v_add_u32_e32 v2, v2, v4
	v_mul_lo_u32 v4, v2, 36
	v_sub_u32_e32 v4, v48, v4
	v_mul_lo_u32 v2, v2, s34
	v_lshlrev_b32_e32 v4, 4, v4
	v_add3_u32 v2, s56, v2, v4
	s_waitcnt vmcnt(3)
	ds_write_b128 v2, v[24:27]
	v_mul_hi_i32 v2, v50, s21
	v_lshrrev_b32_e32 v4, 31, v2
	v_ashrrev_i32_e32 v2, 3, v2
	v_add_u32_e32 v2, v2, v4
	v_mul_lo_u32 v4, v2, 36
	v_sub_u32_e32 v4, v50, v4
	v_mul_lo_u32 v2, v2, s34
	v_lshlrev_b32_e32 v4, 4, v4
	v_add3_u32 v2, s56, v2, v4
	s_waitcnt vmcnt(2)
	ds_write_b128 v2, v[28:31]
	v_mul_hi_i32 v2, v52, s21
	v_lshrrev_b32_e32 v4, 31, v2
	v_ashrrev_i32_e32 v2, 3, v2
	v_add_u32_e32 v2, v2, v4
	v_mul_lo_u32 v4, v2, 36
	v_sub_u32_e32 v4, v52, v4
	v_mul_lo_u32 v2, v2, s34
	v_lshlrev_b32_e32 v4, 4, v4
	v_add3_u32 v2, s56, v2, v4
	s_waitcnt vmcnt(1)
	ds_write_b128 v2, v[32:35]
	v_mul_hi_i32 v2, v54, s21
	v_lshrrev_b32_e32 v4, 31, v2
	v_ashrrev_i32_e32 v2, 3, v2
	v_add_u32_e32 v2, v2, v4
	v_mul_lo_u32 v4, v2, 36
	v_sub_u32_e32 v4, v54, v4
	v_mul_lo_u32 v2, v2, s34
	v_lshlrev_b32_e32 v4, 4, v4
	v_add3_u32 v2, s56, v2, v4
	s_waitcnt vmcnt(0)
	ds_write_b128 v2, v[36:39]
	s_mov_b64 s[14:15], -1
	s_cbranch_scc0 .LBB0_907
	s_setprio 2
	s_lshl_b32 s14, s5, 6
	s_ashr_i32 s15, s14, 31
	s_lshl_b64 s[14:15], s[14:15], 2
	s_add_u32 s14, s16, s14
	v_lshlrev_b32_e32 v2, 2, v221
	s_addc_u32 s15, s17, s15
	v_lshl_or_b32 v2, s22, 7, v2
	global_load_dword v232, v2, s[14:15]
	v_mov_b32_e32 v2, 2
	v_lshlrev_b32_sdwa v2, v2, v220 dst_sel:DWORD dst_unused:UNUSED_PAD src0_sel:DWORD src1_sel:BYTE_0
	v_mov_b32_e32 v4, 4
	v_lshlrev_b32_sdwa v205, v4, v220 dst_sel:DWORD dst_unused:UNUSED_PAD src0_sel:DWORD src1_sel:BYTE_0
	v_or_b32_e32 v204, 0x400, v2
	v_or_b32_e32 v206, 0x800, v2
	v_or_b32_e32 v208, 0xc00, v2
	v_or_b32_e32 v210, 0x1000, v2
	v_or_b32_e32 v212, 0x1400, v2
	v_or_b32_e32 v216, 0x1800, v2
	v_or_b32_e32 v218, 0x1c00, v2
	v_or_b32_e32 v234, 0x2000, v2
	v_or_b32_e32 v236, 0x2400, v2
	v_or_b32_e32 v238, 0x2800, v2
	v_or_b32_e32 v250, 0x2c00, v2
	v_or_b32_e32 v252, 0x3000, v2
	v_or_b32_e32 v224, 0x3400, v2
	v_or_b32_e32 v226, 0x3800, v2
	v_or_b32_e32 v228, 0x3c00, v2
	v_lshlrev_b32_e32 v217, 2, v204
	v_lshlrev_b32_e32 v160, 2, v206
	v_lshlrev_b32_e32 v161, 2, v208
	v_lshlrev_b32_e32 v162, 2, v210
	v_lshlrev_b32_e32 v163, 2, v212
	v_lshlrev_b32_e32 v207, 2, v216
	v_lshlrev_b32_e32 v209, 2, v218
	v_lshlrev_b32_e32 v211, 2, v234
	v_lshlrev_b32_e32 v213, 2, v236
	v_lshlrev_b32_e32 v214, 2, v238
	v_lshlrev_b32_e32 v215, 2, v250
	v_lshlrev_b32_e32 v219, 2, v252
	v_lshlrev_b32_e32 v239, 2, v224
	v_lshlrev_b32_e32 v240, 2, v226
	v_lshlrev_b32_e32 v241, 2, v228
	v_or_b32_sdwa v5, v220, s35 dst_sel:DWORD dst_unused:UNUSED_PAD src0_sel:BYTE_0 src1_sel:DWORD
	v_lshlrev_b32_e32 v4, 3, v220
	v_bfe_u32 v6, v220, 3, 5
	v_lshrrev_b32_e32 v237, 6, v5
	v_lshrrev_b32_e32 v5, 3, v5
	v_and_b32_e32 v7, 0x1f8, v4
	v_and_b32_e32 v4, 56, v4
	v_mad_u32_u24 v6, v6, s34, 0
	v_mad_u32_u24 v5, v5, s34, 0
	v_add_u32_e32 v254, 0, v7
	v_add_u32_e32 v231, v6, v4
	v_add_u32_e32 v230, v5, v4
	v_bfe_u32 v235, v220, 6, 2
	v_mad_u32_u24 v233, v235, s34, v254
	v_mad_u32_u24 v168, v237, s34, v254
	v_lshlrev_b32_e32 v242, 2, v210
	v_lshlrev_b32_e32 v243, 2, v212
	v_lshlrev_b32_e32 v244, 2, v216
	v_lshlrev_b32_e32 v245, 2, v218
	v_lshlrev_b32_e32 v246, 2, v234
	v_lshlrev_b32_e32 v249, 2, v250
	v_lshlrev_b32_e32 v250, 2, v252
	v_mul_u32_u24_e32 v234, 0x250, v237
	v_lshlrev_b32_e32 v251, 2, v224
	v_mad_u32_u24 v224, v235, s34, v225
	v_lshlrev_b32_e32 v252, 2, v226
	v_mad_u32_u24 v226, v235, s34, v229
	v_lshlrev_b32_e32 v253, 2, v228
	v_mad_u32_u24 v228, v235, s34, v227
	v_mad_u32_u24 v235, v235, s34, v1
	v_lshlrev_b32_e32 v247, 2, v236
	v_lshlrev_b32_e32 v248, 2, v238
	v_add_u32_e32 v234, v254, v234
	v_add_u32_e32 v238, v254, v224
	v_add_u32_e32 v237, v254, v226
	v_add_u32_e32 v236, v254, v228
	v_add_u32_e32 v235, v254, v235
	s_waitcnt vmcnt(0)
	v_readlane_b32 s14, v232, 0
	s_ashr_i32 s15, s14, 31
	s_lshl_b64 s[28:29], s[14:15], 17
	s_add_u32 s28, s8, s28
	s_addc_u32 s29, s9, s29
	s_lshl_b64 s[30:31], s[14:15], 14
	global_load_dwordx4 v[84:87], v205, s[28:29] nt
	global_load_dwordx4 v[108:111], v207, s[28:29] nt
	s_add_u32 s30, s10, s30
	global_load_dwordx4 v[88:91], v217, s[28:29] nt
	global_load_dwordx4 v[128:131], v215, s[28:29] nt
	global_load_dwordx4 v[92:95], v160, s[28:29] nt
	global_load_dwordx4 v[96:99], v161, s[28:29] nt
	global_load_dwordx4 v[100:103], v162, s[28:29] nt
	global_load_dwordx4 v[104:107], v163, s[28:29] nt
	global_load_dwordx4 v[112:115], v209, s[28:29] nt
	global_load_dwordx4 v[116:119], v211, s[28:29] nt
	global_load_dwordx4 v[120:123], v213, s[28:29] nt
	global_load_dwordx4 v[124:127], v214, s[28:29] nt
	global_load_dwordx4 v[132:135], v219, s[28:29] nt
	global_load_dwordx4 v[136:139], v239, s[28:29] nt
	global_load_dwordx4 v[140:143], v240, s[28:29] nt
	global_load_dwordx4 v[144:147], v241, s[28:29] nt
	s_addc_u32 s31, s11, s31
	global_load_dwordx4 v[148:151], v205, s[30:31] nt
	global_load_dwordx4 v[156:159], v217, s[30:31] nt
	s_lshl_b64 s[14:15], s[14:15], 7
	s_or_b32 s14, s14, 64
	s_lshl_b64 s[30:31], s[14:15], 10
	s_add_u32 s30, s8, s30
	s_addc_u32 s31, s9, s31
	s_lshl_b64 s[14:15], s[14:15], 7
	v_readlane_b32 s28, v232, 1
	s_add_u32 s14, s10, s14
	s_addc_u32 s15, s11, s15
	s_ashr_i32 s29, s28, 31
	global_load_dwordx4 v[64:67], v160, s[30:31] nt
	global_load_dwordx4 v[60:63], v161, s[30:31] nt
	global_load_dwordx4 v[56:59], v162, s[30:31] nt
	global_load_dwordx4 v[52:55], v163, s[30:31] nt
	global_load_dwordx4 v[48:51], v207, s[30:31] nt
	global_load_dwordx4 v[44:47], v209, s[30:31] nt
	global_load_dwordx4 v[40:43], v211, s[30:31] nt
	global_load_dwordx4 v[36:39], v213, s[30:31] nt
	global_load_dwordx4 v[32:35], v214, s[30:31] nt
	global_load_dwordx4 v[28:31], v215, s[30:31] nt
	global_load_dwordx4 v[24:27], v219, s[30:31] nt
	global_load_dwordx4 v[20:23], v239, s[30:31] nt
	global_load_dwordx4 v[16:19], v240, s[30:31] nt
	global_load_dwordx4 v[12:15], v241, s[30:31] nt
	global_load_dwordx4 v[72:75], v205, s[30:31] nt
	global_load_dwordx4 v[8:11], v205, s[14:15] nt
	global_load_dwordx4 v[68:71], v217, s[30:31] nt
	global_load_dwordx4 v[4:7], v217, s[14:15] nt
	s_lshl_b64 s[14:15], s[28:29], 17
	s_add_u32 s14, s8, s14
	s_addc_u32 s15, s9, s15
	s_lshl_b64 s[30:31], s[28:29], 14
	s_add_u32 s30, s10, s30
	s_addc_u32 s31, s11, s31
	s_lshl_b64 s[28:29], s[28:29], 7
	s_or_b32 s28, s28, 64
	global_load_dwordx4 v[164:167], v205, s[14:15] nt
	global_load_dwordx4 v[80:83], v205, s[30:31] nt
	global_load_dwordx4 v[152:155], v217, s[14:15] nt
	global_load_dwordx4 v[76:79], v217, s[30:31] nt
	s_lshl_b64 s[30:31], s[28:29], 10
	s_add_u32 s30, s8, s30
	s_addc_u32 s31, s9, s31
	s_lshl_b64 s[28:29], s[28:29], 7
	s_waitcnt vmcnt(39)
	v_cvt_pk_bf16_f32 v84, v84, v85
	v_cvt_pk_bf16_f32 v85, v86, v87
	s_waitcnt vmcnt(37)
	v_cvt_pk_bf16_f32 v86, v88, v89
	v_cvt_pk_bf16_f32 v87, v90, v91
	s_waitcnt vmcnt(35)
	v_cvt_pk_bf16_f32 v88, v92, v93
	v_cvt_pk_bf16_f32 v89, v94, v95
	s_waitcnt vmcnt(34)
	v_cvt_pk_bf16_f32 v90, v96, v97
	v_cvt_pk_bf16_f32 v91, v98, v99
	s_waitcnt vmcnt(33)
	v_cvt_pk_bf16_f32 v92, v100, v101
	v_cvt_pk_bf16_f32 v93, v102, v103
	s_waitcnt vmcnt(32)
	v_cvt_pk_bf16_f32 v94, v104, v105
	v_cvt_pk_bf16_f32 v95, v106, v107
	v_cvt_pk_bf16_f32 v96, v108, v109
	v_cvt_pk_bf16_f32 v97, v110, v111
	s_waitcnt vmcnt(31)
	v_cvt_pk_bf16_f32 v98, v112, v113
	v_cvt_pk_bf16_f32 v99, v114, v115
	s_waitcnt vmcnt(30)
	v_cvt_pk_bf16_f32 v100, v116, v117
	v_cvt_pk_bf16_f32 v101, v118, v119
	s_waitcnt vmcnt(29)
	v_cvt_pk_bf16_f32 v102, v120, v121
	v_cvt_pk_bf16_f32 v103, v122, v123
	s_waitcnt vmcnt(28)
	v_cvt_pk_bf16_f32 v104, v124, v125
	v_cvt_pk_bf16_f32 v105, v126, v127
	v_cvt_pk_bf16_f32 v106, v128, v129
	v_cvt_pk_bf16_f32 v107, v130, v131
	s_waitcnt vmcnt(27)
	v_cvt_pk_bf16_f32 v108, v132, v133
	v_cvt_pk_bf16_f32 v109, v134, v135
	s_waitcnt vmcnt(26)
	v_cvt_pk_bf16_f32 v110, v136, v137
	v_cvt_pk_bf16_f32 v111, v138, v139
	s_waitcnt vmcnt(25)
	v_cvt_pk_bf16_f32 v112, v140, v141
	v_cvt_pk_bf16_f32 v113, v142, v143
	s_waitcnt vmcnt(24)
	v_cvt_pk_bf16_f32 v114, v144, v145
	v_cvt_pk_bf16_f32 v115, v146, v147
	ds_write_b64 v233, v[84:85]
	ds_write_b64 v168, v[86:87]
	ds_write_b64 v233, v[88:89] offset:4736
	ds_write_b64 v233, v[90:91] offset:7104
	ds_write_b64 v233, v[92:93] offset:9472
	ds_write_b64 v233, v[94:95] offset:11840
	ds_write_b64 v233, v[96:97] offset:14208
	ds_write_b64 v233, v[98:99] offset:16576
	ds_write_b64 v233, v[100:101] offset:18944
	ds_write_b64 v233, v[102:103] offset:21312
	ds_write_b64 v233, v[104:105] offset:23680
	ds_write_b64 v233, v[106:107] offset:26048
	ds_write_b64 v233, v[108:109] offset:28416
	ds_write_b64 v233, v[110:111] offset:30784
	ds_write_b64 v233, v[112:113] offset:33152
	ds_write_b64 v233, v[114:115] offset:35520
	s_waitcnt vmcnt(23)
	v_cvt_pk_bf16_f32 v84, v148, v149
	v_cvt_pk_bf16_f32 v85, v150, v151
	s_waitcnt vmcnt(22)
	v_cvt_pk_bf16_f32 v86, v156, v157
	v_cvt_pk_bf16_f32 v87, v158, v159
	ds_write_b64 v231, v[84:85] offset:512
	ds_write_b64 v230, v[86:87] offset:512
	global_load_dwordx4 v[200:203], v160, s[14:15] nt
	global_load_dwordx4 v[196:199], v160, s[30:31] nt
	global_load_dwordx4 v[192:195], v161, s[14:15] nt
	global_load_dwordx4 v[188:191], v161, s[30:31] nt
	global_load_dwordx4 v[184:187], v162, s[14:15] nt
	global_load_dwordx4 v[180:183], v162, s[30:31] nt
	global_load_dwordx4 v[176:179], v163, s[14:15] nt
	global_load_dwordx4 v[172:175], v163, s[30:31] nt
	global_load_dwordx4 v[168:171], v207, s[14:15] nt
	s_nop 0
	global_load_dwordx4 v[160:163], v207, s[30:31] nt
	global_load_dwordx4 v[156:159], v209, s[14:15] nt
	global_load_dwordx4 v[148:151], v209, s[30:31] nt
	global_load_dwordx4 v[144:147], v211, s[14:15] nt
	global_load_dwordx4 v[140:143], v211, s[30:31] nt
	global_load_dwordx4 v[136:139], v213, s[14:15] nt
	global_load_dwordx4 v[132:135], v213, s[30:31] nt
	global_load_dwordx4 v[128:131], v214, s[14:15] nt
	global_load_dwordx4 v[124:127], v214, s[30:31] nt
	global_load_dwordx4 v[120:123], v215, s[14:15] nt
	global_load_dwordx4 v[116:119], v215, s[30:31] nt
	global_load_dwordx4 v[112:115], v219, s[14:15] nt
	global_load_dwordx4 v[108:111], v219, s[30:31] nt
	global_load_dwordx4 v[104:107], v239, s[14:15] nt
	global_load_dwordx4 v[100:103], v239, s[30:31] nt
	global_load_dwordx4 v[96:99], v240, s[14:15] nt
	global_load_dwordx4 v[92:95], v240, s[30:31] nt
	global_load_dwordx4 v[88:91], v241, s[14:15] nt
	global_load_dwordx4 v[84:87], v241, s[30:31] nt
	s_add_u32 s14, s10, s28
	s_addc_u32 s15, s11, s29
	v_lshlrev_b32_e32 v239, 2, v204
	v_lshlrev_b32_e32 v240, 2, v206
	v_lshlrev_b32_e32 v241, 2, v208
	global_load_dwordx4 v[208:211], v205, s[30:31] nt
	global_load_dwordx4 v[212:215], v205, s[14:15] nt
	s_nop 0
	global_load_dwordx4 v[204:207], v217, s[30:31] nt
	s_nop 0
	global_load_dwordx4 v[216:219], v217, s[14:15] nt
	s_waitcnt lgkmcnt(0)
	s_barrier
	s_mov_b32 s28, 4
	s_mov_b32 s29, -6
.LBB0_905:
	s_add_i32 s14, s28, -2
	v_readlane_b32 s14, v232, s14
	s_ashr_i32 s15, s14, 31
	s_lshl_b64 s[30:31], s[14:15], 17
	s_waitcnt vmcnt(39)
	v_cvt_pk_bf16_f32 v72, v72, v73
	v_cvt_pk_bf16_f32 v73, v74, v75
	s_waitcnt vmcnt(37)
	v_cvt_pk_bf16_f32 v68, v68, v69
	v_cvt_pk_bf16_f32 v69, v70, v71
	v_cvt_pk_bf16_f32 v64, v64, v65
	v_cvt_pk_bf16_f32 v65, v66, v67
	v_cvt_pk_bf16_f32 v60, v60, v61
	v_cvt_pk_bf16_f32 v61, v62, v63
	v_cvt_pk_bf16_f32 v56, v56, v57
	v_cvt_pk_bf16_f32 v57, v58, v59
	v_cvt_pk_bf16_f32 v52, v52, v53
	v_cvt_pk_bf16_f32 v53, v54, v55
	v_cvt_pk_bf16_f32 v48, v48, v49
	v_cvt_pk_bf16_f32 v49, v50, v51
	v_cvt_pk_bf16_f32 v44, v44, v45
	v_cvt_pk_bf16_f32 v45, v46, v47
	v_cvt_pk_bf16_f32 v40, v40, v41
	v_cvt_pk_bf16_f32 v41, v42, v43
	v_cvt_pk_bf16_f32 v36, v36, v37
	v_cvt_pk_bf16_f32 v37, v38, v39
	v_cvt_pk_bf16_f32 v32, v32, v33
	v_cvt_pk_bf16_f32 v33, v34, v35
	v_cvt_pk_bf16_f32 v28, v28, v29
	v_cvt_pk_bf16_f32 v29, v30, v31
	v_cvt_pk_bf16_f32 v24, v24, v25
	v_cvt_pk_bf16_f32 v25, v26, v27
	v_cvt_pk_bf16_f32 v20, v20, v21
	v_cvt_pk_bf16_f32 v21, v22, v23
	v_cvt_pk_bf16_f32 v16, v16, v17
	v_cvt_pk_bf16_f32 v17, v18, v19
	v_cvt_pk_bf16_f32 v12, v12, v13
	v_cvt_pk_bf16_f32 v13, v14, v15
	v_cvt_pk_bf16_f32 v8, v8, v9
	v_cvt_pk_bf16_f32 v9, v10, v11
	s_waitcnt vmcnt(36)
	v_cvt_pk_bf16_f32 v4, v4, v5
	v_cvt_pk_bf16_f32 v5, v6, v7
	s_add_u32 s30, s8, s30
	ds_write_b64 v233, v[72:73] offset:37888
	ds_write_b64 v234, v[68:69] offset:37888
	ds_write_b64 v233, v[64:65] offset:42624
	ds_write_b64 v233, v[60:61] offset:44992
	ds_write_b64 v233, v[56:57] offset:47360
	ds_write_b64 v233, v[52:53] offset:49728
	ds_write_b64 v233, v[48:49] offset:52096
	ds_write_b64 v233, v[44:45] offset:54464
	ds_write_b64 v233, v[40:41] offset:56832
	ds_write_b64 v233, v[36:37] offset:59200
	ds_write_b64 v233, v[32:33] offset:61568
	ds_write_b64 v233, v[28:29] offset:63936
	ds_write_b64 v238, v[24:25] offset:37888
	ds_write_b64 v237, v[20:21] offset:37888
	ds_write_b64 v236, v[16:17] offset:37888
	ds_write_b64 v235, v[12:13] offset:37888
	ds_write_b64 v231, v[8:9] offset:38400
	ds_write_b64 v230, v[4:5] offset:38400
	s_addc_u32 s31, s9, s31
	s_lshl_b64 s[50:51], s[14:15], 14
	v_lshlrev_b32_e32 v254, 2, v2
	global_load_dwordx4 v[72:75], v254, s[30:31] nt
	global_load_dwordx4 v[68:71], v239, s[30:31] nt
	global_load_dwordx4 v[64:67], v240, s[30:31] nt
	global_load_dwordx4 v[60:63], v241, s[30:31] nt
	global_load_dwordx4 v[56:59], v242, s[30:31] nt
	global_load_dwordx4 v[52:55], v243, s[30:31] nt
	global_load_dwordx4 v[48:51], v244, s[30:31] nt
	global_load_dwordx4 v[44:47], v245, s[30:31] nt
	global_load_dwordx4 v[40:43], v246, s[30:31] nt
	global_load_dwordx4 v[36:39], v247, s[30:31] nt
	global_load_dwordx4 v[32:35], v248, s[30:31] nt
	global_load_dwordx4 v[28:31], v249, s[30:31] nt
	global_load_dwordx4 v[24:27], v250, s[30:31] nt
	global_load_dwordx4 v[20:23], v251, s[30:31] nt
	global_load_dwordx4 v[16:19], v252, s[30:31] nt
	global_load_dwordx4 v[8:11], v253, s[30:31] nt
	s_add_u32 s30, s10, s50
	s_addc_u32 s31, s11, s51
	s_waitcnt vmcnt(51)
	v_cvt_pk_bf16_f32 v164, v164, v165
	v_cvt_pk_bf16_f32 v165, v166, v167
	s_waitcnt vmcnt(49)
	v_cvt_pk_bf16_f32 v152, v152, v153
	v_cvt_pk_bf16_f32 v153, v154, v155
	global_load_dwordx4 v[12:15], v254, s[30:31] nt
	global_load_dwordx4 v[4:7], v239, s[30:31] nt
	s_waitcnt lgkmcnt(0)
	s_barrier
	ds_write_b64 v233, v[164:165]
	ds_write_b64 v234, v[152:153]
	s_waitcnt vmcnt(49)
	v_cvt_pk_bf16_f32 v152, v200, v201
	v_cvt_pk_bf16_f32 v153, v202, v203
	s_lshl_b64 s[14:15], s[14:15], 7
	ds_write_b64 v233, v[152:153] offset:4736
	s_waitcnt vmcnt(47)
	v_cvt_pk_bf16_f32 v152, v192, v193
	v_cvt_pk_bf16_f32 v153, v194, v195
	s_or_b32 s14, s14, 64
	ds_write_b64 v233, v[152:153] offset:7104
	s_waitcnt vmcnt(45)
	v_cvt_pk_bf16_f32 v152, v184, v185
	v_cvt_pk_bf16_f32 v153, v186, v187
	s_lshl_b64 s[30:31], s[14:15], 10
	ds_write_b64 v233, v[152:153] offset:9472
	s_waitcnt vmcnt(43)
	v_cvt_pk_bf16_f32 v152, v176, v177
	v_cvt_pk_bf16_f32 v153, v178, v179
	s_add_u32 s30, s8, s30
	ds_write_b64 v233, v[152:153] offset:11840
	s_waitcnt vmcnt(41)
	v_cvt_pk_bf16_f32 v152, v168, v169
	v_cvt_pk_bf16_f32 v153, v170, v171
	s_addc_u32 s31, s9, s31
	s_lshl_b64 s[14:15], s[14:15], 7
	ds_write_b64 v233, v[152:153] offset:14208
	s_waitcnt vmcnt(39)
	v_cvt_pk_bf16_f32 v152, v156, v157
	v_cvt_pk_bf16_f32 v153, v158, v159
	s_waitcnt vmcnt(37)
	v_cvt_pk_bf16_f32 v144, v144, v145
	v_cvt_pk_bf16_f32 v145, v146, v147
	s_waitcnt vmcnt(35)
	v_cvt_pk_bf16_f32 v136, v136, v137
	v_cvt_pk_bf16_f32 v137, v138, v139
	s_waitcnt vmcnt(33)
	v_cvt_pk_bf16_f32 v128, v128, v129
	v_cvt_pk_bf16_f32 v129, v130, v131
	s_waitcnt vmcnt(31)
	v_cvt_pk_bf16_f32 v120, v120, v121
	v_cvt_pk_bf16_f32 v121, v122, v123
	s_waitcnt vmcnt(29)
	v_cvt_pk_bf16_f32 v112, v112, v113
	v_cvt_pk_bf16_f32 v113, v114, v115
	s_waitcnt vmcnt(27)
	v_cvt_pk_bf16_f32 v104, v104, v105
	v_cvt_pk_bf16_f32 v105, v106, v107
	s_waitcnt vmcnt(25)
	v_cvt_pk_bf16_f32 v96, v96, v97
	v_cvt_pk_bf16_f32 v97, v98, v99
	s_waitcnt vmcnt(23)
	v_cvt_pk_bf16_f32 v88, v88, v89
	v_cvt_pk_bf16_f32 v89, v90, v91
	v_cvt_pk_bf16_f32 v80, v80, v81
	v_cvt_pk_bf16_f32 v81, v82, v83
	v_cvt_pk_bf16_f32 v76, v76, v77
	v_cvt_pk_bf16_f32 v77, v78, v79
	s_add_u32 s14, s10, s14
	ds_write_b64 v233, v[152:153] offset:16576
	ds_write_b64 v233, v[144:145] offset:18944
	ds_write_b64 v233, v[136:137] offset:21312
	ds_write_b64 v233, v[128:129] offset:23680
	ds_write_b64 v233, v[120:121] offset:26048
	ds_write_b64 v233, v[112:113] offset:28416
	ds_write_b64 v233, v[104:105] offset:30784
	ds_write_b64 v233, v[96:97] offset:33152
	ds_write_b64 v233, v[88:89] offset:35520
	ds_write_b64 v231, v[80:81] offset:512
	ds_write_b64 v230, v[76:77] offset:512
	s_addc_u32 s15, s11, s15
	global_load_dwordx4 v[200:203], v254, s[30:31] nt
	global_load_dwordx4 v[192:195], v239, s[30:31] nt
	global_load_dwordx4 v[184:187], v240, s[30:31] nt
	global_load_dwordx4 v[176:179], v241, s[30:31] nt
	global_load_dwordx4 v[168:171], v242, s[30:31] nt
	global_load_dwordx4 v[164:167], v243, s[30:31] nt
	global_load_dwordx4 v[156:159], v244, s[30:31] nt
	global_load_dwordx4 v[152:155], v245, s[30:31] nt
	global_load_dwordx4 v[144:147], v246, s[30:31] nt
	global_load_dwordx4 v[136:139], v247, s[30:31] nt
	global_load_dwordx4 v[128:131], v248, s[30:31] nt
	global_load_dwordx4 v[120:123], v249, s[30:31] nt
	global_load_dwordx4 v[112:115], v250, s[30:31] nt
	global_load_dwordx4 v[104:107], v251, s[30:31] nt
	global_load_dwordx4 v[96:99], v252, s[30:31] nt
	global_load_dwordx4 v[80:83], v253, s[30:31] nt
	global_load_dwordx4 v[88:91], v254, s[14:15] nt
	global_load_dwordx4 v[76:79], v239, s[14:15] nt
	s_add_i32 s14, s28, -1
	v_readlane_b32 s14, v232, s14
	s_ashr_i32 s15, s14, 31
	s_waitcnt vmcnt(39)
	v_cvt_pk_bf16_f32 v208, v208, v209
	v_cvt_pk_bf16_f32 v209, v210, v211
	s_waitcnt vmcnt(37)
	v_cvt_pk_bf16_f32 v204, v204, v205
	v_cvt_pk_bf16_f32 v205, v206, v207
	v_cvt_pk_bf16_f32 v84, v84, v85
	v_cvt_pk_bf16_f32 v85, v86, v87
	s_lshl_b64 s[30:31], s[14:15], 14
	s_lshl_b64 s[50:51], s[14:15], 17
	s_waitcnt lgkmcnt(0)
	s_barrier
	ds_write_b64 v233, v[208:209] offset:37888
	ds_write_b64 v234, v[204:205] offset:37888
	v_cvt_pk_bf16_f32 v196, v196, v197
	v_cvt_pk_bf16_f32 v197, v198, v199
	v_cvt_pk_bf16_f32 v188, v188, v189
	v_cvt_pk_bf16_f32 v189, v190, v191
	v_cvt_pk_bf16_f32 v180, v180, v181
	v_cvt_pk_bf16_f32 v181, v182, v183
	v_cvt_pk_bf16_f32 v172, v172, v173
	v_cvt_pk_bf16_f32 v173, v174, v175
	v_cvt_pk_bf16_f32 v160, v160, v161
	v_cvt_pk_bf16_f32 v161, v162, v163
	v_cvt_pk_bf16_f32 v148, v148, v149
	v_cvt_pk_bf16_f32 v149, v150, v151
	v_cvt_pk_bf16_f32 v140, v140, v141
	v_cvt_pk_bf16_f32 v141, v142, v143
	v_cvt_pk_bf16_f32 v132, v132, v133
	v_cvt_pk_bf16_f32 v133, v134, v135
	v_cvt_pk_bf16_f32 v124, v124, v125
	v_cvt_pk_bf16_f32 v125, v126, v127
	v_cvt_pk_bf16_f32 v116, v116, v117
	v_cvt_pk_bf16_f32 v117, v118, v119
	v_cvt_pk_bf16_f32 v108, v108, v109
	v_cvt_pk_bf16_f32 v109, v110, v111
	v_cvt_pk_bf16_f32 v100, v100, v101
	v_cvt_pk_bf16_f32 v101, v102, v103
	v_cvt_pk_bf16_f32 v92, v92, v93
	v_cvt_pk_bf16_f32 v93, v94, v95
	ds_write_b64 v235, v[84:85] offset:37888
	v_cvt_pk_bf16_f32 v84, v212, v213
	v_cvt_pk_bf16_f32 v85, v214, v215
	s_add_u32 s50, s8, s50
	ds_write_b64 v233, v[196:197] offset:42624
	ds_write_b64 v233, v[188:189] offset:44992
	ds_write_b64 v233, v[180:181] offset:47360
	ds_write_b64 v233, v[172:173] offset:49728
	ds_write_b64 v233, v[160:161] offset:52096
	ds_write_b64 v233, v[148:149] offset:54464
	ds_write_b64 v233, v[140:141] offset:56832
	ds_write_b64 v233, v[132:133] offset:59200
	ds_write_b64 v233, v[124:125] offset:61568
	ds_write_b64 v233, v[116:117] offset:63936
	ds_write_b64 v238, v[108:109] offset:37888
	ds_write_b64 v237, v[100:101] offset:37888
	ds_write_b64 v236, v[92:93] offset:37888
	ds_write_b64 v231, v[84:85] offset:38400
	s_waitcnt vmcnt(36)
	v_cvt_pk_bf16_f32 v84, v216, v217
	v_cvt_pk_bf16_f32 v85, v218, v219
	s_addc_u32 s51, s9, s51
	ds_write_b64 v230, v[84:85] offset:38400
	s_add_u32 s30, s10, s30
	global_load_dwordx4 v[216:219], v254, s[50:51] nt
	global_load_dwordx4 v[212:215], v239, s[50:51] nt
	global_load_dwordx4 v[208:211], v240, s[50:51] nt
	global_load_dwordx4 v[204:207], v241, s[50:51] nt
	global_load_dwordx4 v[196:199], v242, s[50:51] nt
	global_load_dwordx4 v[188:191], v243, s[50:51] nt
	global_load_dwordx4 v[180:183], v244, s[50:51] nt
	global_load_dwordx4 v[172:175], v245, s[50:51] nt
	global_load_dwordx4 v[160:163], v246, s[50:51] nt
	global_load_dwordx4 v[148:151], v247, s[50:51] nt
	global_load_dwordx4 v[140:143], v248, s[50:51] nt
	global_load_dwordx4 v[132:135], v249, s[50:51] nt
	global_load_dwordx4 v[124:127], v250, s[50:51] nt
	global_load_dwordx4 v[116:119], v251, s[50:51] nt
	global_load_dwordx4 v[108:111], v252, s[50:51] nt
	global_load_dwordx4 v[92:95], v253, s[50:51] nt
	s_addc_u32 s31, s11, s31
	global_load_dwordx4 v[100:103], v254, s[30:31] nt
	global_load_dwordx4 v[84:87], v239, s[30:31] nt
	s_lshl_b64 s[14:15], s[14:15], 7
	s_or_b32 s14, s14, 64
	s_lshl_b64 s[30:31], s[14:15], 10
	s_add_u32 s30, s8, s30
	s_waitcnt vmcnt(53)
	v_cvt_pk_bf16_f32 v72, v72, v73
	v_cvt_pk_bf16_f32 v73, v74, v75
	s_waitcnt vmcnt(52)
	v_cvt_pk_bf16_f32 v68, v68, v69
	v_cvt_pk_bf16_f32 v69, v70, v71
	s_waitcnt vmcnt(38)
	v_cvt_pk_bf16_f32 v8, v8, v9
	v_cvt_pk_bf16_f32 v9, v10, v11
	s_addc_u32 s31, s9, s31
	s_lshl_b64 s[14:15], s[14:15], 7
	s_waitcnt lgkmcnt(0)
	s_barrier
	ds_write_b64 v233, v[72:73]
	ds_write_b64 v234, v[68:69]
	v_cvt_pk_bf16_f32 v64, v64, v65
	v_cvt_pk_bf16_f32 v65, v66, v67
	v_cvt_pk_bf16_f32 v60, v60, v61
	v_cvt_pk_bf16_f32 v61, v62, v63
	v_cvt_pk_bf16_f32 v56, v56, v57
	v_cvt_pk_bf16_f32 v57, v58, v59
	v_cvt_pk_bf16_f32 v52, v52, v53
	v_cvt_pk_bf16_f32 v53, v54, v55
	v_cvt_pk_bf16_f32 v48, v48, v49
	v_cvt_pk_bf16_f32 v49, v50, v51
	v_cvt_pk_bf16_f32 v44, v44, v45
	v_cvt_pk_bf16_f32 v45, v46, v47
	v_cvt_pk_bf16_f32 v40, v40, v41
	v_cvt_pk_bf16_f32 v41, v42, v43
	v_cvt_pk_bf16_f32 v36, v36, v37
	v_cvt_pk_bf16_f32 v37, v38, v39
	v_cvt_pk_bf16_f32 v32, v32, v33
	v_cvt_pk_bf16_f32 v33, v34, v35
	v_cvt_pk_bf16_f32 v28, v28, v29
	v_cvt_pk_bf16_f32 v29, v30, v31
	v_cvt_pk_bf16_f32 v24, v24, v25
	v_cvt_pk_bf16_f32 v25, v26, v27
	v_cvt_pk_bf16_f32 v20, v20, v21
	v_cvt_pk_bf16_f32 v21, v22, v23
	v_cvt_pk_bf16_f32 v16, v16, v17
	v_cvt_pk_bf16_f32 v17, v18, v19
	ds_write_b64 v233, v[8:9] offset:35520
	s_waitcnt vmcnt(37)
	v_cvt_pk_bf16_f32 v8, v12, v13
	v_cvt_pk_bf16_f32 v9, v14, v15
	s_waitcnt vmcnt(36)
	v_cvt_pk_bf16_f32 v4, v4, v5
	v_cvt_pk_bf16_f32 v5, v6, v7
	s_add_u32 s14, s10, s14
	ds_write_b64 v233, v[64:65] offset:4736
	ds_write_b64 v233, v[60:61] offset:7104
	ds_write_b64 v233, v[56:57] offset:9472
	ds_write_b64 v233, v[52:53] offset:11840
	ds_write_b64 v233, v[48:49] offset:14208
	ds_write_b64 v233, v[44:45] offset:16576
	ds_write_b64 v233, v[40:41] offset:18944
	ds_write_b64 v233, v[36:37] offset:21312
	ds_write_b64 v233, v[32:33] offset:23680
	ds_write_b64 v233, v[28:29] offset:26048
	ds_write_b64 v233, v[24:25] offset:28416
	ds_write_b64 v233, v[20:21] offset:30784
	ds_write_b64 v233, v[16:17] offset:33152
	ds_write_b64 v231, v[8:9] offset:512
	ds_write_b64 v230, v[4:5] offset:512
	s_addc_u32 s15, s11, s15
	global_load_dwordx4 v[72:75], v254, s[30:31] nt
	global_load_dwordx4 v[68:71], v239, s[30:31] nt
	global_load_dwordx4 v[64:67], v240, s[30:31] nt
	global_load_dwordx4 v[60:63], v241, s[30:31] nt
	global_load_dwordx4 v[56:59], v242, s[30:31] nt
	global_load_dwordx4 v[52:55], v243, s[30:31] nt
	global_load_dwordx4 v[48:51], v244, s[30:31] nt
	global_load_dwordx4 v[44:47], v245, s[30:31] nt
	global_load_dwordx4 v[40:43], v246, s[30:31] nt
	global_load_dwordx4 v[36:39], v247, s[30:31] nt
	global_load_dwordx4 v[32:35], v248, s[30:31] nt
	global_load_dwordx4 v[28:31], v249, s[30:31] nt
	global_load_dwordx4 v[24:27], v250, s[30:31] nt
	global_load_dwordx4 v[20:23], v251, s[30:31] nt
	global_load_dwordx4 v[16:19], v252, s[30:31] nt
	global_load_dwordx4 v[12:15], v253, s[30:31] nt
	global_load_dwordx4 v[8:11], v254, s[14:15] nt
	global_load_dwordx4 v[4:7], v239, s[14:15] nt
	v_readlane_b32 s14, v232, s28
	s_ashr_i32 s15, s14, 31
	s_lshl_b64 s[30:31], s[14:15], 14
	s_lshl_b64 s[50:51], s[14:15], 17
	s_add_u32 s50, s8, s50
	s_addc_u32 s51, s9, s51
	s_waitcnt vmcnt(53)
	v_cvt_pk_bf16_f32 v200, v200, v201
	v_cvt_pk_bf16_f32 v201, v202, v203
	s_waitcnt vmcnt(52)
	v_cvt_pk_bf16_f32 v192, v192, v193
	v_cvt_pk_bf16_f32 v193, v194, v195
	s_waitcnt vmcnt(38)
	v_cvt_pk_bf16_f32 v80, v80, v81
	v_cvt_pk_bf16_f32 v81, v82, v83
	s_add_u32 s30, s10, s30
	s_waitcnt lgkmcnt(0)
	s_barrier
	ds_write_b64 v233, v[200:201] offset:37888
	ds_write_b64 v234, v[192:193] offset:37888
	v_cvt_pk_bf16_f32 v184, v184, v185
	v_cvt_pk_bf16_f32 v185, v186, v187
	v_cvt_pk_bf16_f32 v176, v176, v177
	v_cvt_pk_bf16_f32 v177, v178, v179
	v_cvt_pk_bf16_f32 v168, v168, v169
	v_cvt_pk_bf16_f32 v169, v170, v171
	v_cvt_pk_bf16_f32 v164, v164, v165
	v_cvt_pk_bf16_f32 v165, v166, v167
	v_cvt_pk_bf16_f32 v156, v156, v157
	v_cvt_pk_bf16_f32 v157, v158, v159
	v_cvt_pk_bf16_f32 v152, v152, v153
	v_cvt_pk_bf16_f32 v153, v154, v155
	v_cvt_pk_bf16_f32 v144, v144, v145
	v_cvt_pk_bf16_f32 v145, v146, v147
	v_cvt_pk_bf16_f32 v136, v136, v137
	v_cvt_pk_bf16_f32 v137, v138, v139
	v_cvt_pk_bf16_f32 v128, v128, v129
	v_cvt_pk_bf16_f32 v129, v130, v131
	v_cvt_pk_bf16_f32 v120, v120, v121
	v_cvt_pk_bf16_f32 v121, v122, v123
	v_cvt_pk_bf16_f32 v112, v112, v113
	v_cvt_pk_bf16_f32 v113, v114, v115
	v_cvt_pk_bf16_f32 v104, v104, v105
	v_cvt_pk_bf16_f32 v105, v106, v107
	v_cvt_pk_bf16_f32 v96, v96, v97
	v_cvt_pk_bf16_f32 v97, v98, v99
	ds_write_b64 v235, v[80:81] offset:37888
	s_waitcnt vmcnt(37)
	v_cvt_pk_bf16_f32 v80, v88, v89
	v_cvt_pk_bf16_f32 v81, v90, v91
	s_waitcnt vmcnt(36)
	v_cvt_pk_bf16_f32 v76, v76, v77
	v_cvt_pk_bf16_f32 v77, v78, v79
	s_addc_u32 s31, s11, s31
	s_lshl_b64 s[14:15], s[14:15], 7
	ds_write_b64 v233, v[184:185] offset:42624
	ds_write_b64 v233, v[176:177] offset:44992
	ds_write_b64 v233, v[168:169] offset:47360
	ds_write_b64 v233, v[164:165] offset:49728
	ds_write_b64 v233, v[156:157] offset:52096
	ds_write_b64 v233, v[152:153] offset:54464
	ds_write_b64 v233, v[144:145] offset:56832
	ds_write_b64 v233, v[136:137] offset:59200
	ds_write_b64 v233, v[128:129] offset:61568
	ds_write_b64 v233, v[120:121] offset:63936
	ds_write_b64 v238, v[112:113] offset:37888
	ds_write_b64 v237, v[104:105] offset:37888
	ds_write_b64 v236, v[96:97] offset:37888
	ds_write_b64 v231, v[80:81] offset:38400
	ds_write_b64 v230, v[76:77] offset:38400
	s_or_b32 s14, s14, 64
	global_load_dwordx4 v[164:167], v254, s[50:51] nt
	global_load_dwordx4 v[152:155], v239, s[50:51] nt
	global_load_dwordx4 v[200:203], v240, s[50:51] nt
	global_load_dwordx4 v[192:195], v241, s[50:51] nt
	global_load_dwordx4 v[184:187], v242, s[50:51] nt
	global_load_dwordx4 v[176:179], v243, s[50:51] nt
	global_load_dwordx4 v[168:171], v244, s[50:51] nt
	global_load_dwordx4 v[156:159], v245, s[50:51] nt
	global_load_dwordx4 v[144:147], v246, s[50:51] nt
	global_load_dwordx4 v[136:139], v247, s[50:51] nt
	global_load_dwordx4 v[128:131], v248, s[50:51] nt
	global_load_dwordx4 v[120:123], v249, s[50:51] nt
	global_load_dwordx4 v[112:115], v250, s[50:51] nt
	global_load_dwordx4 v[104:107], v251, s[50:51] nt
	global_load_dwordx4 v[96:99], v252, s[50:51] nt
	global_load_dwordx4 v[88:91], v253, s[50:51] nt
	global_load_dwordx4 v[80:83], v254, s[30:31] nt
	global_load_dwordx4 v[76:79], v239, s[30:31] nt
	s_waitcnt vmcnt(53)
	v_cvt_pk_bf16_f32 v216, v216, v217
	v_cvt_pk_bf16_f32 v217, v218, v219
	s_waitcnt vmcnt(52)
	v_cvt_pk_bf16_f32 v212, v212, v213
	v_cvt_pk_bf16_f32 v213, v214, v215
	s_waitcnt vmcnt(38)
	v_cvt_pk_bf16_f32 v92, v92, v93
	v_cvt_pk_bf16_f32 v93, v94, v95
	s_lshl_b64 s[30:31], s[14:15], 10
	s_waitcnt lgkmcnt(0)
	s_barrier
	ds_write_b64 v233, v[216:217]
	ds_write_b64 v234, v[212:213]
	v_cvt_pk_bf16_f32 v208, v208, v209
	v_cvt_pk_bf16_f32 v209, v210, v211
	v_cvt_pk_bf16_f32 v204, v204, v205
	v_cvt_pk_bf16_f32 v205, v206, v207
	v_cvt_pk_bf16_f32 v196, v196, v197
	v_cvt_pk_bf16_f32 v197, v198, v199
	v_cvt_pk_bf16_f32 v188, v188, v189
	v_cvt_pk_bf16_f32 v189, v190, v191
	v_cvt_pk_bf16_f32 v180, v180, v181
	v_cvt_pk_bf16_f32 v181, v182, v183
	v_cvt_pk_bf16_f32 v172, v172, v173
	v_cvt_pk_bf16_f32 v173, v174, v175
	v_cvt_pk_bf16_f32 v160, v160, v161
	v_cvt_pk_bf16_f32 v161, v162, v163
	v_cvt_pk_bf16_f32 v148, v148, v149
	v_cvt_pk_bf16_f32 v149, v150, v151
	v_cvt_pk_bf16_f32 v140, v140, v141
	v_cvt_pk_bf16_f32 v141, v142, v143
	v_cvt_pk_bf16_f32 v132, v132, v133
	v_cvt_pk_bf16_f32 v133, v134, v135
	v_cvt_pk_bf16_f32 v124, v124, v125
	v_cvt_pk_bf16_f32 v125, v126, v127
	v_cvt_pk_bf16_f32 v116, v116, v117
	v_cvt_pk_bf16_f32 v117, v118, v119
	v_cvt_pk_bf16_f32 v108, v108, v109
	v_cvt_pk_bf16_f32 v109, v110, v111
	ds_write_b64 v233, v[92:93] offset:35520
	s_waitcnt vmcnt(37)
	v_cvt_pk_bf16_f32 v92, v100, v101
	v_cvt_pk_bf16_f32 v93, v102, v103
	s_waitcnt vmcnt(36)
	v_cvt_pk_bf16_f32 v84, v84, v85
	v_cvt_pk_bf16_f32 v85, v86, v87
	s_add_u32 s30, s8, s30
	ds_write_b64 v233, v[208:209] offset:4736
	ds_write_b64 v233, v[204:205] offset:7104
	ds_write_b64 v233, v[196:197] offset:9472
	ds_write_b64 v233, v[188:189] offset:11840
	ds_write_b64 v233, v[180:181] offset:14208
	ds_write_b64 v233, v[172:173] offset:16576
	ds_write_b64 v233, v[160:161] offset:18944
	ds_write_b64 v233, v[148:149] offset:21312
	ds_write_b64 v233, v[140:141] offset:23680
	ds_write_b64 v233, v[132:133] offset:26048
	ds_write_b64 v233, v[124:125] offset:28416
	ds_write_b64 v233, v[116:117] offset:30784
	ds_write_b64 v233, v[108:109] offset:33152
	ds_write_b64 v231, v[92:93] offset:512
	ds_write_b64 v230, v[84:85] offset:512
	s_addc_u32 s31, s9, s31
	global_load_dwordx4 v[208:211], v254, s[30:31] nt
	global_load_dwordx4 v[204:207], v239, s[30:31] nt
	global_load_dwordx4 v[196:199], v240, s[30:31] nt
	global_load_dwordx4 v[188:191], v241, s[30:31] nt
	global_load_dwordx4 v[180:183], v242, s[30:31] nt
	global_load_dwordx4 v[172:175], v243, s[30:31] nt
	global_load_dwordx4 v[160:163], v244, s[30:31] nt
	global_load_dwordx4 v[148:151], v245, s[30:31] nt
	global_load_dwordx4 v[140:143], v246, s[30:31] nt
	global_load_dwordx4 v[132:135], v247, s[30:31] nt
	global_load_dwordx4 v[124:127], v248, s[30:31] nt
	global_load_dwordx4 v[116:119], v249, s[30:31] nt
	global_load_dwordx4 v[108:111], v250, s[30:31] nt
	global_load_dwordx4 v[100:103], v251, s[30:31] nt
	global_load_dwordx4 v[92:95], v252, s[30:31] nt
	global_load_dwordx4 v[84:87], v253, s[30:31] nt
	s_lshl_b64 s[14:15], s[14:15], 7
	s_add_u32 s14, s10, s14
	s_addc_u32 s15, s11, s15
	global_load_dwordx4 v[212:215], v254, s[14:15] nt
	global_load_dwordx4 v[216:219], v239, s[14:15] nt
	s_waitcnt lgkmcnt(0)
	s_barrier
	s_add_i32 s29, s29, 6
	s_add_i32 s28, s28, 3
	s_cmp_gt_u32 s29, 53
	s_cbranch_scc0 .LBB0_905
	v_readlane_b32 s14, v232, 31
	s_ashr_i32 s15, s14, 31
	s_lshl_b64 s[14:15], s[14:15], 7
	s_or_b32 s14, s14, 64
	s_lshl_b64 s[28:29], s[14:15], 10
	s_add_u32 s28, s8, s28
	s_waitcnt vmcnt(53)
	v_cvt_pk_bf16_f32 v72, v72, v73
	v_cvt_pk_bf16_f32 v73, v74, v75
	s_waitcnt vmcnt(52)
	v_cvt_pk_bf16_f32 v68, v68, v69
	v_cvt_pk_bf16_f32 v69, v70, v71
	s_waitcnt vmcnt(51)
	v_cvt_pk_bf16_f32 v64, v64, v65
	v_cvt_pk_bf16_f32 v65, v66, v67
	s_waitcnt vmcnt(50)
	v_cvt_pk_bf16_f32 v60, v60, v61
	v_cvt_pk_bf16_f32 v61, v62, v63
	s_waitcnt vmcnt(49)
	v_cvt_pk_bf16_f32 v56, v56, v57
	v_cvt_pk_bf16_f32 v57, v58, v59
	s_waitcnt vmcnt(48)
	v_cvt_pk_bf16_f32 v52, v52, v53
	v_cvt_pk_bf16_f32 v53, v54, v55
	s_waitcnt vmcnt(47)
	v_cvt_pk_bf16_f32 v48, v48, v49
	v_cvt_pk_bf16_f32 v49, v50, v51
	s_waitcnt vmcnt(46)
	v_cvt_pk_bf16_f32 v44, v44, v45
	v_cvt_pk_bf16_f32 v45, v46, v47
	s_waitcnt vmcnt(45)
	v_cvt_pk_bf16_f32 v40, v40, v41
	v_cvt_pk_bf16_f32 v41, v42, v43
	s_waitcnt vmcnt(44)
	v_cvt_pk_bf16_f32 v36, v36, v37
	v_cvt_pk_bf16_f32 v37, v38, v39
	s_waitcnt vmcnt(43)
	v_cvt_pk_bf16_f32 v32, v32, v33
	v_cvt_pk_bf16_f32 v33, v34, v35
	s_waitcnt vmcnt(42)
	v_cvt_pk_bf16_f32 v28, v28, v29
	v_cvt_pk_bf16_f32 v29, v30, v31
	s_waitcnt vmcnt(41)
	v_cvt_pk_bf16_f32 v24, v24, v25
	v_cvt_pk_bf16_f32 v25, v26, v27
	s_waitcnt vmcnt(40)
	v_cvt_pk_bf16_f32 v20, v20, v21
	v_cvt_pk_bf16_f32 v21, v22, v23
	s_waitcnt vmcnt(39)
	v_cvt_pk_bf16_f32 v16, v16, v17
	v_cvt_pk_bf16_f32 v17, v18, v19
	s_waitcnt vmcnt(38)
	v_cvt_pk_bf16_f32 v12, v12, v13
	v_cvt_pk_bf16_f32 v13, v14, v15
	s_waitcnt vmcnt(37)
	v_cvt_pk_bf16_f32 v8, v8, v9
	v_cvt_pk_bf16_f32 v9, v10, v11
	s_waitcnt vmcnt(36)
	v_cvt_pk_bf16_f32 v4, v4, v5
	v_cvt_pk_bf16_f32 v5, v6, v7
	s_addc_u32 s29, s9, s29
	s_lshl_b64 s[14:15], s[14:15], 7
	ds_write_b64 v233, v[72:73] offset:37888
	ds_write_b64 v234, v[68:69] offset:37888
	ds_write_b64 v233, v[64:65] offset:42624
	ds_write_b64 v233, v[60:61] offset:44992
	ds_write_b64 v233, v[56:57] offset:47360
	ds_write_b64 v233, v[52:53] offset:49728
	ds_write_b64 v233, v[48:49] offset:52096
	ds_write_b64 v233, v[44:45] offset:54464
	ds_write_b64 v233, v[40:41] offset:56832
	ds_write_b64 v233, v[36:37] offset:59200
	ds_write_b64 v233, v[32:33] offset:61568
	ds_write_b64 v233, v[28:29] offset:63936
	ds_write_b64 v238, v[24:25] offset:37888
	ds_write_b64 v237, v[20:21] offset:37888
	ds_write_b64 v236, v[16:17] offset:37888
	ds_write_b64 v235, v[12:13] offset:37888
	ds_write_b64 v231, v[8:9] offset:38400
	ds_write_b64 v230, v[4:5] offset:38400
	s_add_u32 s14, s10, s14
	global_load_dwordx4 v[36:39], v240, s[28:29] nt
	global_load_dwordx4 v[40:43], v241, s[28:29] nt
	global_load_dwordx4 v[44:47], v242, s[28:29] nt
	global_load_dwordx4 v[48:51], v243, s[28:29] nt
	global_load_dwordx4 v[52:55], v244, s[28:29] nt
	global_load_dwordx4 v[56:59], v245, s[28:29] nt
	global_load_dwordx4 v[60:63], v246, s[28:29] nt
	global_load_dwordx4 v[64:67], v247, s[28:29] nt
	global_load_dwordx4 v[32:35], v248, s[28:29] nt
	global_load_dwordx4 v[28:31], v249, s[28:29] nt
	global_load_dwordx4 v[24:27], v250, s[28:29] nt
	global_load_dwordx4 v[20:23], v251, s[28:29] nt
	global_load_dwordx4 v[16:19], v252, s[28:29] nt
	global_load_dwordx4 v[8:11], v253, s[28:29] nt
	s_addc_u32 s15, s11, s15
	global_load_dwordx4 v[68:71], v254, s[28:29] nt
	global_load_dwordx4 v[12:15], v254, s[14:15] nt
	global_load_dwordx4 v[72:75], v239, s[28:29] nt
	global_load_dwordx4 v[4:7], v239, s[14:15] nt
	s_waitcnt vmcnt(53)
	v_cvt_pk_bf16_f32 v164, v164, v165
	v_cvt_pk_bf16_f32 v165, v166, v167
	s_waitcnt vmcnt(52)
	v_cvt_pk_bf16_f32 v152, v152, v153
	v_cvt_pk_bf16_f32 v153, v154, v155
	s_waitcnt lgkmcnt(0)
	s_barrier
	ds_write_b64 v233, v[164:165]
	ds_write_b64 v234, v[152:153]
	s_waitcnt vmcnt(51)
	v_cvt_pk_bf16_f32 v152, v200, v201
	v_cvt_pk_bf16_f32 v153, v202, v203
	ds_write_b64 v233, v[152:153] offset:4736
	s_waitcnt vmcnt(50)
	v_cvt_pk_bf16_f32 v152, v192, v193
	v_cvt_pk_bf16_f32 v153, v194, v195
	ds_write_b64 v233, v[152:153] offset:7104
	s_waitcnt vmcnt(49)
	v_cvt_pk_bf16_f32 v152, v184, v185
	v_cvt_pk_bf16_f32 v153, v186, v187
	ds_write_b64 v233, v[152:153] offset:9472
	s_waitcnt vmcnt(48)
	v_cvt_pk_bf16_f32 v152, v176, v177
	v_cvt_pk_bf16_f32 v153, v178, v179
	ds_write_b64 v233, v[152:153] offset:11840
	s_waitcnt vmcnt(47)
	v_cvt_pk_bf16_f32 v152, v168, v169
	v_cvt_pk_bf16_f32 v153, v170, v171
	ds_write_b64 v233, v[152:153] offset:14208
	s_waitcnt vmcnt(46)
	v_cvt_pk_bf16_f32 v152, v156, v157
	v_cvt_pk_bf16_f32 v153, v158, v159
	s_waitcnt vmcnt(45)
	v_cvt_pk_bf16_f32 v144, v144, v145
	v_cvt_pk_bf16_f32 v145, v146, v147
	s_waitcnt vmcnt(44)
	v_cvt_pk_bf16_f32 v136, v136, v137
	v_cvt_pk_bf16_f32 v137, v138, v139
	s_waitcnt vmcnt(43)
	v_cvt_pk_bf16_f32 v128, v128, v129
	v_cvt_pk_bf16_f32 v129, v130, v131
	s_waitcnt vmcnt(42)
	v_cvt_pk_bf16_f32 v120, v120, v121
	v_cvt_pk_bf16_f32 v121, v122, v123
	s_waitcnt vmcnt(41)
	v_cvt_pk_bf16_f32 v112, v112, v113
	v_cvt_pk_bf16_f32 v113, v114, v115
	s_waitcnt vmcnt(40)
	v_cvt_pk_bf16_f32 v104, v104, v105
	v_cvt_pk_bf16_f32 v105, v106, v107
	s_waitcnt vmcnt(39)
	v_cvt_pk_bf16_f32 v96, v96, v97
	v_cvt_pk_bf16_f32 v97, v98, v99
	s_waitcnt vmcnt(38)
	v_cvt_pk_bf16_f32 v88, v88, v89
	v_cvt_pk_bf16_f32 v89, v90, v91
	s_waitcnt vmcnt(37)
	v_cvt_pk_bf16_f32 v80, v80, v81
	v_cvt_pk_bf16_f32 v81, v82, v83
	s_waitcnt vmcnt(36)
	v_cvt_pk_bf16_f32 v76, v76, v77
	v_cvt_pk_bf16_f32 v77, v78, v79
	ds_write_b64 v233, v[152:153] offset:16576
	ds_write_b64 v233, v[144:145] offset:18944
	ds_write_b64 v233, v[136:137] offset:21312
	ds_write_b64 v233, v[128:129] offset:23680
	ds_write_b64 v233, v[120:121] offset:26048
	ds_write_b64 v233, v[112:113] offset:28416
	ds_write_b64 v233, v[104:105] offset:30784
	ds_write_b64 v233, v[96:97] offset:33152
	ds_write_b64 v233, v[88:89] offset:35520
	ds_write_b64 v231, v[80:81] offset:512
	ds_write_b64 v230, v[76:77] offset:512
	s_waitcnt vmcnt(35)
	v_cvt_pk_bf16_f32 v76, v208, v209
	v_cvt_pk_bf16_f32 v77, v210, v211
	s_waitcnt lgkmcnt(0)
	s_barrier
	ds_write_b64 v233, v[76:77] offset:37888
	s_waitcnt vmcnt(34)
	v_cvt_pk_bf16_f32 v76, v204, v205
	v_cvt_pk_bf16_f32 v77, v206, v207
	ds_write_b64 v234, v[76:77] offset:37888
	s_waitcnt vmcnt(33)
	v_cvt_pk_bf16_f32 v76, v196, v197
	v_cvt_pk_bf16_f32 v77, v198, v199
	ds_write_b64 v233, v[76:77] offset:42624
	s_waitcnt vmcnt(32)
	v_cvt_pk_bf16_f32 v76, v188, v189
	v_cvt_pk_bf16_f32 v77, v190, v191
	ds_write_b64 v233, v[76:77] offset:44992
	s_waitcnt vmcnt(31)
	v_cvt_pk_bf16_f32 v76, v180, v181
	v_cvt_pk_bf16_f32 v77, v182, v183
	ds_write_b64 v233, v[76:77] offset:47360
	s_waitcnt vmcnt(30)
	v_cvt_pk_bf16_f32 v76, v172, v173
	v_cvt_pk_bf16_f32 v77, v174, v175
	ds_write_b64 v233, v[76:77] offset:49728
	s_waitcnt vmcnt(29)
	v_cvt_pk_bf16_f32 v76, v160, v161
	v_cvt_pk_bf16_f32 v77, v162, v163
	ds_write_b64 v233, v[76:77] offset:52096
	s_waitcnt vmcnt(28)
	v_cvt_pk_bf16_f32 v76, v148, v149
	v_cvt_pk_bf16_f32 v77, v150, v151
	ds_write_b64 v233, v[76:77] offset:54464
	s_waitcnt vmcnt(27)
	v_cvt_pk_bf16_f32 v76, v140, v141
	v_cvt_pk_bf16_f32 v77, v142, v143
	ds_write_b64 v233, v[76:77] offset:56832
	s_waitcnt vmcnt(26)
	v_cvt_pk_bf16_f32 v76, v132, v133
	v_cvt_pk_bf16_f32 v77, v134, v135
	ds_write_b64 v233, v[76:77] offset:59200
	s_waitcnt vmcnt(25)
	v_cvt_pk_bf16_f32 v76, v124, v125
	v_cvt_pk_bf16_f32 v77, v126, v127
	ds_write_b64 v233, v[76:77] offset:61568
	s_waitcnt vmcnt(24)
	v_cvt_pk_bf16_f32 v76, v116, v117
	v_cvt_pk_bf16_f32 v77, v118, v119
	ds_write_b64 v233, v[76:77] offset:63936
	s_waitcnt vmcnt(23)
	v_cvt_pk_bf16_f32 v76, v108, v109
	v_cvt_pk_bf16_f32 v77, v110, v111
	ds_write_b64 v238, v[76:77] offset:37888
	s_waitcnt vmcnt(22)
	v_cvt_pk_bf16_f32 v76, v100, v101
	v_cvt_pk_bf16_f32 v77, v102, v103
	ds_write_b64 v237, v[76:77] offset:37888
	s_waitcnt vmcnt(21)
	v_cvt_pk_bf16_f32 v76, v92, v93
	v_cvt_pk_bf16_f32 v77, v94, v95
	ds_write_b64 v236, v[76:77] offset:37888
	s_waitcnt vmcnt(20)
	v_cvt_pk_bf16_f32 v76, v84, v85
	v_cvt_pk_bf16_f32 v77, v86, v87
	ds_write_b64 v235, v[76:77] offset:37888
	s_waitcnt vmcnt(19)
	v_cvt_pk_bf16_f32 v76, v212, v213
	v_cvt_pk_bf16_f32 v77, v214, v215
	ds_write_b64 v231, v[76:77] offset:38400
	s_waitcnt vmcnt(18)
	v_cvt_pk_bf16_f32 v76, v216, v217
	v_cvt_pk_bf16_f32 v77, v218, v219
	ds_write_b64 v230, v[76:77] offset:38400
	s_waitcnt vmcnt(3)
	v_cvt_pk_bf16_f32 v68, v68, v69
	v_cvt_pk_bf16_f32 v69, v70, v71
	s_waitcnt lgkmcnt(0)
	s_barrier
	ds_write_b64 v233, v[68:69]
	s_waitcnt vmcnt(1)
	v_cvt_pk_bf16_f32 v68, v72, v73
	v_cvt_pk_bf16_f32 v69, v74, v75
	v_cvt_pk_bf16_f32 v36, v36, v37
	v_cvt_pk_bf16_f32 v37, v38, v39
	ds_write_b64 v234, v[68:69]
	ds_write_b64 v233, v[36:37] offset:4736
	v_cvt_pk_bf16_f32 v36, v40, v41
	v_cvt_pk_bf16_f32 v37, v42, v43
	ds_write_b64 v233, v[36:37] offset:7104
	v_cvt_pk_bf16_f32 v36, v44, v45
	v_cvt_pk_bf16_f32 v37, v46, v47
	ds_write_b64 v233, v[36:37] offset:9472
	v_cvt_pk_bf16_f32 v36, v48, v49
	v_cvt_pk_bf16_f32 v37, v50, v51
	ds_write_b64 v233, v[36:37] offset:11840
	v_cvt_pk_bf16_f32 v36, v52, v53
	v_cvt_pk_bf16_f32 v37, v54, v55
	ds_write_b64 v233, v[36:37] offset:14208
	v_cvt_pk_bf16_f32 v36, v56, v57
	v_cvt_pk_bf16_f32 v37, v58, v59
	ds_write_b64 v233, v[36:37] offset:16576
	v_cvt_pk_bf16_f32 v36, v60, v61
	v_cvt_pk_bf16_f32 v37, v62, v63
	v_cvt_pk_bf16_f32 v8, v8, v9
	v_cvt_pk_bf16_f32 v9, v10, v11
	ds_write_b64 v233, v[36:37] offset:18944
	v_cvt_pk_bf16_f32 v36, v64, v65
	v_cvt_pk_bf16_f32 v37, v66, v67
	v_cvt_pk_bf16_f32 v32, v32, v33
	v_cvt_pk_bf16_f32 v33, v34, v35
	v_cvt_pk_bf16_f32 v28, v28, v29
	v_cvt_pk_bf16_f32 v29, v30, v31
	v_cvt_pk_bf16_f32 v24, v24, v25
	v_cvt_pk_bf16_f32 v25, v26, v27
	v_cvt_pk_bf16_f32 v20, v20, v21
	v_cvt_pk_bf16_f32 v21, v22, v23
	v_cvt_pk_bf16_f32 v16, v16, v17
	v_cvt_pk_bf16_f32 v17, v18, v19
	ds_write_b64 v233, v[8:9] offset:35520
	v_cvt_pk_bf16_f32 v8, v12, v13
	v_cvt_pk_bf16_f32 v9, v14, v15
	s_waitcnt vmcnt(0)
	v_cvt_pk_bf16_f32 v4, v4, v5
	v_cvt_pk_bf16_f32 v5, v6, v7
	ds_write_b64 v233, v[36:37] offset:21312
	ds_write_b64 v233, v[32:33] offset:23680
	ds_write_b64 v233, v[28:29] offset:26048
	ds_write_b64 v233, v[24:25] offset:28416
	ds_write_b64 v233, v[20:21] offset:30784
	ds_write_b64 v233, v[16:17] offset:33152
	ds_write_b64 v231, v[8:9] offset:512
	ds_write_b64 v230, v[4:5] offset:512
	s_waitcnt lgkmcnt(0)
	s_barrier
	s_mov_b64 s[14:15], 0
	s_setprio 0
